# GEMM mainloops: back-to-back s_setprio 0 / s_setprio 1 between the two MFMA blocks of a super-phase removed (priority stays raised across both blocks, 32 pairs)
# speedup vs baseline: 1.0068x; 1.0068x over previous
; #define PG8_STAGE(bufoff, gbase, voff) do { _Pragma("unroll") for (int _i = 0; _i < 2; ++_i) \
;         __builtin_amdgcn_global_load_lds((const unsigned*)((const char*)(gbase) + (voff)[_i]), (PG8_LAS unsigned*)(lds + (bufoff) + ldsw + _i * 8192), 16, 0, 0); } while (0)
; #define PG8_LDA(dst, b, h) do { _Pragma("unroll") for (int m = 0; m < 4; ++m) _Pragma("unroll") for (int k = 0; k < 2; ++k) dst[m][k] = *(const PG8_LAS bf16x8*)(lds + PG8_SA(b, h) + aoff + m * 2048 + k * 1024); } while (0)
; #define PG8_LDB(dst, b, h) do { _Pragma("unroll") for (int n = 0; n < 2; ++n) _Pragma("unroll") for (int k = 0; k < 2; ++k) dst[n][k] = *(const PG8_LAS bf16x8*)(lds + PG8_SB(b, h) + boff + n * 2048 + k * 1024); } while (0)
; #define PG8_MMA(ai, bj, At, Bt) do { __builtin_amdgcn_s_setprio(1); _Pragma("unroll") for (int m = 0; m < 4; ++m) _Pragma("unroll") for (int n = 0; n < 2; ++n) _Pragma("unroll") for (int k = 0; k < 2; ++k) \
;         acc[ai][bj][m][n] = __builtin_amdgcn_mfma_f32_16x16x32_bf16(Bt[n][k], At[m][k], acc[ai][bj][m][n], 0, 0, 0); __builtin_amdgcn_s_setprio(0); } while (0)
; #define PG8_WAIT_V(n) asm volatile("s_waitcnt vmcnt(" #n ")" ::: "memory")
; #define PG8_WAIT_L(n) asm volatile("s_waitcnt lgkmcnt(" #n ")" ::: "memory")
; #define PG8_BAR __builtin_amdgcn_s_barrier()
; #define PG8_SCHED __builtin_amdgcn_sched_barrier(0)
; template <class Epi, class Sched, bool ALIGN_EPI = false, bool SP2 = false>
; __device__ __forceinline__ void gemm_phase(PG8_LAS unsigned char* lds, const Gemm g, const Sched& S, const Epi& E) {
;     ...
;             PG8_LDB(B0, 0, 0); PG8_LDB(B1, 0, 1); PG8_SCHED; PG8_LDA(At, 0, 0); PG8_STAGE(PG8_SA(1, 1), a1 + hstep, voffA);
;             PG8_WAIT_V(8); PG8_WAIT_L(0); PG8_BAR; PG8_MMA(0, 0, At, B0); PG8_MMA(0, 1, At, B1); PG8_BAR; PG8_SCHED;
;             PG8_LDA(At, 0, 1); PG8_STAGE(PG8_SB(0, 0), b2, voffB); PG8_STAGE(PG8_SB(0, 1), b2 + hstep, voffB); PG8_STAGE(PG8_SA(0, 0), a2, voffA);
;             PG8_WAIT_V(8); PG8_WAIT_L(0); PG8_BAR; PG8_MMA(1, 0, At, B0); PG8_MMA(1, 1, At, B1); PG8_BAR; PG8_SCHED;
.LBB0_176:
	ds_read_b128 v[10:13], v178
	ds_read_b128 v[14:17], v178 offset:1024
	ds_read_b128 v[138:141], v178 offset:2048
	ds_read_b128 v[142:145], v178 offset:3072
	ds_read_b128 v[166:169], v179
	ds_read_b128 v[172:175], v179 offset:1024
	ds_read_b128 v[186:189], v179 offset:2048
	ds_read_b128 v[190:193], v179 offset:3072
	s_add_u32 s0, s8, 0xfffc0080
	s_addc_u32 s1, s9, -1
	s_cmp_eq_u32 s41, 12
	s_cselect_b32 s13, s7, s1
	s_cselect_b32 s12, s14, s0
	s_cselect_b32 s11, s15, s39
	s_cselect_b32 s10, s16, s17
	v_lshl_add_u64 v[226:227], s[8:9], 0, v[158:159]
	s_add_i32 m0, s59, 0xc000
	ds_read_b128 v[194:197], v180
	ds_read_b128 v[198:201], v180 offset:1024
	ds_read_b128 v[202:205], v180 offset:2048
	ds_read_b128 v[206:209], v180 offset:3072
	ds_read_b128 v[210:213], v180 offset:4096
	ds_read_b128 v[214:217], v180 offset:5120
	ds_read_b128 v[218:221], v180 offset:6144
	ds_read_b128 v[222:225], v180 offset:7168
	global_load_lds_dwordx4 v[226:227], off
	v_lshl_add_u64 v[226:227], s[8:9], 0, v[160:161]
	s_add_i32 m0, s59, 0xe000
	s_nop 0
	global_load_lds_dwordx4 v[226:227], off
	s_waitcnt vmcnt(8)
	s_waitcnt lgkmcnt(0)
	s_barrier
	s_setprio 1
	s_waitcnt lgkmcnt(0)
	v_mfma_f32_16x16x32_bf16 v[2:5], v[10:13], v[194:197], v[2:5]
	v_mfma_f32_16x16x32_bf16 v[6:9], v[138:141], v[194:197], v[6:9]
	v_mfma_f32_16x16x32_bf16 v[134:137], v[10:13], v[202:205], v[134:137]
	v_mfma_f32_16x16x32_bf16 v[130:133], v[138:141], v[202:205], v[130:133]
	v_mfma_f32_16x16x32_bf16 v[126:129], v[10:13], v[210:213], v[126:129]
	v_mfma_f32_16x16x32_bf16 v[122:125], v[138:141], v[210:213], v[122:125]
	v_mfma_f32_16x16x32_bf16 v[118:121], v[10:13], v[218:221], v[118:121]
	v_mfma_f32_16x16x32_bf16 v[114:117], v[138:141], v[218:221], v[114:117]
	v_mfma_f32_16x16x32_bf16 v[2:5], v[14:17], v[198:201], v[2:5]
	v_mfma_f32_16x16x32_bf16 v[6:9], v[142:145], v[198:201], v[6:9]
	v_mfma_f32_16x16x32_bf16 v[134:137], v[14:17], v[206:209], v[134:137]
	v_mfma_f32_16x16x32_bf16 v[130:133], v[142:145], v[206:209], v[130:133]
	v_mfma_f32_16x16x32_bf16 v[126:129], v[14:17], v[214:217], v[126:129]
	v_mfma_f32_16x16x32_bf16 v[122:125], v[142:145], v[214:217], v[122:125]
	v_mfma_f32_16x16x32_bf16 v[118:121], v[14:17], v[222:225], v[118:121]
	v_mfma_f32_16x16x32_bf16 v[114:117], v[142:145], v[222:225], v[114:117]
	v_mfma_f32_16x16x32_bf16 v[78:81], v[166:169], v[194:197], v[78:81]
	v_mfma_f32_16x16x32_bf16 v[74:77], v[186:189], v[194:197], v[74:77]
	v_mfma_f32_16x16x32_bf16 v[70:73], v[166:169], v[202:205], v[70:73]
	v_mfma_f32_16x16x32_bf16 v[66:69], v[186:189], v[202:205], v[66:69]
	v_mfma_f32_16x16x32_bf16 v[62:65], v[166:169], v[210:213], v[62:65]
	v_mfma_f32_16x16x32_bf16 v[58:61], v[186:189], v[210:213], v[58:61]
	v_mfma_f32_16x16x32_bf16 v[54:57], v[166:169], v[218:221], v[54:57]
	v_mfma_f32_16x16x32_bf16 v[50:53], v[186:189], v[218:221], v[50:53]
	v_mfma_f32_16x16x32_bf16 v[78:81], v[172:175], v[198:201], v[78:81]
	v_mfma_f32_16x16x32_bf16 v[74:77], v[190:193], v[198:201], v[74:77]
	v_mfma_f32_16x16x32_bf16 v[70:73], v[172:175], v[206:209], v[70:73]
	v_mfma_f32_16x16x32_bf16 v[66:69], v[190:193], v[206:209], v[66:69]
	v_mfma_f32_16x16x32_bf16 v[62:65], v[172:175], v[214:217], v[62:65]
	v_mfma_f32_16x16x32_bf16 v[58:61], v[190:193], v[214:217], v[58:61]
	v_mfma_f32_16x16x32_bf16 v[54:57], v[172:175], v[222:225], v[54:57]
	v_mfma_f32_16x16x32_bf16 v[50:53], v[190:193], v[222:225], v[50:53]
	s_setprio 0
	s_barrier
	s_add_i32 s0, s84, s58
	v_lshl_add_u64 v[226:227], s[10:11], 0, v[148:149]
	s_mov_b32 m0, s0
	ds_read_b128 v[194:197], v180 offset:16384
	ds_read_b128 v[198:201], v180 offset:17408
	ds_read_b128 v[202:205], v180 offset:18432
	ds_read_b128 v[206:209], v180 offset:19456
	ds_read_b128 v[210:213], v180 offset:20480
	ds_read_b128 v[214:217], v180 offset:21504
	ds_read_b128 v[218:221], v180 offset:22528
	ds_read_b128 v[222:225], v180 offset:23552
	global_load_lds_dwordx4 v[226:227], off
	s_add_i32 m0, s0, 0x2000
	s_add_u32 s0, s10, 0x40000
	v_lshl_add_u64 v[228:229], s[10:11], 0, v[152:153]
	s_addc_u32 s1, s11, 0
	s_add_i32 s48, s85, s58
	global_load_lds_dwordx4 v[228:229], off
	v_lshl_add_u64 v[230:231], s[0:1], 0, v[148:149]
	s_mov_b32 m0, s48
	v_lshl_add_u64 v[232:233], s[12:13], 0, v[150:151]
	global_load_lds_dwordx4 v[230:231], off
	v_lshl_add_u64 v[230:231], s[0:1], 0, v[152:153]
	s_add_i32 m0, s48, 0x2000
	s_nop 0
	global_load_lds_dwordx4 v[230:231], off
	v_lshl_add_u64 v[230:231], s[12:13], 0, v[146:147]
	s_mov_b32 m0, s59
	s_nop 0
	global_load_lds_dwordx4 v[230:231], off
	s_mov_b32 m0, s72
	s_nop 0
	global_load_lds_dwordx4 v[232:233], off
	s_waitcnt vmcnt(8)
	s_waitcnt lgkmcnt(0)
	s_barrier
; #define PG8_STAGE(bufoff, gbase, voff) do { _Pragma("unroll") for (int _i = 0; _i < 2; ++_i) \
;         __builtin_amdgcn_global_load_lds((const unsigned*)((const char*)(gbase) + (voff)[_i]), (PG8_LAS unsigned*)(lds + (bufoff) + ldsw + _i * 8192), 16, 0, 0); } while (0)
; #define PG8_LDA(dst, b, h) do { _Pragma("unroll") for (int m = 0; m < 4; ++m) _Pragma("unroll") for (int k = 0; k < 2; ++k) dst[m][k] = *(const PG8_LAS bf16x8*)(lds + PG8_SA(b, h) + aoff + m * 2048 + k * 1024); } while (0)
; #define PG8_LDB(dst, b, h) do { _Pragma("unroll") for (int n = 0; n < 2; ++n) _Pragma("unroll") for (int k = 0; k < 2; ++k) dst[n][k] = *(const PG8_LAS bf16x8*)(lds + PG8_SB(b, h) + boff + n * 2048 + k * 1024); } while (0)
; #define PG8_MMA(ai, bj, At, Bt) do { __builtin_amdgcn_s_setprio(1); _Pragma("unroll") for (int m = 0; m < 4; ++m) _Pragma("unroll") for (int n = 0; n < 2; ++n) _Pragma("unroll") for (int k = 0; k < 2; ++k) \
;         acc[ai][bj][m][n] = __builtin_amdgcn_mfma_f32_16x16x32_bf16(Bt[n][k], At[m][k], acc[ai][bj][m][n], 0, 0, 0); __builtin_amdgcn_s_setprio(0); } while (0)
; #define PG8_WAIT_V(n) asm volatile("s_waitcnt vmcnt(" #n ")" ::: "memory")
; #define PG8_WAIT_L(n) asm volatile("s_waitcnt lgkmcnt(" #n ")" ::: "memory")
; #define PG8_BAR __builtin_amdgcn_s_barrier()
; #define PG8_SCHED __builtin_amdgcn_sched_barrier(0)
; template <class Epi, class Sched, bool ALIGN_EPI = false, bool SP2 = false>
; __device__ __forceinline__ void gemm_phase(PG8_LAS unsigned char* lds, const Gemm g, const Sched& S, const Epi& E) {
;     ...
;             PG8_WAIT_V(8); PG8_WAIT_L(0); PG8_BAR; PG8_MMA(1, 0, At, B0); PG8_MMA(1, 1, At, B1); PG8_BAR; PG8_SCHED;
;             PG8_LDB(B0, 1, 0); PG8_LDB(B1, 1, 1); PG8_SCHED; PG8_LDA(At, 1, 0); PG8_STAGE(PG8_SA(0, 1), a2 + hstep, voffA);
;             PG8_WAIT_V(8); PG8_WAIT_L(0); PG8_BAR; PG8_MMA(0, 0, At, B0); PG8_MMA(0, 1, At, B1); PG8_BAR; PG8_SCHED;
	s_setprio 1
	s_waitcnt lgkmcnt(0)
	v_mfma_f32_16x16x32_bf16 v[110:113], v[10:13], v[194:197], v[110:113]
	v_mfma_f32_16x16x32_bf16 v[106:109], v[138:141], v[194:197], v[106:109]
	v_mfma_f32_16x16x32_bf16 v[102:105], v[10:13], v[202:205], v[102:105]
	v_mfma_f32_16x16x32_bf16 v[98:101], v[138:141], v[202:205], v[98:101]
	v_mfma_f32_16x16x32_bf16 v[94:97], v[10:13], v[210:213], v[94:97]
	v_mfma_f32_16x16x32_bf16 v[90:93], v[138:141], v[210:213], v[90:93]
	v_mfma_f32_16x16x32_bf16 v[10:13], v[10:13], v[218:221], v[86:89]
	v_mfma_f32_16x16x32_bf16 v[110:113], v[14:17], v[198:201], v[110:113]
	v_mfma_f32_16x16x32_bf16 v[106:109], v[142:145], v[198:201], v[106:109]
	v_mfma_f32_16x16x32_bf16 v[102:105], v[14:17], v[206:209], v[102:105]
	v_mfma_f32_16x16x32_bf16 v[98:101], v[142:145], v[206:209], v[98:101]
	v_mfma_f32_16x16x32_bf16 v[94:97], v[14:17], v[214:217], v[94:97]
	v_mfma_f32_16x16x32_bf16 v[90:93], v[142:145], v[214:217], v[90:93]
	v_mfma_f32_16x16x32_bf16 v[10:13], v[14:17], v[222:225], v[10:13]
	v_mfma_f32_16x16x32_bf16 v[14:17], v[138:141], v[218:221], v[82:85]
	v_mfma_f32_16x16x32_bf16 v[14:17], v[142:145], v[222:225], v[14:17]
	v_mfma_f32_16x16x32_bf16 v[46:49], v[166:169], v[194:197], v[46:49]
	v_mfma_f32_16x16x32_bf16 v[42:45], v[186:189], v[194:197], v[42:45]
	v_mfma_f32_16x16x32_bf16 v[38:41], v[166:169], v[202:205], v[38:41]
	v_mfma_f32_16x16x32_bf16 v[34:37], v[186:189], v[202:205], v[34:37]
	v_mfma_f32_16x16x32_bf16 v[30:33], v[166:169], v[210:213], v[30:33]
	v_mfma_f32_16x16x32_bf16 v[26:29], v[186:189], v[210:213], v[26:29]
	v_mfma_f32_16x16x32_bf16 v[22:25], v[166:169], v[218:221], v[22:25]
	v_mfma_f32_16x16x32_bf16 v[18:21], v[186:189], v[218:221], v[18:21]
	v_mfma_f32_16x16x32_bf16 v[46:49], v[172:175], v[198:201], v[46:49]
	v_mfma_f32_16x16x32_bf16 v[42:45], v[190:193], v[198:201], v[42:45]
	v_mfma_f32_16x16x32_bf16 v[38:41], v[172:175], v[206:209], v[38:41]
	v_mfma_f32_16x16x32_bf16 v[34:37], v[190:193], v[206:209], v[34:37]
	v_mfma_f32_16x16x32_bf16 v[30:33], v[172:175], v[214:217], v[30:33]
	v_mfma_f32_16x16x32_bf16 v[26:29], v[190:193], v[214:217], v[26:29]
	v_mfma_f32_16x16x32_bf16 v[22:25], v[172:175], v[222:225], v[22:25]
	v_mfma_f32_16x16x32_bf16 v[18:21], v[190:193], v[222:225], v[18:21]
	s_setprio 0
	s_barrier
	s_add_i32 s48, 0, 0x18000
	s_add_i32 s49, 0, 0x1c000
	v_add_u32_e32 v142, s48, v176
	v_add_u32_e32 v154, s49, v176
	ds_read_b128 v[82:85], v142
	ds_read_b128 v[86:89], v142 offset:1024
	ds_read_b128 v[138:141], v142 offset:2048
	ds_read_b128 v[142:145], v142 offset:3072
	ds_read_b128 v[166:169], v154
	ds_read_b128 v[172:175], v154 offset:1024
	ds_read_b128 v[186:189], v154 offset:2048
	ds_read_b128 v[190:193], v154 offset:3072
	s_add_u32 s0, s12, 0x40000
	s_addc_u32 s1, s13, 0
	s_mov_b32 m0, s73
	v_lshl_add_u64 v[234:235], s[0:1], 0, v[146:147]
	ds_read_b128 v[194:197], v180 offset:32768
	ds_read_b128 v[198:201], v180 offset:33792
	ds_read_b128 v[202:205], v180 offset:34816
	ds_read_b128 v[206:209], v180 offset:35840
	ds_read_b128 v[210:213], v180 offset:36864
	ds_read_b128 v[214:217], v180 offset:37888
	ds_read_b128 v[218:221], v180 offset:38912
	ds_read_b128 v[222:225], v180 offset:39936
	global_load_lds_dwordx4 v[234:235], off
	v_lshl_add_u64 v[234:235], s[0:1], 0, v[150:151]
	s_mov_b32 m0, s74
	s_nop 0
	global_load_lds_dwordx4 v[234:235], off
	s_waitcnt vmcnt(8)
	s_waitcnt lgkmcnt(0)
	s_barrier
	s_setprio 1
	s_waitcnt lgkmcnt(0)
	v_mfma_f32_16x16x32_bf16 v[2:5], v[82:85], v[194:197], v[2:5]
	v_mfma_f32_16x16x32_bf16 v[6:9], v[138:141], v[194:197], v[6:9]
	v_mfma_f32_16x16x32_bf16 v[134:137], v[82:85], v[202:205], v[134:137]
	v_mfma_f32_16x16x32_bf16 v[130:133], v[138:141], v[202:205], v[130:133]
	v_mfma_f32_16x16x32_bf16 v[126:129], v[82:85], v[210:213], v[126:129]
	v_mfma_f32_16x16x32_bf16 v[122:125], v[138:141], v[210:213], v[122:125]
	v_mfma_f32_16x16x32_bf16 v[118:121], v[82:85], v[218:221], v[118:121]
	v_mfma_f32_16x16x32_bf16 v[114:117], v[138:141], v[218:221], v[114:117]
	v_mfma_f32_16x16x32_bf16 v[2:5], v[86:89], v[198:201], v[2:5]
	v_mfma_f32_16x16x32_bf16 v[6:9], v[142:145], v[198:201], v[6:9]
	v_mfma_f32_16x16x32_bf16 v[134:137], v[86:89], v[206:209], v[134:137]
	v_mfma_f32_16x16x32_bf16 v[130:133], v[142:145], v[206:209], v[130:133]
	v_mfma_f32_16x16x32_bf16 v[126:129], v[86:89], v[214:217], v[126:129]
	v_mfma_f32_16x16x32_bf16 v[122:125], v[142:145], v[214:217], v[122:125]
	v_mfma_f32_16x16x32_bf16 v[118:121], v[86:89], v[222:225], v[118:121]
	v_mfma_f32_16x16x32_bf16 v[114:117], v[142:145], v[222:225], v[114:117]
	v_mfma_f32_16x16x32_bf16 v[78:81], v[166:169], v[194:197], v[78:81]
	v_mfma_f32_16x16x32_bf16 v[74:77], v[186:189], v[194:197], v[74:77]
	v_mfma_f32_16x16x32_bf16 v[70:73], v[166:169], v[202:205], v[70:73]
	v_mfma_f32_16x16x32_bf16 v[66:69], v[186:189], v[202:205], v[66:69]
	v_mfma_f32_16x16x32_bf16 v[62:65], v[166:169], v[210:213], v[62:65]
	v_mfma_f32_16x16x32_bf16 v[58:61], v[186:189], v[210:213], v[58:61]
	v_mfma_f32_16x16x32_bf16 v[54:57], v[166:169], v[218:221], v[54:57]
	v_mfma_f32_16x16x32_bf16 v[50:53], v[186:189], v[218:221], v[50:53]
	v_mfma_f32_16x16x32_bf16 v[78:81], v[172:175], v[198:201], v[78:81]
	v_mfma_f32_16x16x32_bf16 v[74:77], v[190:193], v[198:201], v[74:77]
	v_mfma_f32_16x16x32_bf16 v[70:73], v[172:175], v[206:209], v[70:73]
	v_mfma_f32_16x16x32_bf16 v[66:69], v[190:193], v[206:209], v[66:69]
	v_mfma_f32_16x16x32_bf16 v[62:65], v[172:175], v[214:217], v[62:65]
	v_mfma_f32_16x16x32_bf16 v[58:61], v[190:193], v[214:217], v[58:61]
	v_mfma_f32_16x16x32_bf16 v[54:57], v[172:175], v[222:225], v[54:57]
	v_mfma_f32_16x16x32_bf16 v[50:53], v[190:193], v[222:225], v[50:53]
	s_setprio 0
	s_barrier
; #define PG8_STAGE(bufoff, gbase, voff) do { _Pragma("unroll") for (int _i = 0; _i < 2; ++_i) \
;         __builtin_amdgcn_global_load_lds((const unsigned*)((const char*)(gbase) + (voff)[_i]), (PG8_LAS unsigned*)(lds + (bufoff) + ldsw + _i * 8192), 16, 0, 0); } while (0)
; #define PG8_LDA(dst, b, h) do { _Pragma("unroll") for (int m = 0; m < 4; ++m) _Pragma("unroll") for (int k = 0; k < 2; ++k) dst[m][k] = *(const PG8_LAS bf16x8*)(lds + PG8_SA(b, h) + aoff + m * 2048 + k * 1024); } while (0)
; #define PG8_MMA(ai, bj, At, Bt) do { __builtin_amdgcn_s_setprio(1); _Pragma("unroll") for (int m = 0; m < 4; ++m) _Pragma("unroll") for (int n = 0; n < 2; ++n) _Pragma("unroll") for (int k = 0; k < 2; ++k) \
;         acc[ai][bj][m][n] = __builtin_amdgcn_mfma_f32_16x16x32_bf16(Bt[n][k], At[m][k], acc[ai][bj][m][n], 0, 0, 0); __builtin_amdgcn_s_setprio(0); } while (0)
; #define PG8_WAIT_V(n) asm volatile("s_waitcnt vmcnt(" #n ")" ::: "memory")
; #define PG8_WAIT_L(n) asm volatile("s_waitcnt lgkmcnt(" #n ")" ::: "memory")
; #define PG8_BAR __builtin_amdgcn_s_barrier()
; #define PG8_SCHED __builtin_amdgcn_sched_barrier(0)
; template <class Epi, class Sched, bool ALIGN_EPI = false, bool SP2 = false>
; __device__ __forceinline__ void gemm_phase(PG8_LAS unsigned char* lds, const Gemm g, const Sched& S, const Epi& E) {
;     ...
;         for (int t = 0; t < nt; t += 2) {
;             const bool last = (t == nt - 2);
;             const char* a1 = cA + (size_t)(t + 1) * kstep;
;             const char* a2 = last ? nA : cA + (size_t)(t + 2) * kstep; const char* b2 = last ? nB : cB + (size_t)(t + 2) * kstep;
;             const char* a3 = a2 + kstep; const char* b3 = b2 + kstep;
;             if (last && has_next) S.a_ready(nxt);
;     ...
;             PG8_LDA(At, 1, 1); PG8_STAGE(PG8_SB(1, 0), b3, voffB); PG8_STAGE(PG8_SB(1, 1), b3 + hstep, voffB); PG8_STAGE(PG8_SA(1, 0), a3, voffA);
;             PG8_WAIT_V(8); PG8_WAIT_L(0); PG8_BAR; PG8_MMA(1, 0, At, B0); PG8_MMA(1, 1, At, B1); PG8_BAR; PG8_SCHED;
;     ...
;         if constexpr (ALIGN_EPI) { if (wr == 0) PG8_BAR; }
;         if constexpr (!Epi::AFTER_DRAIN) { E(acc, cur, wr, wc, fr, fq); S.done(cur); }
;         if (!has_next) break;
	s_add_i32 s0, s48, s58
	v_lshl_add_u64 v[226:227], v[226:227], 0, s[26:27]
	s_mov_b32 m0, s0
	ds_read_b128 v[194:197], v180 offset:49152
	ds_read_b128 v[198:201], v180 offset:50176
	ds_read_b128 v[202:205], v180 offset:51200
	ds_read_b128 v[206:209], v180 offset:52224
	ds_read_b128 v[210:213], v180 offset:53248
	ds_read_b128 v[214:217], v180 offset:54272
	ds_read_b128 v[218:221], v180 offset:55296
	ds_read_b128 v[222:225], v180 offset:56320
	global_load_lds_dwordx4 v[226:227], off
	s_add_i32 m0, s0, 0x2000
	s_add_u32 s0, s10, 0x40080
	v_lshl_add_u64 v[226:227], v[228:229], 0, s[26:27]
	s_addc_u32 s1, s11, 0
	s_add_i32 s10, s49, s58
	global_load_lds_dwordx4 v[226:227], off
	v_lshl_add_u64 v[226:227], s[0:1], 0, v[148:149]
	s_mov_b32 m0, s10
	s_nop 0
	global_load_lds_dwordx4 v[226:227], off
	v_lshl_add_u64 v[226:227], s[0:1], 0, v[152:153]
	s_add_i32 m0, s10, 0x2000
	s_nop 0
	global_load_lds_dwordx4 v[226:227], off
	v_lshl_add_u64 v[226:227], v[230:231], 0, s[26:27]
	s_mov_b32 m0, s79
	s_nop 0
	global_load_lds_dwordx4 v[226:227], off
	v_lshl_add_u64 v[226:227], v[232:233], 0, s[26:27]
	s_mov_b32 m0, s80
	s_nop 0
	global_load_lds_dwordx4 v[226:227], off
	s_waitcnt vmcnt(8)
	s_waitcnt lgkmcnt(0)
	s_barrier
	s_setprio 1
	s_waitcnt lgkmcnt(0)
	v_mfma_f32_16x16x32_bf16 v[110:113], v[82:85], v[194:197], v[110:113]
	v_mfma_f32_16x16x32_bf16 v[102:105], v[82:85], v[202:205], v[102:105]
	v_mfma_f32_16x16x32_bf16 v[94:97], v[82:85], v[210:213], v[94:97]
	v_mfma_f32_16x16x32_bf16 v[10:13], v[82:85], v[218:221], v[10:13]
	v_mfma_f32_16x16x32_bf16 v[110:113], v[86:89], v[198:201], v[110:113]
	v_mfma_f32_16x16x32_bf16 v[106:109], v[138:141], v[194:197], v[106:109]
	v_mfma_f32_16x16x32_bf16 v[102:105], v[86:89], v[206:209], v[102:105]
	v_mfma_f32_16x16x32_bf16 v[98:101], v[138:141], v[202:205], v[98:101]
	v_mfma_f32_16x16x32_bf16 v[94:97], v[86:89], v[214:217], v[94:97]
	v_mfma_f32_16x16x32_bf16 v[90:93], v[138:141], v[210:213], v[90:93]
	v_mfma_f32_16x16x32_bf16 v[86:89], v[86:89], v[222:225], v[10:13]
	v_mfma_f32_16x16x32_bf16 v[10:13], v[138:141], v[218:221], v[14:17]
	v_mfma_f32_16x16x32_bf16 v[106:109], v[142:145], v[198:201], v[106:109]
	v_mfma_f32_16x16x32_bf16 v[98:101], v[142:145], v[206:209], v[98:101]
	v_mfma_f32_16x16x32_bf16 v[90:93], v[142:145], v[214:217], v[90:93]
	v_mfma_f32_16x16x32_bf16 v[82:85], v[142:145], v[222:225], v[10:13]
	v_mfma_f32_16x16x32_bf16 v[10:13], v[166:169], v[194:197], v[46:49]
	v_mfma_f32_16x16x32_bf16 v[46:49], v[172:175], v[198:201], v[10:13]
	v_mfma_f32_16x16x32_bf16 v[10:13], v[186:189], v[194:197], v[42:45]
	v_mfma_f32_16x16x32_bf16 v[42:45], v[190:193], v[198:201], v[10:13]
	v_mfma_f32_16x16x32_bf16 v[10:13], v[166:169], v[202:205], v[38:41]
	v_mfma_f32_16x16x32_bf16 v[38:41], v[172:175], v[206:209], v[10:13]
	v_mfma_f32_16x16x32_bf16 v[10:13], v[186:189], v[202:205], v[34:37]
	v_mfma_f32_16x16x32_bf16 v[34:37], v[190:193], v[206:209], v[10:13]
	v_mfma_f32_16x16x32_bf16 v[10:13], v[166:169], v[210:213], v[30:33]
	v_mfma_f32_16x16x32_bf16 v[30:33], v[172:175], v[214:217], v[10:13]
	v_mfma_f32_16x16x32_bf16 v[10:13], v[186:189], v[210:213], v[26:29]
	v_mfma_f32_16x16x32_bf16 v[26:29], v[190:193], v[214:217], v[10:13]
	v_mfma_f32_16x16x32_bf16 v[10:13], v[166:169], v[218:221], v[22:25]
	v_mfma_f32_16x16x32_bf16 v[22:25], v[172:175], v[222:225], v[10:13]
	v_mfma_f32_16x16x32_bf16 v[10:13], v[186:189], v[218:221], v[18:21]
	v_mfma_f32_16x16x32_bf16 v[18:21], v[190:193], v[222:225], v[10:13]
	s_setprio 0
	s_barrier
	s_add_i32 s41, s41, 2
	s_add_u32 s8, s8, 0x100
	s_addc_u32 s9, s9, 0
	s_add_u32 s17, s17, 0x100
	s_addc_u32 s39, s39, 0
	s_cmp_gt_u32 s41, 13
	s_cbranch_scc0 .LBB0_176
	s_and_b64 vcc, exec, s[30:31]
	s_cbranch_vccnz .LBB0_181
	s_lshl_b32 s48, s50, 8
	s_cmp_gt_i32 s50, 12
	v_lshl_add_u32 v166, s6, 8, v171
	s_cbranch_scc0 .LBB0_182

; #define PG8_STAGE(bufoff, gbase, voff) do { _Pragma("unroll") for (int _i = 0; _i < 2; ++_i) \
;         __builtin_amdgcn_global_load_lds((const unsigned*)((const char*)(gbase) + (voff)[_i]), (PG8_LAS unsigned*)(lds + (bufoff) + ldsw + _i * 8192), 16, 0, 0); } while (0)
; #define PG8_LDA(dst, b, h) do { _Pragma("unroll") for (int m = 0; m < 4; ++m) _Pragma("unroll") for (int k = 0; k < 2; ++k) dst[m][k] = *(const PG8_LAS bf16x8*)(lds + PG8_SA(b, h) + aoff + m * 2048 + k * 1024); } while (0)
; #define PG8_LDB(dst, b, h) do { _Pragma("unroll") for (int n = 0; n < 2; ++n) _Pragma("unroll") for (int k = 0; k < 2; ++k) dst[n][k] = *(const PG8_LAS bf16x8*)(lds + PG8_SB(b, h) + boff + n * 2048 + k * 1024); } while (0)
; #define PG8_MMA(ai, bj, At, Bt) do { __builtin_amdgcn_s_setprio(1); _Pragma("unroll") for (int m = 0; m < 4; ++m) _Pragma("unroll") for (int n = 0; n < 2; ++n) _Pragma("unroll") for (int k = 0; k < 2; ++k) \
;         acc[ai][bj][m][n] = __builtin_amdgcn_mfma_f32_16x16x32_bf16(Bt[n][k], At[m][k], acc[ai][bj][m][n], 0, 0, 0); __builtin_amdgcn_s_setprio(0); } while (0)
; #define PG8_WAIT_V(n) asm volatile("s_waitcnt vmcnt(" #n ")" ::: "memory")
; #define PG8_WAIT_L(n) asm volatile("s_waitcnt lgkmcnt(" #n ")" ::: "memory")
; #define PG8_BAR __builtin_amdgcn_s_barrier()
; #define PG8_SCHED __builtin_amdgcn_sched_barrier(0)
; template <class Epi, class Sched, bool ALIGN_EPI = false, bool SP2 = false>
; __device__ __forceinline__ void gemm_phase(PG8_LAS unsigned char* lds, const Gemm g, const Sched& S, const Epi& E) {
;     ...
;             PG8_LDB(B0, 0, 0); PG8_LDB(B1, 0, 1); PG8_SCHED; PG8_LDA(At, 0, 0); PG8_STAGE(PG8_SA(1, 1), a1 + hstep, voffA);
;             PG8_WAIT_V(8); PG8_WAIT_L(0); PG8_BAR; PG8_MMA(0, 0, At, B0); PG8_MMA(0, 1, At, B1); PG8_BAR; PG8_SCHED;
;             PG8_LDA(At, 0, 1); PG8_STAGE(PG8_SB(0, 0), b2, voffB); PG8_STAGE(PG8_SB(0, 1), b2 + hstep, voffB); PG8_STAGE(PG8_SA(0, 0), a2, voffA);
;             PG8_WAIT_V(8); PG8_WAIT_L(0); PG8_BAR; PG8_MMA(1, 0, At, B0); PG8_MMA(1, 1, At, B1); PG8_BAR; PG8_SCHED;
.LBB0_1422:
	ds_read_b128 v[146:149], v152
	ds_read_b128 v[156:159], v152 offset:1024
	ds_read_b128 v[160:163], v152 offset:2048
	ds_read_b128 v[164:167], v152 offset:3072
	ds_read_b128 v[168:171], v153
	ds_read_b128 v[172:175], v153 offset:1024
	ds_read_b128 v[176:179], v153 offset:2048
	ds_read_b128 v[180:183], v153 offset:3072
	s_add_u32 s0, s34, 0xfffc0080
	s_addc_u32 s1, s35, -1
	s_cmp_eq_u32 s58, 12
	s_cselect_b32 s39, s23, s1
	s_cselect_b32 s38, s29, s0
	s_cselect_b32 s37, s21, s57
	s_cselect_b32 s36, s55, s56
	v_lshl_add_u64 v[208:209], s[34:35], 0, v[138:139]
	s_add_i32 m0, s31, 0xc000
	ds_read_b128 v[184:187], v154
	ds_read_b128 v[188:191], v154 offset:1024
	ds_read_b128 v[192:195], v154 offset:2048
	ds_read_b128 v[196:199], v154 offset:3072
	ds_read_b128 v[200:203], v154 offset:4096
	ds_read_b128 v[204:207], v154 offset:5120
	ds_read_b128 v[212:215], v154 offset:6144
	ds_read_b128 v[216:219], v154 offset:7168
	global_load_lds_dwordx4 v[208:209], off
	v_lshl_add_u64 v[208:209], s[34:35], 0, v[140:141]
	s_add_i32 m0, s31, 0xe000
	s_nop 0
	global_load_lds_dwordx4 v[208:209], off
	s_waitcnt vmcnt(8)
	s_waitcnt lgkmcnt(0)
	s_barrier
	s_setprio 1
	s_waitcnt lgkmcnt(0)
	v_mfma_f32_16x16x32_bf16 v[126:129], v[146:149], v[184:187], v[126:129]
	v_mfma_f32_16x16x32_bf16 v[122:125], v[160:163], v[184:187], v[122:125]
	v_mfma_f32_16x16x32_bf16 v[110:113], v[146:149], v[192:195], v[110:113]
	v_mfma_f32_16x16x32_bf16 v[106:109], v[160:163], v[192:195], v[106:109]
	v_mfma_f32_16x16x32_bf16 v[94:97], v[146:149], v[200:203], v[94:97]
	v_mfma_f32_16x16x32_bf16 v[90:93], v[160:163], v[200:203], v[90:93]
	v_mfma_f32_16x16x32_bf16 v[78:81], v[146:149], v[212:215], v[78:81]
	v_mfma_f32_16x16x32_bf16 v[74:77], v[160:163], v[212:215], v[74:77]
	v_mfma_f32_16x16x32_bf16 v[126:129], v[156:159], v[188:191], v[126:129]
	v_mfma_f32_16x16x32_bf16 v[122:125], v[164:167], v[188:191], v[122:125]
	v_mfma_f32_16x16x32_bf16 v[110:113], v[156:159], v[196:199], v[110:113]
	v_mfma_f32_16x16x32_bf16 v[106:109], v[164:167], v[196:199], v[106:109]
	v_mfma_f32_16x16x32_bf16 v[94:97], v[156:159], v[204:207], v[94:97]
	v_mfma_f32_16x16x32_bf16 v[90:93], v[164:167], v[204:207], v[90:93]
	v_mfma_f32_16x16x32_bf16 v[78:81], v[156:159], v[216:219], v[78:81]
	v_mfma_f32_16x16x32_bf16 v[74:77], v[164:167], v[216:219], v[74:77]
	v_mfma_f32_16x16x32_bf16 v[118:121], v[168:171], v[184:187], v[118:121]
	v_mfma_f32_16x16x32_bf16 v[114:117], v[176:179], v[184:187], v[114:117]
	v_mfma_f32_16x16x32_bf16 v[102:105], v[168:171], v[192:195], v[102:105]
	v_mfma_f32_16x16x32_bf16 v[98:101], v[176:179], v[192:195], v[98:101]
	v_mfma_f32_16x16x32_bf16 v[86:89], v[168:171], v[200:203], v[86:89]
	v_mfma_f32_16x16x32_bf16 v[82:85], v[176:179], v[200:203], v[82:85]
	v_mfma_f32_16x16x32_bf16 v[70:73], v[168:171], v[212:215], v[70:73]
	v_mfma_f32_16x16x32_bf16 v[66:69], v[176:179], v[212:215], v[66:69]
	v_mfma_f32_16x16x32_bf16 v[118:121], v[172:175], v[188:191], v[118:121]
	v_mfma_f32_16x16x32_bf16 v[114:117], v[180:183], v[188:191], v[114:117]
	v_mfma_f32_16x16x32_bf16 v[102:105], v[172:175], v[196:199], v[102:105]
	v_mfma_f32_16x16x32_bf16 v[98:101], v[180:183], v[196:199], v[98:101]
	v_mfma_f32_16x16x32_bf16 v[86:89], v[172:175], v[204:207], v[86:89]
	v_mfma_f32_16x16x32_bf16 v[82:85], v[180:183], v[204:207], v[82:85]
	v_mfma_f32_16x16x32_bf16 v[70:73], v[172:175], v[216:219], v[70:73]
	v_mfma_f32_16x16x32_bf16 v[66:69], v[180:183], v[216:219], v[66:69]
	s_setprio 0
	s_barrier
	s_add_i32 s0, s53, s44
	v_lshl_add_u64 v[208:209], s[36:37], 0, v[132:133]
	s_mov_b32 m0, s0
	ds_read_b128 v[184:187], v154 offset:16384
	ds_read_b128 v[188:191], v154 offset:17408
	ds_read_b128 v[192:195], v154 offset:18432
	ds_read_b128 v[196:199], v154 offset:19456
	ds_read_b128 v[200:203], v154 offset:20480
	ds_read_b128 v[204:207], v154 offset:21504
	ds_read_b128 v[212:215], v154 offset:22528
	ds_read_b128 v[216:219], v154 offset:23552
	global_load_lds_dwordx4 v[208:209], off
	s_add_i32 m0, s0, 0x2000
	s_add_u32 s0, s36, 0x40000
	v_lshl_add_u64 v[220:221], s[36:37], 0, v[136:137]
	s_addc_u32 s1, s37, 0
	s_add_i32 s59, s54, s44
	global_load_lds_dwordx4 v[220:221], off
	v_lshl_add_u64 v[222:223], s[0:1], 0, v[132:133]
	s_mov_b32 m0, s59
	v_lshl_add_u64 v[224:225], s[38:39], 0, v[134:135]
	global_load_lds_dwordx4 v[222:223], off
	v_lshl_add_u64 v[222:223], s[0:1], 0, v[136:137]
	s_add_i32 m0, s59, 0x2000
	s_nop 0
	global_load_lds_dwordx4 v[222:223], off
	v_lshl_add_u64 v[222:223], s[38:39], 0, v[130:131]
	s_mov_b32 m0, s31
	s_nop 0
	global_load_lds_dwordx4 v[222:223], off
	s_mov_b32 m0, s45
	s_nop 0
	global_load_lds_dwordx4 v[224:225], off
	s_waitcnt vmcnt(8)
	s_waitcnt lgkmcnt(0)
	s_barrier
; #define PG8_STAGE(bufoff, gbase, voff) do { _Pragma("unroll") for (int _i = 0; _i < 2; ++_i) \
;         __builtin_amdgcn_global_load_lds((const unsigned*)((const char*)(gbase) + (voff)[_i]), (PG8_LAS unsigned*)(lds + (bufoff) + ldsw + _i * 8192), 16, 0, 0); } while (0)
; #define PG8_LDA(dst, b, h) do { _Pragma("unroll") for (int m = 0; m < 4; ++m) _Pragma("unroll") for (int k = 0; k < 2; ++k) dst[m][k] = *(const PG8_LAS bf16x8*)(lds + PG8_SA(b, h) + aoff + m * 2048 + k * 1024); } while (0)
; #define PG8_LDB(dst, b, h) do { _Pragma("unroll") for (int n = 0; n < 2; ++n) _Pragma("unroll") for (int k = 0; k < 2; ++k) dst[n][k] = *(const PG8_LAS bf16x8*)(lds + PG8_SB(b, h) + boff + n * 2048 + k * 1024); } while (0)
; #define PG8_MMA(ai, bj, At, Bt) do { __builtin_amdgcn_s_setprio(1); _Pragma("unroll") for (int m = 0; m < 4; ++m) _Pragma("unroll") for (int n = 0; n < 2; ++n) _Pragma("unroll") for (int k = 0; k < 2; ++k) \
;         acc[ai][bj][m][n] = __builtin_amdgcn_mfma_f32_16x16x32_bf16(Bt[n][k], At[m][k], acc[ai][bj][m][n], 0, 0, 0); __builtin_amdgcn_s_setprio(0); } while (0)
; #define PG8_WAIT_V(n) asm volatile("s_waitcnt vmcnt(" #n ")" ::: "memory")
; #define PG8_WAIT_L(n) asm volatile("s_waitcnt lgkmcnt(" #n ")" ::: "memory")
; #define PG8_BAR __builtin_amdgcn_s_barrier()
; #define PG8_SCHED __builtin_amdgcn_sched_barrier(0)
; template <class Epi, class Sched, bool ALIGN_EPI = false, bool SP2 = false>
; __device__ __forceinline__ void gemm_phase(PG8_LAS unsigned char* lds, const Gemm g, const Sched& S, const Epi& E) {
;     ...
;             PG8_WAIT_V(8); PG8_WAIT_L(0); PG8_BAR; PG8_MMA(1, 0, At, B0); PG8_MMA(1, 1, At, B1); PG8_BAR; PG8_SCHED;
;             PG8_LDB(B0, 1, 0); PG8_LDB(B1, 1, 1); PG8_SCHED; PG8_LDA(At, 1, 0); PG8_STAGE(PG8_SA(0, 1), a2 + hstep, voffA);
;             PG8_WAIT_V(8); PG8_WAIT_L(0); PG8_BAR; PG8_MMA(0, 0, At, B0); PG8_MMA(0, 1, At, B1); PG8_BAR; PG8_SCHED;
	s_setprio 1
	s_waitcnt lgkmcnt(0)
	v_mfma_f32_16x16x32_bf16 v[62:65], v[146:149], v[184:187], v[62:65]
	v_mfma_f32_16x16x32_bf16 v[58:61], v[160:163], v[184:187], v[58:61]
	v_mfma_f32_16x16x32_bf16 v[46:49], v[146:149], v[192:195], v[46:49]
	v_mfma_f32_16x16x32_bf16 v[42:45], v[160:163], v[192:195], v[42:45]
	v_mfma_f32_16x16x32_bf16 v[30:33], v[146:149], v[200:203], v[30:33]
	v_mfma_f32_16x16x32_bf16 v[26:29], v[160:163], v[200:203], v[26:29]
	v_mfma_f32_16x16x32_bf16 v[14:17], v[146:149], v[212:215], v[14:17]
	v_mfma_f32_16x16x32_bf16 v[10:13], v[160:163], v[212:215], v[10:13]
	v_mfma_f32_16x16x32_bf16 v[62:65], v[156:159], v[188:191], v[62:65]
	v_mfma_f32_16x16x32_bf16 v[58:61], v[164:167], v[188:191], v[58:61]
	v_mfma_f32_16x16x32_bf16 v[46:49], v[156:159], v[196:199], v[46:49]
	v_mfma_f32_16x16x32_bf16 v[42:45], v[164:167], v[196:199], v[42:45]
	v_mfma_f32_16x16x32_bf16 v[30:33], v[156:159], v[204:207], v[30:33]
	v_mfma_f32_16x16x32_bf16 v[26:29], v[164:167], v[204:207], v[26:29]
	v_mfma_f32_16x16x32_bf16 v[14:17], v[156:159], v[216:219], v[14:17]
	v_mfma_f32_16x16x32_bf16 v[10:13], v[164:167], v[216:219], v[10:13]
	v_mfma_f32_16x16x32_bf16 v[54:57], v[168:171], v[184:187], v[54:57]
	v_mfma_f32_16x16x32_bf16 v[50:53], v[176:179], v[184:187], v[50:53]
	v_mfma_f32_16x16x32_bf16 v[38:41], v[168:171], v[192:195], v[38:41]
	v_mfma_f32_16x16x32_bf16 v[34:37], v[176:179], v[192:195], v[34:37]
	v_mfma_f32_16x16x32_bf16 v[22:25], v[168:171], v[200:203], v[22:25]
	v_mfma_f32_16x16x32_bf16 v[18:21], v[176:179], v[200:203], v[18:21]
	v_mfma_f32_16x16x32_bf16 v[6:9], v[168:171], v[212:215], v[6:9]
	v_mfma_f32_16x16x32_bf16 v[2:5], v[176:179], v[212:215], v[2:5]
	v_mfma_f32_16x16x32_bf16 v[54:57], v[172:175], v[188:191], v[54:57]
	v_mfma_f32_16x16x32_bf16 v[50:53], v[180:183], v[188:191], v[50:53]
	v_mfma_f32_16x16x32_bf16 v[38:41], v[172:175], v[196:199], v[38:41]
	v_mfma_f32_16x16x32_bf16 v[34:37], v[180:183], v[196:199], v[34:37]
	v_mfma_f32_16x16x32_bf16 v[22:25], v[172:175], v[204:207], v[22:25]
	v_mfma_f32_16x16x32_bf16 v[18:21], v[180:183], v[204:207], v[18:21]
	v_mfma_f32_16x16x32_bf16 v[6:9], v[172:175], v[216:219], v[6:9]
	v_mfma_f32_16x16x32_bf16 v[2:5], v[180:183], v[216:219], v[2:5]
	s_setprio 0
	s_barrier
	s_add_i32 s59, 0, 0x18000
	s_add_i32 s60, 0, 0x1c000
	v_add_u32_e32 v164, s59, v150
	v_add_u32_e32 v180, s60, v150
	ds_read_b128 v[146:149], v164
	ds_read_b128 v[156:159], v164 offset:1024
	ds_read_b128 v[160:163], v164 offset:2048
	ds_read_b128 v[164:167], v164 offset:3072
	ds_read_b128 v[168:171], v180
	ds_read_b128 v[172:175], v180 offset:1024
	ds_read_b128 v[176:179], v180 offset:2048
	ds_read_b128 v[180:183], v180 offset:3072
	s_add_u32 s0, s38, 0x40000
	s_addc_u32 s1, s39, 0
	s_mov_b32 m0, s46
	v_lshl_add_u64 v[226:227], s[0:1], 0, v[130:131]
	ds_read_b128 v[184:187], v154 offset:32768
	ds_read_b128 v[188:191], v154 offset:33792
	ds_read_b128 v[192:195], v154 offset:34816
	ds_read_b128 v[196:199], v154 offset:35840
	ds_read_b128 v[200:203], v154 offset:36864
	ds_read_b128 v[204:207], v154 offset:37888
	ds_read_b128 v[212:215], v154 offset:38912
	ds_read_b128 v[216:219], v154 offset:39936
	global_load_lds_dwordx4 v[226:227], off
	v_lshl_add_u64 v[226:227], s[0:1], 0, v[134:135]
	s_mov_b32 m0, s47
	s_nop 0
	global_load_lds_dwordx4 v[226:227], off
	s_waitcnt vmcnt(8)
	s_waitcnt lgkmcnt(0)
	s_barrier
	s_setprio 1
	s_waitcnt lgkmcnt(0)
	v_mfma_f32_16x16x32_bf16 v[126:129], v[146:149], v[184:187], v[126:129]
	v_mfma_f32_16x16x32_bf16 v[122:125], v[160:163], v[184:187], v[122:125]
	v_mfma_f32_16x16x32_bf16 v[110:113], v[146:149], v[192:195], v[110:113]
	v_mfma_f32_16x16x32_bf16 v[106:109], v[160:163], v[192:195], v[106:109]
	v_mfma_f32_16x16x32_bf16 v[94:97], v[146:149], v[200:203], v[94:97]
	v_mfma_f32_16x16x32_bf16 v[90:93], v[160:163], v[200:203], v[90:93]
	v_mfma_f32_16x16x32_bf16 v[78:81], v[146:149], v[212:215], v[78:81]
	v_mfma_f32_16x16x32_bf16 v[74:77], v[160:163], v[212:215], v[74:77]
	v_mfma_f32_16x16x32_bf16 v[126:129], v[156:159], v[188:191], v[126:129]
	v_mfma_f32_16x16x32_bf16 v[122:125], v[164:167], v[188:191], v[122:125]
	v_mfma_f32_16x16x32_bf16 v[110:113], v[156:159], v[196:199], v[110:113]
	v_mfma_f32_16x16x32_bf16 v[106:109], v[164:167], v[196:199], v[106:109]
	v_mfma_f32_16x16x32_bf16 v[94:97], v[156:159], v[204:207], v[94:97]
	v_mfma_f32_16x16x32_bf16 v[90:93], v[164:167], v[204:207], v[90:93]
	v_mfma_f32_16x16x32_bf16 v[78:81], v[156:159], v[216:219], v[78:81]
	v_mfma_f32_16x16x32_bf16 v[74:77], v[164:167], v[216:219], v[74:77]
	v_mfma_f32_16x16x32_bf16 v[118:121], v[168:171], v[184:187], v[118:121]
	v_mfma_f32_16x16x32_bf16 v[114:117], v[176:179], v[184:187], v[114:117]
	v_mfma_f32_16x16x32_bf16 v[102:105], v[168:171], v[192:195], v[102:105]
	v_mfma_f32_16x16x32_bf16 v[98:101], v[176:179], v[192:195], v[98:101]
	v_mfma_f32_16x16x32_bf16 v[86:89], v[168:171], v[200:203], v[86:89]
	v_mfma_f32_16x16x32_bf16 v[82:85], v[176:179], v[200:203], v[82:85]
	v_mfma_f32_16x16x32_bf16 v[70:73], v[168:171], v[212:215], v[70:73]
	v_mfma_f32_16x16x32_bf16 v[66:69], v[176:179], v[212:215], v[66:69]
	v_mfma_f32_16x16x32_bf16 v[118:121], v[172:175], v[188:191], v[118:121]
	v_mfma_f32_16x16x32_bf16 v[114:117], v[180:183], v[188:191], v[114:117]
	v_mfma_f32_16x16x32_bf16 v[102:105], v[172:175], v[196:199], v[102:105]
	v_mfma_f32_16x16x32_bf16 v[98:101], v[180:183], v[196:199], v[98:101]
	v_mfma_f32_16x16x32_bf16 v[86:89], v[172:175], v[204:207], v[86:89]
	v_mfma_f32_16x16x32_bf16 v[82:85], v[180:183], v[204:207], v[82:85]
	v_mfma_f32_16x16x32_bf16 v[70:73], v[172:175], v[216:219], v[70:73]
	v_mfma_f32_16x16x32_bf16 v[66:69], v[180:183], v[216:219], v[66:69]
	s_setprio 0
	s_barrier
; #define PG8_STAGE(bufoff, gbase, voff) do { _Pragma("unroll") for (int _i = 0; _i < 2; ++_i) \
;         __builtin_amdgcn_global_load_lds((const unsigned*)((const char*)(gbase) + (voff)[_i]), (PG8_LAS unsigned*)(lds + (bufoff) + ldsw + _i * 8192), 16, 0, 0); } while (0)
; #define PG8_LDA(dst, b, h) do { _Pragma("unroll") for (int m = 0; m < 4; ++m) _Pragma("unroll") for (int k = 0; k < 2; ++k) dst[m][k] = *(const PG8_LAS bf16x8*)(lds + PG8_SA(b, h) + aoff + m * 2048 + k * 1024); } while (0)
; #define PG8_MMA(ai, bj, At, Bt) do { __builtin_amdgcn_s_setprio(1); _Pragma("unroll") for (int m = 0; m < 4; ++m) _Pragma("unroll") for (int n = 0; n < 2; ++n) _Pragma("unroll") for (int k = 0; k < 2; ++k) \
;         acc[ai][bj][m][n] = __builtin_amdgcn_mfma_f32_16x16x32_bf16(Bt[n][k], At[m][k], acc[ai][bj][m][n], 0, 0, 0); __builtin_amdgcn_s_setprio(0); } while (0)
; #define PG8_WAIT_V(n) asm volatile("s_waitcnt vmcnt(" #n ")" ::: "memory")
; #define PG8_WAIT_L(n) asm volatile("s_waitcnt lgkmcnt(" #n ")" ::: "memory")
; #define PG8_BAR __builtin_amdgcn_s_barrier()
; #define PG8_SCHED __builtin_amdgcn_sched_barrier(0)
; template <class Epi, class Sched, bool ALIGN_EPI = false, bool SP2 = false>
; __device__ __forceinline__ void gemm_phase(PG8_LAS unsigned char* lds, const Gemm g, const Sched& S, const Epi& E) {
;     ...
;         for (int t = 0; t < nt; t += 2) {
;             const bool last = (t == nt - 2);
;             const char* a1 = cA + (size_t)(t + 1) * kstep;
;             const char* a2 = last ? nA : cA + (size_t)(t + 2) * kstep; const char* b2 = last ? nB : cB + (size_t)(t + 2) * kstep;
;             const char* a3 = a2 + kstep; const char* b3 = b2 + kstep;
;             if (last && has_next) S.a_ready(nxt);
;     ...
;             PG8_LDA(At, 1, 1); PG8_STAGE(PG8_SB(1, 0), b3, voffB); PG8_STAGE(PG8_SB(1, 1), b3 + hstep, voffB); PG8_STAGE(PG8_SA(1, 0), a3, voffA);
;             PG8_WAIT_V(8); PG8_WAIT_L(0); PG8_BAR; PG8_MMA(1, 0, At, B0); PG8_MMA(1, 1, At, B1); PG8_BAR; PG8_SCHED;
;     ...
;         if constexpr (ALIGN_EPI) { if (wr == 0) PG8_BAR; }
;         if constexpr (!Epi::AFTER_DRAIN) { E(acc, cur, wr, wc, fr, fq); S.done(cur); }
;         if (!has_next) break;
	s_add_i32 s0, s59, s44
	v_lshl_add_u64 v[208:209], v[208:209], 0, s[16:17]
	s_mov_b32 m0, s0
	ds_read_b128 v[184:187], v154 offset:49152
	ds_read_b128 v[188:191], v154 offset:50176
	ds_read_b128 v[192:195], v154 offset:51200
	ds_read_b128 v[196:199], v154 offset:52224
	ds_read_b128 v[200:203], v154 offset:53248
	ds_read_b128 v[204:207], v154 offset:54272
	ds_read_b128 v[212:215], v154 offset:55296
	ds_read_b128 v[216:219], v154 offset:56320
	global_load_lds_dwordx4 v[208:209], off
	s_add_i32 m0, s0, 0x2000
	s_add_u32 s0, s36, 0x40080
	v_lshl_add_u64 v[208:209], v[220:221], 0, s[16:17]
	s_addc_u32 s1, s37, 0
	s_add_i32 s36, s60, s44
	global_load_lds_dwordx4 v[208:209], off
	v_lshl_add_u64 v[208:209], s[0:1], 0, v[132:133]
	s_mov_b32 m0, s36
	s_nop 0
	global_load_lds_dwordx4 v[208:209], off
	v_lshl_add_u64 v[208:209], s[0:1], 0, v[136:137]
	s_add_i32 m0, s36, 0x2000
	s_nop 0
	global_load_lds_dwordx4 v[208:209], off
	v_lshl_add_u64 v[208:209], v[222:223], 0, s[16:17]
	s_mov_b32 m0, s49
	s_nop 0
	global_load_lds_dwordx4 v[208:209], off
	v_lshl_add_u64 v[208:209], v[224:225], 0, s[16:17]
	s_mov_b32 m0, s50
	s_nop 0
	global_load_lds_dwordx4 v[208:209], off
	s_waitcnt vmcnt(8)
	s_waitcnt lgkmcnt(0)
	s_barrier
	s_setprio 1
	s_waitcnt lgkmcnt(0)
	v_mfma_f32_16x16x32_bf16 v[62:65], v[146:149], v[184:187], v[62:65]
	v_mfma_f32_16x16x32_bf16 v[58:61], v[160:163], v[184:187], v[58:61]
	v_mfma_f32_16x16x32_bf16 v[46:49], v[146:149], v[192:195], v[46:49]
	v_mfma_f32_16x16x32_bf16 v[42:45], v[160:163], v[192:195], v[42:45]
	v_mfma_f32_16x16x32_bf16 v[30:33], v[146:149], v[200:203], v[30:33]
	v_mfma_f32_16x16x32_bf16 v[26:29], v[160:163], v[200:203], v[26:29]
	v_mfma_f32_16x16x32_bf16 v[14:17], v[146:149], v[212:215], v[14:17]
	v_mfma_f32_16x16x32_bf16 v[10:13], v[160:163], v[212:215], v[10:13]
	v_mfma_f32_16x16x32_bf16 v[62:65], v[156:159], v[188:191], v[62:65]
	v_mfma_f32_16x16x32_bf16 v[58:61], v[164:167], v[188:191], v[58:61]
	v_mfma_f32_16x16x32_bf16 v[46:49], v[156:159], v[196:199], v[46:49]
	v_mfma_f32_16x16x32_bf16 v[42:45], v[164:167], v[196:199], v[42:45]
	v_mfma_f32_16x16x32_bf16 v[30:33], v[156:159], v[204:207], v[30:33]
	v_mfma_f32_16x16x32_bf16 v[26:29], v[164:167], v[204:207], v[26:29]
	v_mfma_f32_16x16x32_bf16 v[14:17], v[156:159], v[216:219], v[14:17]
	v_mfma_f32_16x16x32_bf16 v[10:13], v[164:167], v[216:219], v[10:13]
	v_mfma_f32_16x16x32_bf16 v[54:57], v[168:171], v[184:187], v[54:57]
	v_mfma_f32_16x16x32_bf16 v[50:53], v[176:179], v[184:187], v[50:53]
	v_mfma_f32_16x16x32_bf16 v[38:41], v[168:171], v[192:195], v[38:41]
	v_mfma_f32_16x16x32_bf16 v[34:37], v[176:179], v[192:195], v[34:37]
	v_mfma_f32_16x16x32_bf16 v[22:25], v[168:171], v[200:203], v[22:25]
	v_mfma_f32_16x16x32_bf16 v[18:21], v[176:179], v[200:203], v[18:21]
	v_mfma_f32_16x16x32_bf16 v[6:9], v[168:171], v[212:215], v[6:9]
	v_mfma_f32_16x16x32_bf16 v[2:5], v[176:179], v[212:215], v[2:5]
	v_mfma_f32_16x16x32_bf16 v[54:57], v[172:175], v[188:191], v[54:57]
	v_mfma_f32_16x16x32_bf16 v[50:53], v[180:183], v[188:191], v[50:53]
	v_mfma_f32_16x16x32_bf16 v[38:41], v[172:175], v[196:199], v[38:41]
	v_mfma_f32_16x16x32_bf16 v[34:37], v[180:183], v[196:199], v[34:37]
	v_mfma_f32_16x16x32_bf16 v[22:25], v[172:175], v[204:207], v[22:25]
	v_mfma_f32_16x16x32_bf16 v[18:21], v[180:183], v[204:207], v[18:21]
	v_mfma_f32_16x16x32_bf16 v[6:9], v[172:175], v[216:219], v[6:9]
	v_mfma_f32_16x16x32_bf16 v[2:5], v[180:183], v[216:219], v[2:5]
	s_setprio 0
	s_barrier
	s_add_i32 s58, s58, 2
	s_add_u32 s34, s34, 0x100
	s_addc_u32 s35, s35, 0
	s_add_u32 s56, s56, 0x100
	s_addc_u32 s57, s57, 0
	s_cmp_gt_u32 s58, 13
	s_cbranch_scc0 .LBB0_1422
	s_and_b64 vcc, exec, s[18:19]
	s_cbranch_vccz .LBB0_1425
	s_barrier

; #define PG8_STAGE(bufoff, gbase, voff) do { _Pragma("unroll") for (int _i = 0; _i < 2; ++_i) \
;         __builtin_amdgcn_global_load_lds((const unsigned*)((const char*)(gbase) + (voff)[_i]), (PG8_LAS unsigned*)(lds + (bufoff) + ldsw + _i * 8192), 16, 0, 0); } while (0)
; #define PG8_LDA(dst, b, h) do { _Pragma("unroll") for (int m = 0; m < 4; ++m) _Pragma("unroll") for (int k = 0; k < 2; ++k) dst[m][k] = *(const PG8_LAS bf16x8*)(lds + PG8_SA(b, h) + aoff + m * 2048 + k * 1024); } while (0)
; #define PG8_LDB(dst, b, h) do { _Pragma("unroll") for (int n = 0; n < 2; ++n) _Pragma("unroll") for (int k = 0; k < 2; ++k) dst[n][k] = *(const PG8_LAS bf16x8*)(lds + PG8_SB(b, h) + boff + n * 2048 + k * 1024); } while (0)
; #define PG8_MMA(ai, bj, At, Bt) do { __builtin_amdgcn_s_setprio(1); _Pragma("unroll") for (int m = 0; m < 4; ++m) _Pragma("unroll") for (int n = 0; n < 2; ++n) _Pragma("unroll") for (int k = 0; k < 2; ++k) \
;         acc[ai][bj][m][n] = __builtin_amdgcn_mfma_f32_16x16x32_bf16(Bt[n][k], At[m][k], acc[ai][bj][m][n], 0, 0, 0); __builtin_amdgcn_s_setprio(0); } while (0)
; #define PG8_WAIT_V(n) asm volatile("s_waitcnt vmcnt(" #n ")" ::: "memory")
; #define PG8_WAIT_L(n) asm volatile("s_waitcnt lgkmcnt(" #n ")" ::: "memory")
; #define PG8_BAR __builtin_amdgcn_s_barrier()
; #define PG8_SCHED __builtin_amdgcn_sched_barrier(0)
; template <class Epi, class Sched, bool ALIGN_EPI = false, bool SP2 = false>
; __device__ __forceinline__ void gemm_phase(PG8_LAS unsigned char* lds, const Gemm g, const Sched& S, const Epi& E) {
;     ...
;             PG8_LDB(B0, 0, 0); PG8_LDB(B1, 0, 1); PG8_SCHED; PG8_LDA(At, 0, 0); PG8_STAGE(PG8_SA(1, 1), a1 + hstep, voffA);
;             PG8_WAIT_V(8); PG8_WAIT_L(0); PG8_BAR; PG8_MMA(0, 0, At, B0); PG8_MMA(0, 1, At, B1); PG8_BAR; PG8_SCHED;
;             PG8_LDA(At, 0, 1); PG8_STAGE(PG8_SB(0, 0), b2, voffB); PG8_STAGE(PG8_SB(0, 1), b2 + hstep, voffB); PG8_STAGE(PG8_SA(0, 0), a2, voffA);
;             PG8_WAIT_V(8); PG8_WAIT_L(0); PG8_BAR; PG8_MMA(1, 0, At, B0); PG8_MMA(1, 1, At, B1); PG8_BAR; PG8_SCHED;
.LBB0_1472:
	ds_read_b128 v[154:157], v150
	ds_read_b128 v[158:161], v150 offset:1024
	ds_read_b128 v[162:165], v150 offset:2048
	ds_read_b128 v[166:169], v150 offset:3072
	ds_read_b128 v[170:173], v151
	ds_read_b128 v[174:177], v151 offset:1024
	ds_read_b128 v[178:181], v151 offset:2048
	ds_read_b128 v[182:185], v151 offset:3072
	s_add_u32 s0, s30, 0xfffc0080
	s_addc_u32 s1, s31, -1
	s_cmp_eq_u32 s72, 12
	s_cselect_b32 s37, s23, s1
	s_cselect_b32 s36, s58, s0
	s_cselect_b32 s35, s21, s61
	s_cselect_b32 s34, s59, s60
	v_lshl_add_u64 v[146:147], s[30:31], 0, v[138:139]
	s_add_i32 m0, s29, 0xc000
	ds_read_b128 v[186:189], v152
	ds_read_b128 v[190:193], v152 offset:1024
	ds_read_b128 v[194:197], v152 offset:2048
	ds_read_b128 v[198:201], v152 offset:3072
	ds_read_b128 v[202:205], v152 offset:4096
	ds_read_b128 v[206:209], v152 offset:5120
	ds_read_b128 v[212:215], v152 offset:6144
	ds_read_b128 v[216:219], v152 offset:7168
	global_load_lds_dwordx4 v[146:147], off
	v_lshl_add_u64 v[146:147], s[30:31], 0, v[140:141]
	s_add_i32 m0, s29, 0xe000
	s_nop 0
	global_load_lds_dwordx4 v[146:147], off
	s_waitcnt vmcnt(8)
	s_waitcnt lgkmcnt(0)
	s_barrier
	s_setprio 1
	s_waitcnt lgkmcnt(0)
	v_mfma_f32_16x16x32_bf16 v[126:129], v[154:157], v[186:189], v[126:129]
	v_mfma_f32_16x16x32_bf16 v[122:125], v[162:165], v[186:189], v[122:125]
	v_mfma_f32_16x16x32_bf16 v[110:113], v[154:157], v[194:197], v[110:113]
	v_mfma_f32_16x16x32_bf16 v[106:109], v[162:165], v[194:197], v[106:109]
	v_mfma_f32_16x16x32_bf16 v[94:97], v[154:157], v[202:205], v[94:97]
	v_mfma_f32_16x16x32_bf16 v[90:93], v[162:165], v[202:205], v[90:93]
	v_mfma_f32_16x16x32_bf16 v[78:81], v[154:157], v[212:215], v[78:81]
	v_mfma_f32_16x16x32_bf16 v[74:77], v[162:165], v[212:215], v[74:77]
	v_mfma_f32_16x16x32_bf16 v[126:129], v[158:161], v[190:193], v[126:129]
	v_mfma_f32_16x16x32_bf16 v[122:125], v[166:169], v[190:193], v[122:125]
	v_mfma_f32_16x16x32_bf16 v[110:113], v[158:161], v[198:201], v[110:113]
	v_mfma_f32_16x16x32_bf16 v[106:109], v[166:169], v[198:201], v[106:109]
	v_mfma_f32_16x16x32_bf16 v[94:97], v[158:161], v[206:209], v[94:97]
	v_mfma_f32_16x16x32_bf16 v[90:93], v[166:169], v[206:209], v[90:93]
	v_mfma_f32_16x16x32_bf16 v[78:81], v[158:161], v[216:219], v[78:81]
	v_mfma_f32_16x16x32_bf16 v[74:77], v[166:169], v[216:219], v[74:77]
	v_mfma_f32_16x16x32_bf16 v[118:121], v[170:173], v[186:189], v[118:121]
	v_mfma_f32_16x16x32_bf16 v[114:117], v[178:181], v[186:189], v[114:117]
	v_mfma_f32_16x16x32_bf16 v[102:105], v[170:173], v[194:197], v[102:105]
	v_mfma_f32_16x16x32_bf16 v[98:101], v[178:181], v[194:197], v[98:101]
	v_mfma_f32_16x16x32_bf16 v[86:89], v[170:173], v[202:205], v[86:89]
	v_mfma_f32_16x16x32_bf16 v[82:85], v[178:181], v[202:205], v[82:85]
	v_mfma_f32_16x16x32_bf16 v[70:73], v[170:173], v[212:215], v[70:73]
	v_mfma_f32_16x16x32_bf16 v[66:69], v[178:181], v[212:215], v[66:69]
	v_mfma_f32_16x16x32_bf16 v[118:121], v[174:177], v[190:193], v[118:121]
	v_mfma_f32_16x16x32_bf16 v[114:117], v[182:185], v[190:193], v[114:117]
	v_mfma_f32_16x16x32_bf16 v[102:105], v[174:177], v[198:201], v[102:105]
	v_mfma_f32_16x16x32_bf16 v[98:101], v[182:185], v[198:201], v[98:101]
	v_mfma_f32_16x16x32_bf16 v[86:89], v[174:177], v[206:209], v[86:89]
	v_mfma_f32_16x16x32_bf16 v[82:85], v[182:185], v[206:209], v[82:85]
	v_mfma_f32_16x16x32_bf16 v[70:73], v[174:177], v[216:219], v[70:73]
	v_mfma_f32_16x16x32_bf16 v[66:69], v[182:185], v[216:219], v[66:69]
	s_setprio 0
	s_barrier
	s_add_i32 s0, s51, s41
	v_lshl_add_u64 v[146:147], s[34:35], 0, v[132:133]
	s_mov_b32 m0, s0
	ds_read_b128 v[186:189], v152 offset:16384
	ds_read_b128 v[190:193], v152 offset:17408
	ds_read_b128 v[194:197], v152 offset:18432
	ds_read_b128 v[198:201], v152 offset:19456
	ds_read_b128 v[202:205], v152 offset:20480
	ds_read_b128 v[206:209], v152 offset:21504
	ds_read_b128 v[212:215], v152 offset:22528
	ds_read_b128 v[216:219], v152 offset:23552
	global_load_lds_dwordx4 v[146:147], off
	s_add_i32 m0, s0, 0x2000
	s_add_u32 s0, s34, 0x40000
	v_lshl_add_u64 v[220:221], s[34:35], 0, v[136:137]
	s_addc_u32 s1, s35, 0
	s_add_i32 s73, s52, s41
	global_load_lds_dwordx4 v[220:221], off
	v_lshl_add_u64 v[222:223], s[0:1], 0, v[132:133]
	s_mov_b32 m0, s73
	v_lshl_add_u64 v[224:225], s[36:37], 0, v[134:135]
	global_load_lds_dwordx4 v[222:223], off
	v_lshl_add_u64 v[222:223], s[0:1], 0, v[136:137]
	s_add_i32 m0, s73, 0x2000
	s_nop 0
	global_load_lds_dwordx4 v[222:223], off
	v_lshl_add_u64 v[222:223], s[36:37], 0, v[130:131]
	s_mov_b32 m0, s29
	s_nop 0
	global_load_lds_dwordx4 v[222:223], off
	s_mov_b32 m0, s44
	s_nop 0
	global_load_lds_dwordx4 v[224:225], off
	s_waitcnt vmcnt(8)
	s_waitcnt lgkmcnt(0)
	s_barrier
; #define PG8_STAGE(bufoff, gbase, voff) do { _Pragma("unroll") for (int _i = 0; _i < 2; ++_i) \
;         __builtin_amdgcn_global_load_lds((const unsigned*)((const char*)(gbase) + (voff)[_i]), (PG8_LAS unsigned*)(lds + (bufoff) + ldsw + _i * 8192), 16, 0, 0); } while (0)
; #define PG8_LDA(dst, b, h) do { _Pragma("unroll") for (int m = 0; m < 4; ++m) _Pragma("unroll") for (int k = 0; k < 2; ++k) dst[m][k] = *(const PG8_LAS bf16x8*)(lds + PG8_SA(b, h) + aoff + m * 2048 + k * 1024); } while (0)
; #define PG8_LDB(dst, b, h) do { _Pragma("unroll") for (int n = 0; n < 2; ++n) _Pragma("unroll") for (int k = 0; k < 2; ++k) dst[n][k] = *(const PG8_LAS bf16x8*)(lds + PG8_SB(b, h) + boff + n * 2048 + k * 1024); } while (0)
; #define PG8_MMA(ai, bj, At, Bt) do { __builtin_amdgcn_s_setprio(1); _Pragma("unroll") for (int m = 0; m < 4; ++m) _Pragma("unroll") for (int n = 0; n < 2; ++n) _Pragma("unroll") for (int k = 0; k < 2; ++k) \
;         acc[ai][bj][m][n] = __builtin_amdgcn_mfma_f32_16x16x32_bf16(Bt[n][k], At[m][k], acc[ai][bj][m][n], 0, 0, 0); __builtin_amdgcn_s_setprio(0); } while (0)
; #define PG8_WAIT_V(n) asm volatile("s_waitcnt vmcnt(" #n ")" ::: "memory")
; #define PG8_WAIT_L(n) asm volatile("s_waitcnt lgkmcnt(" #n ")" ::: "memory")
; #define PG8_BAR __builtin_amdgcn_s_barrier()
; #define PG8_SCHED __builtin_amdgcn_sched_barrier(0)
; template <class Epi, class Sched, bool ALIGN_EPI = false, bool SP2 = false>
; __device__ __forceinline__ void gemm_phase(PG8_LAS unsigned char* lds, const Gemm g, const Sched& S, const Epi& E) {
;     ...
;             PG8_WAIT_V(8); PG8_WAIT_L(0); PG8_BAR; PG8_MMA(1, 0, At, B0); PG8_MMA(1, 1, At, B1); PG8_BAR; PG8_SCHED;
;             PG8_LDB(B0, 1, 0); PG8_LDB(B1, 1, 1); PG8_SCHED; PG8_LDA(At, 1, 0); PG8_STAGE(PG8_SA(0, 1), a2 + hstep, voffA);
;             PG8_WAIT_V(8); PG8_WAIT_L(0); PG8_BAR; PG8_MMA(0, 0, At, B0); PG8_MMA(0, 1, At, B1); PG8_BAR; PG8_SCHED;
	s_setprio 1
	s_waitcnt lgkmcnt(0)
	v_mfma_f32_16x16x32_bf16 v[62:65], v[154:157], v[186:189], v[62:65]
	v_mfma_f32_16x16x32_bf16 v[58:61], v[162:165], v[186:189], v[58:61]
	v_mfma_f32_16x16x32_bf16 v[50:53], v[154:157], v[194:197], v[50:53]
	v_mfma_f32_16x16x32_bf16 v[42:45], v[162:165], v[194:197], v[42:45]
	v_mfma_f32_16x16x32_bf16 v[34:37], v[154:157], v[202:205], v[34:37]
	v_mfma_f32_16x16x32_bf16 v[26:29], v[162:165], v[202:205], v[26:29]
	v_mfma_f32_16x16x32_bf16 v[18:21], v[154:157], v[212:215], v[18:21]
	v_mfma_f32_16x16x32_bf16 v[10:13], v[162:165], v[212:215], v[10:13]
	v_mfma_f32_16x16x32_bf16 v[62:65], v[158:161], v[190:193], v[62:65]
	v_mfma_f32_16x16x32_bf16 v[58:61], v[166:169], v[190:193], v[58:61]
	v_mfma_f32_16x16x32_bf16 v[50:53], v[158:161], v[198:201], v[50:53]
	v_mfma_f32_16x16x32_bf16 v[42:45], v[166:169], v[198:201], v[42:45]
	v_mfma_f32_16x16x32_bf16 v[34:37], v[158:161], v[206:209], v[34:37]
	v_mfma_f32_16x16x32_bf16 v[26:29], v[166:169], v[206:209], v[26:29]
	v_mfma_f32_16x16x32_bf16 v[18:21], v[158:161], v[216:219], v[18:21]
	v_mfma_f32_16x16x32_bf16 v[10:13], v[166:169], v[216:219], v[10:13]
	v_mfma_f32_16x16x32_bf16 v[54:57], v[170:173], v[186:189], v[54:57]
	v_mfma_f32_16x16x32_bf16 v[46:49], v[178:181], v[186:189], v[46:49]
	v_mfma_f32_16x16x32_bf16 v[38:41], v[170:173], v[194:197], v[38:41]
	v_mfma_f32_16x16x32_bf16 v[30:33], v[178:181], v[194:197], v[30:33]
	v_mfma_f32_16x16x32_bf16 v[22:25], v[170:173], v[202:205], v[22:25]
	v_mfma_f32_16x16x32_bf16 v[14:17], v[178:181], v[202:205], v[14:17]
	v_mfma_f32_16x16x32_bf16 v[6:9], v[170:173], v[212:215], v[6:9]
	v_mfma_f32_16x16x32_bf16 v[2:5], v[178:181], v[212:215], v[2:5]
	v_mfma_f32_16x16x32_bf16 v[54:57], v[174:177], v[190:193], v[54:57]
	v_mfma_f32_16x16x32_bf16 v[46:49], v[182:185], v[190:193], v[46:49]
	v_mfma_f32_16x16x32_bf16 v[38:41], v[174:177], v[198:201], v[38:41]
	v_mfma_f32_16x16x32_bf16 v[30:33], v[182:185], v[198:201], v[30:33]
	v_mfma_f32_16x16x32_bf16 v[22:25], v[174:177], v[206:209], v[22:25]
	v_mfma_f32_16x16x32_bf16 v[14:17], v[182:185], v[206:209], v[14:17]
	v_mfma_f32_16x16x32_bf16 v[6:9], v[174:177], v[216:219], v[6:9]
	v_mfma_f32_16x16x32_bf16 v[2:5], v[182:185], v[216:219], v[2:5]
	s_setprio 0
	s_barrier
	s_add_i32 s73, 0, 0x18000
	v_add_u32_e32 v153, s73, v148
	s_add_i32 s74, 0, 0x1c000
	ds_read_b128 v[154:157], v153
	ds_read_b128 v[158:161], v153 offset:1024
	ds_read_b128 v[162:165], v153 offset:2048
	ds_read_b128 v[166:169], v153 offset:3072
	v_add_u32_e32 v153, s74, v148
	ds_read_b128 v[170:173], v153
	ds_read_b128 v[174:177], v153 offset:1024
	ds_read_b128 v[178:181], v153 offset:2048
	ds_read_b128 v[182:185], v153 offset:3072
	s_add_u32 s0, s36, 0x40000
	s_addc_u32 s1, s37, 0
	s_mov_b32 m0, s45
	v_lshl_add_u64 v[226:227], s[0:1], 0, v[130:131]
	ds_read_b128 v[186:189], v152 offset:32768
	ds_read_b128 v[190:193], v152 offset:33792
	ds_read_b128 v[194:197], v152 offset:34816
	ds_read_b128 v[198:201], v152 offset:35840
	ds_read_b128 v[202:205], v152 offset:36864
	ds_read_b128 v[206:209], v152 offset:37888
	ds_read_b128 v[212:215], v152 offset:38912
	ds_read_b128 v[216:219], v152 offset:39936
	global_load_lds_dwordx4 v[226:227], off
	v_lshl_add_u64 v[226:227], s[0:1], 0, v[134:135]
	s_mov_b32 m0, s46
	s_nop 0
	global_load_lds_dwordx4 v[226:227], off
	s_waitcnt vmcnt(8)
	s_waitcnt lgkmcnt(0)
	s_barrier
	s_setprio 1
	s_waitcnt lgkmcnt(0)
	v_mfma_f32_16x16x32_bf16 v[126:129], v[154:157], v[186:189], v[126:129]
	v_mfma_f32_16x16x32_bf16 v[122:125], v[162:165], v[186:189], v[122:125]
	v_mfma_f32_16x16x32_bf16 v[110:113], v[154:157], v[194:197], v[110:113]
	v_mfma_f32_16x16x32_bf16 v[106:109], v[162:165], v[194:197], v[106:109]
	v_mfma_f32_16x16x32_bf16 v[94:97], v[154:157], v[202:205], v[94:97]
	v_mfma_f32_16x16x32_bf16 v[90:93], v[162:165], v[202:205], v[90:93]
	v_mfma_f32_16x16x32_bf16 v[78:81], v[154:157], v[212:215], v[78:81]
	v_mfma_f32_16x16x32_bf16 v[74:77], v[162:165], v[212:215], v[74:77]
	v_mfma_f32_16x16x32_bf16 v[126:129], v[158:161], v[190:193], v[126:129]
	v_mfma_f32_16x16x32_bf16 v[122:125], v[166:169], v[190:193], v[122:125]
	v_mfma_f32_16x16x32_bf16 v[110:113], v[158:161], v[198:201], v[110:113]
	v_mfma_f32_16x16x32_bf16 v[106:109], v[166:169], v[198:201], v[106:109]
	v_mfma_f32_16x16x32_bf16 v[94:97], v[158:161], v[206:209], v[94:97]
	v_mfma_f32_16x16x32_bf16 v[90:93], v[166:169], v[206:209], v[90:93]
	v_mfma_f32_16x16x32_bf16 v[78:81], v[158:161], v[216:219], v[78:81]
	v_mfma_f32_16x16x32_bf16 v[74:77], v[166:169], v[216:219], v[74:77]
	v_mfma_f32_16x16x32_bf16 v[118:121], v[170:173], v[186:189], v[118:121]
	v_mfma_f32_16x16x32_bf16 v[114:117], v[178:181], v[186:189], v[114:117]
	v_mfma_f32_16x16x32_bf16 v[102:105], v[170:173], v[194:197], v[102:105]
	v_mfma_f32_16x16x32_bf16 v[98:101], v[178:181], v[194:197], v[98:101]
	v_mfma_f32_16x16x32_bf16 v[86:89], v[170:173], v[202:205], v[86:89]
	v_mfma_f32_16x16x32_bf16 v[82:85], v[178:181], v[202:205], v[82:85]
	v_mfma_f32_16x16x32_bf16 v[70:73], v[170:173], v[212:215], v[70:73]
	v_mfma_f32_16x16x32_bf16 v[66:69], v[178:181], v[212:215], v[66:69]
	v_mfma_f32_16x16x32_bf16 v[118:121], v[174:177], v[190:193], v[118:121]
	v_mfma_f32_16x16x32_bf16 v[114:117], v[182:185], v[190:193], v[114:117]
	v_mfma_f32_16x16x32_bf16 v[102:105], v[174:177], v[198:201], v[102:105]
	v_mfma_f32_16x16x32_bf16 v[98:101], v[182:185], v[198:201], v[98:101]
	v_mfma_f32_16x16x32_bf16 v[86:89], v[174:177], v[206:209], v[86:89]
	v_mfma_f32_16x16x32_bf16 v[82:85], v[182:185], v[206:209], v[82:85]
	v_mfma_f32_16x16x32_bf16 v[70:73], v[174:177], v[216:219], v[70:73]
	v_mfma_f32_16x16x32_bf16 v[66:69], v[182:185], v[216:219], v[66:69]
	s_setprio 0
	s_barrier
; #define PG8_STAGE(bufoff, gbase, voff) do { _Pragma("unroll") for (int _i = 0; _i < 2; ++_i) \
;         __builtin_amdgcn_global_load_lds((const unsigned*)((const char*)(gbase) + (voff)[_i]), (PG8_LAS unsigned*)(lds + (bufoff) + ldsw + _i * 8192), 16, 0, 0); } while (0)
; #define PG8_LDA(dst, b, h) do { _Pragma("unroll") for (int m = 0; m < 4; ++m) _Pragma("unroll") for (int k = 0; k < 2; ++k) dst[m][k] = *(const PG8_LAS bf16x8*)(lds + PG8_SA(b, h) + aoff + m * 2048 + k * 1024); } while (0)
; #define PG8_MMA(ai, bj, At, Bt) do { __builtin_amdgcn_s_setprio(1); _Pragma("unroll") for (int m = 0; m < 4; ++m) _Pragma("unroll") for (int n = 0; n < 2; ++n) _Pragma("unroll") for (int k = 0; k < 2; ++k) \
;         acc[ai][bj][m][n] = __builtin_amdgcn_mfma_f32_16x16x32_bf16(Bt[n][k], At[m][k], acc[ai][bj][m][n], 0, 0, 0); __builtin_amdgcn_s_setprio(0); } while (0)
; #define PG8_WAIT_V(n) asm volatile("s_waitcnt vmcnt(" #n ")" ::: "memory")
; #define PG8_WAIT_L(n) asm volatile("s_waitcnt lgkmcnt(" #n ")" ::: "memory")
; #define PG8_BAR __builtin_amdgcn_s_barrier()
; #define PG8_SCHED __builtin_amdgcn_sched_barrier(0)
; template <class Epi, class Sched, bool ALIGN_EPI = false, bool SP2 = false>
; __device__ __forceinline__ void gemm_phase(PG8_LAS unsigned char* lds, const Gemm g, const Sched& S, const Epi& E) {
;     ...
;         for (int t = 0; t < nt; t += 2) {
;             const bool last = (t == nt - 2);
;             const char* a1 = cA + (size_t)(t + 1) * kstep;
;             const char* a2 = last ? nA : cA + (size_t)(t + 2) * kstep; const char* b2 = last ? nB : cB + (size_t)(t + 2) * kstep;
;             const char* a3 = a2 + kstep; const char* b3 = b2 + kstep;
;             if (last && has_next) S.a_ready(nxt);
;     ...
;             PG8_LDA(At, 1, 1); PG8_STAGE(PG8_SB(1, 0), b3, voffB); PG8_STAGE(PG8_SB(1, 1), b3 + hstep, voffB); PG8_STAGE(PG8_SA(1, 0), a3, voffA);
;             PG8_WAIT_V(8); PG8_WAIT_L(0); PG8_BAR; PG8_MMA(1, 0, At, B0); PG8_MMA(1, 1, At, B1); PG8_BAR; PG8_SCHED;
;     ...
;         if constexpr (ALIGN_EPI) { if (wr == 0) PG8_BAR; }
;         if constexpr (!Epi::AFTER_DRAIN) { E(acc, cur, wr, wc, fr, fq); S.done(cur); }
;         if (!has_next) break;
	s_add_i32 s0, s73, s41
	v_lshl_add_u64 v[146:147], v[146:147], 0, s[8:9]
	s_mov_b32 m0, s0
	ds_read_b128 v[186:189], v152 offset:49152
	ds_read_b128 v[190:193], v152 offset:50176
	ds_read_b128 v[194:197], v152 offset:51200
	ds_read_b128 v[198:201], v152 offset:52224
	ds_read_b128 v[202:205], v152 offset:53248
	ds_read_b128 v[206:209], v152 offset:54272
	ds_read_b128 v[212:215], v152 offset:55296
	ds_read_b128 v[216:219], v152 offset:56320
	global_load_lds_dwordx4 v[146:147], off
	s_add_i32 m0, s0, 0x2000
	s_add_u32 s0, s34, 0x40080
	v_lshl_add_u64 v[146:147], v[220:221], 0, s[8:9]
	s_addc_u32 s1, s35, 0
	s_add_i32 s34, s74, s41
	global_load_lds_dwordx4 v[146:147], off
	v_lshl_add_u64 v[146:147], s[0:1], 0, v[132:133]
	s_mov_b32 m0, s34
	s_nop 0
	global_load_lds_dwordx4 v[146:147], off
	v_lshl_add_u64 v[146:147], s[0:1], 0, v[136:137]
	s_add_i32 m0, s34, 0x2000
	s_nop 0
	global_load_lds_dwordx4 v[146:147], off
	v_lshl_add_u64 v[146:147], v[222:223], 0, s[8:9]
	s_mov_b32 m0, s48
	s_nop 0
	global_load_lds_dwordx4 v[146:147], off
	v_lshl_add_u64 v[146:147], v[224:225], 0, s[8:9]
	s_mov_b32 m0, s49
	s_nop 0
	global_load_lds_dwordx4 v[146:147], off
	s_waitcnt vmcnt(8)
	s_waitcnt lgkmcnt(0)
	s_barrier
	s_setprio 1
	s_waitcnt lgkmcnt(0)
	v_mfma_f32_16x16x32_bf16 v[62:65], v[154:157], v[186:189], v[62:65]
	v_mfma_f32_16x16x32_bf16 v[58:61], v[162:165], v[186:189], v[58:61]
	v_mfma_f32_16x16x32_bf16 v[50:53], v[154:157], v[194:197], v[50:53]
	v_mfma_f32_16x16x32_bf16 v[42:45], v[162:165], v[194:197], v[42:45]
	v_mfma_f32_16x16x32_bf16 v[34:37], v[154:157], v[202:205], v[34:37]
	v_mfma_f32_16x16x32_bf16 v[26:29], v[162:165], v[202:205], v[26:29]
	v_mfma_f32_16x16x32_bf16 v[18:21], v[154:157], v[212:215], v[18:21]
	v_mfma_f32_16x16x32_bf16 v[10:13], v[162:165], v[212:215], v[10:13]
	v_mfma_f32_16x16x32_bf16 v[62:65], v[158:161], v[190:193], v[62:65]
	v_mfma_f32_16x16x32_bf16 v[58:61], v[166:169], v[190:193], v[58:61]
	v_mfma_f32_16x16x32_bf16 v[50:53], v[158:161], v[198:201], v[50:53]
	v_mfma_f32_16x16x32_bf16 v[42:45], v[166:169], v[198:201], v[42:45]
	v_mfma_f32_16x16x32_bf16 v[34:37], v[158:161], v[206:209], v[34:37]
	v_mfma_f32_16x16x32_bf16 v[26:29], v[166:169], v[206:209], v[26:29]
	v_mfma_f32_16x16x32_bf16 v[18:21], v[158:161], v[216:219], v[18:21]
	v_mfma_f32_16x16x32_bf16 v[10:13], v[166:169], v[216:219], v[10:13]
	v_mfma_f32_16x16x32_bf16 v[54:57], v[170:173], v[186:189], v[54:57]
	v_mfma_f32_16x16x32_bf16 v[46:49], v[178:181], v[186:189], v[46:49]
	v_mfma_f32_16x16x32_bf16 v[38:41], v[170:173], v[194:197], v[38:41]
	v_mfma_f32_16x16x32_bf16 v[30:33], v[178:181], v[194:197], v[30:33]
	v_mfma_f32_16x16x32_bf16 v[22:25], v[170:173], v[202:205], v[22:25]
	v_mfma_f32_16x16x32_bf16 v[14:17], v[178:181], v[202:205], v[14:17]
	v_mfma_f32_16x16x32_bf16 v[6:9], v[170:173], v[212:215], v[6:9]
	v_mfma_f32_16x16x32_bf16 v[2:5], v[178:181], v[212:215], v[2:5]
	v_mfma_f32_16x16x32_bf16 v[54:57], v[174:177], v[190:193], v[54:57]
	v_mfma_f32_16x16x32_bf16 v[46:49], v[182:185], v[190:193], v[46:49]
	v_mfma_f32_16x16x32_bf16 v[38:41], v[174:177], v[198:201], v[38:41]
	v_mfma_f32_16x16x32_bf16 v[30:33], v[182:185], v[198:201], v[30:33]
	v_mfma_f32_16x16x32_bf16 v[22:25], v[174:177], v[206:209], v[22:25]
	v_mfma_f32_16x16x32_bf16 v[14:17], v[182:185], v[206:209], v[14:17]
	v_mfma_f32_16x16x32_bf16 v[6:9], v[174:177], v[216:219], v[6:9]
	v_mfma_f32_16x16x32_bf16 v[2:5], v[182:185], v[216:219], v[2:5]
	s_setprio 0
	s_barrier
	s_add_i32 s72, s72, 2
	s_add_u32 s30, s30, 0x100
	s_addc_u32 s31, s31, 0
	s_add_u32 s60, s60, 0x100
	s_addc_u32 s61, s61, 0
	s_cmp_gt_u32 s72, 13
	s_cbranch_scc0 .LBB0_1472
	s_and_b64 vcc, exec, s[10:11]
	s_cbranch_vccz .LBB0_1475
	s_barrier

; #define PG8_STAGE(bufoff, gbase, voff) do { _Pragma("unroll") for (int _i = 0; _i < 2; ++_i) \
;         __builtin_amdgcn_global_load_lds((const unsigned*)((const char*)(gbase) + (voff)[_i]), (PG8_LAS unsigned*)(lds + (bufoff) + ldsw + _i * 8192), 16, 0, 0); } while (0)
; #define PG8_LDA(dst, b, h) do { _Pragma("unroll") for (int m = 0; m < 4; ++m) _Pragma("unroll") for (int k = 0; k < 2; ++k) dst[m][k] = *(const PG8_LAS bf16x8*)(lds + PG8_SA(b, h) + aoff + m * 2048 + k * 1024); } while (0)
; #define PG8_LDB(dst, b, h) do { _Pragma("unroll") for (int n = 0; n < 2; ++n) _Pragma("unroll") for (int k = 0; k < 2; ++k) dst[n][k] = *(const PG8_LAS bf16x8*)(lds + PG8_SB(b, h) + boff + n * 2048 + k * 1024); } while (0)
; #define PG8_MMA(ai, bj, At, Bt) do { __builtin_amdgcn_s_setprio(1); _Pragma("unroll") for (int m = 0; m < 4; ++m) _Pragma("unroll") for (int n = 0; n < 2; ++n) _Pragma("unroll") for (int k = 0; k < 2; ++k) \
;         acc[ai][bj][m][n] = __builtin_amdgcn_mfma_f32_16x16x32_bf16(Bt[n][k], At[m][k], acc[ai][bj][m][n], 0, 0, 0); __builtin_amdgcn_s_setprio(0); } while (0)
; #define PG8_WAIT_V(n) asm volatile("s_waitcnt vmcnt(" #n ")" ::: "memory")
; #define PG8_WAIT_L(n) asm volatile("s_waitcnt lgkmcnt(" #n ")" ::: "memory")
; #define PG8_BAR __builtin_amdgcn_s_barrier()
; #define PG8_SCHED __builtin_amdgcn_sched_barrier(0)
; template <class Epi, class Sched, bool ALIGN_EPI = false, bool SP2 = false>
; __device__ __forceinline__ void gemm_phase(PG8_LAS unsigned char* lds, const Gemm g, const Sched& S, const Epi& E) {
;     ...
;             PG8_LDB(B0, 0, 0); PG8_LDB(B1, 0, 1); PG8_SCHED; PG8_LDA(At, 0, 0); PG8_STAGE(PG8_SA(1, 1), a1 + hstep, voffA);
;             PG8_WAIT_V(8); PG8_WAIT_L(0); PG8_BAR; PG8_MMA(0, 0, At, B0); PG8_MMA(0, 1, At, B1); PG8_BAR; PG8_SCHED;
;             PG8_LDA(At, 0, 1); PG8_STAGE(PG8_SB(0, 0), b2, voffB); PG8_STAGE(PG8_SB(0, 1), b2 + hstep, voffB); PG8_STAGE(PG8_SA(0, 0), a2, voffA);
;             PG8_WAIT_V(8); PG8_WAIT_L(0); PG8_BAR; PG8_MMA(1, 0, At, B0); PG8_MMA(1, 1, At, B1); PG8_BAR; PG8_SCHED;
.LBB0_1508:
	ds_read_b128 v[146:149], v154
	ds_read_b128 v[160:163], v154 offset:1024
	ds_read_b128 v[164:167], v154 offset:2048
	ds_read_b128 v[168:171], v154 offset:3072
	ds_read_b128 v[172:175], v155
	ds_read_b128 v[176:179], v155 offset:1024
	ds_read_b128 v[180:183], v155 offset:2048
	ds_read_b128 v[184:187], v155 offset:3072
	s_add_u32 s0, s34, 0xfff00080
	s_addc_u32 s1, s35, -1
	s_cmp_eq_u32 s58, 60
	s_cselect_b32 s39, s23, s1
	s_cselect_b32 s38, s29, s0
	s_cselect_b32 s37, s21, s57
	s_cselect_b32 s36, s55, s56
	v_lshl_add_u64 v[150:151], s[34:35], 0, v[138:139]
	s_add_i32 m0, s31, 0xc000
	ds_read_b128 v[188:191], v156
	ds_read_b128 v[192:195], v156 offset:1024
	ds_read_b128 v[196:199], v156 offset:2048
	ds_read_b128 v[200:203], v156 offset:3072
	ds_read_b128 v[204:207], v156 offset:4096
	ds_read_b128 v[212:215], v156 offset:5120
	ds_read_b128 v[216:219], v156 offset:6144
	ds_read_b128 v[220:223], v156 offset:7168
	global_load_lds_dwordx4 v[150:151], off
	v_lshl_add_u64 v[150:151], s[34:35], 0, v[140:141]
	s_add_i32 m0, s31, 0xe000
	s_nop 0
	global_load_lds_dwordx4 v[150:151], off
	s_waitcnt vmcnt(8)
	s_waitcnt lgkmcnt(0)
	s_barrier
	s_setprio 1
	s_waitcnt lgkmcnt(0)
	v_mfma_f32_16x16x32_bf16 v[126:129], v[146:149], v[188:191], v[126:129]
	v_mfma_f32_16x16x32_bf16 v[122:125], v[164:167], v[188:191], v[122:125]
	v_mfma_f32_16x16x32_bf16 v[110:113], v[146:149], v[196:199], v[110:113]
	v_mfma_f32_16x16x32_bf16 v[106:109], v[164:167], v[196:199], v[106:109]
	v_mfma_f32_16x16x32_bf16 v[94:97], v[146:149], v[204:207], v[94:97]
	v_mfma_f32_16x16x32_bf16 v[90:93], v[164:167], v[204:207], v[90:93]
	v_mfma_f32_16x16x32_bf16 v[78:81], v[146:149], v[216:219], v[78:81]
	v_mfma_f32_16x16x32_bf16 v[74:77], v[164:167], v[216:219], v[74:77]
	v_mfma_f32_16x16x32_bf16 v[126:129], v[160:163], v[192:195], v[126:129]
	v_mfma_f32_16x16x32_bf16 v[122:125], v[168:171], v[192:195], v[122:125]
	v_mfma_f32_16x16x32_bf16 v[110:113], v[160:163], v[200:203], v[110:113]
	v_mfma_f32_16x16x32_bf16 v[106:109], v[168:171], v[200:203], v[106:109]
	v_mfma_f32_16x16x32_bf16 v[94:97], v[160:163], v[212:215], v[94:97]
	v_mfma_f32_16x16x32_bf16 v[90:93], v[168:171], v[212:215], v[90:93]
	v_mfma_f32_16x16x32_bf16 v[78:81], v[160:163], v[220:223], v[78:81]
	v_mfma_f32_16x16x32_bf16 v[74:77], v[168:171], v[220:223], v[74:77]
	v_mfma_f32_16x16x32_bf16 v[118:121], v[172:175], v[188:191], v[118:121]
	v_mfma_f32_16x16x32_bf16 v[114:117], v[180:183], v[188:191], v[114:117]
	v_mfma_f32_16x16x32_bf16 v[102:105], v[172:175], v[196:199], v[102:105]
	v_mfma_f32_16x16x32_bf16 v[98:101], v[180:183], v[196:199], v[98:101]
	v_mfma_f32_16x16x32_bf16 v[86:89], v[172:175], v[204:207], v[86:89]
	v_mfma_f32_16x16x32_bf16 v[82:85], v[180:183], v[204:207], v[82:85]
	v_mfma_f32_16x16x32_bf16 v[70:73], v[172:175], v[216:219], v[70:73]
	v_mfma_f32_16x16x32_bf16 v[66:69], v[180:183], v[216:219], v[66:69]
	v_mfma_f32_16x16x32_bf16 v[118:121], v[176:179], v[192:195], v[118:121]
	v_mfma_f32_16x16x32_bf16 v[114:117], v[184:187], v[192:195], v[114:117]
	v_mfma_f32_16x16x32_bf16 v[102:105], v[176:179], v[200:203], v[102:105]
	v_mfma_f32_16x16x32_bf16 v[98:101], v[184:187], v[200:203], v[98:101]
	v_mfma_f32_16x16x32_bf16 v[86:89], v[176:179], v[212:215], v[86:89]
	v_mfma_f32_16x16x32_bf16 v[82:85], v[184:187], v[212:215], v[82:85]
	v_mfma_f32_16x16x32_bf16 v[70:73], v[176:179], v[220:223], v[70:73]
	v_mfma_f32_16x16x32_bf16 v[66:69], v[184:187], v[220:223], v[66:69]
	s_setprio 0
	s_barrier
	s_add_i32 s0, s53, s44
	v_lshl_add_u64 v[150:151], s[36:37], 0, v[132:133]
	s_mov_b32 m0, s0
	ds_read_b128 v[188:191], v156 offset:16384
	ds_read_b128 v[192:195], v156 offset:17408
	ds_read_b128 v[196:199], v156 offset:18432
	ds_read_b128 v[200:203], v156 offset:19456
	ds_read_b128 v[204:207], v156 offset:20480
	ds_read_b128 v[212:215], v156 offset:21504
	ds_read_b128 v[216:219], v156 offset:22528
	ds_read_b128 v[220:223], v156 offset:23552
	global_load_lds_dwordx4 v[150:151], off
	s_add_i32 m0, s0, 0x2000
	s_add_u32 s0, s36, 0x100000
	v_lshl_add_u64 v[208:209], s[36:37], 0, v[136:137]
	s_addc_u32 s1, s37, 0
	s_add_i32 s59, s54, s44
	global_load_lds_dwordx4 v[208:209], off
	v_lshl_add_u64 v[224:225], s[0:1], 0, v[132:133]
	s_mov_b32 m0, s59
	v_lshl_add_u64 v[226:227], s[38:39], 0, v[134:135]
	global_load_lds_dwordx4 v[224:225], off
	v_lshl_add_u64 v[224:225], s[0:1], 0, v[136:137]
	s_add_i32 m0, s59, 0x2000
	s_nop 0
	global_load_lds_dwordx4 v[224:225], off
	v_lshl_add_u64 v[224:225], s[38:39], 0, v[130:131]
	s_mov_b32 m0, s31
	s_nop 0
	global_load_lds_dwordx4 v[224:225], off
	s_mov_b32 m0, s45
	s_nop 0
	global_load_lds_dwordx4 v[226:227], off
	s_waitcnt vmcnt(8)
	s_waitcnt lgkmcnt(0)
	s_barrier
; #define PG8_STAGE(bufoff, gbase, voff) do { _Pragma("unroll") for (int _i = 0; _i < 2; ++_i) \
;         __builtin_amdgcn_global_load_lds((const unsigned*)((const char*)(gbase) + (voff)[_i]), (PG8_LAS unsigned*)(lds + (bufoff) + ldsw + _i * 8192), 16, 0, 0); } while (0)
; #define PG8_LDA(dst, b, h) do { _Pragma("unroll") for (int m = 0; m < 4; ++m) _Pragma("unroll") for (int k = 0; k < 2; ++k) dst[m][k] = *(const PG8_LAS bf16x8*)(lds + PG8_SA(b, h) + aoff + m * 2048 + k * 1024); } while (0)
; #define PG8_LDB(dst, b, h) do { _Pragma("unroll") for (int n = 0; n < 2; ++n) _Pragma("unroll") for (int k = 0; k < 2; ++k) dst[n][k] = *(const PG8_LAS bf16x8*)(lds + PG8_SB(b, h) + boff + n * 2048 + k * 1024); } while (0)
; #define PG8_MMA(ai, bj, At, Bt) do { __builtin_amdgcn_s_setprio(1); _Pragma("unroll") for (int m = 0; m < 4; ++m) _Pragma("unroll") for (int n = 0; n < 2; ++n) _Pragma("unroll") for (int k = 0; k < 2; ++k) \
;         acc[ai][bj][m][n] = __builtin_amdgcn_mfma_f32_16x16x32_bf16(Bt[n][k], At[m][k], acc[ai][bj][m][n], 0, 0, 0); __builtin_amdgcn_s_setprio(0); } while (0)
; #define PG8_WAIT_V(n) asm volatile("s_waitcnt vmcnt(" #n ")" ::: "memory")
; #define PG8_WAIT_L(n) asm volatile("s_waitcnt lgkmcnt(" #n ")" ::: "memory")
; #define PG8_BAR __builtin_amdgcn_s_barrier()
; #define PG8_SCHED __builtin_amdgcn_sched_barrier(0)
; template <class Epi, class Sched, bool ALIGN_EPI = false, bool SP2 = false>
; __device__ __forceinline__ void gemm_phase(PG8_LAS unsigned char* lds, const Gemm g, const Sched& S, const Epi& E) {
;     ...
;             PG8_WAIT_V(8); PG8_WAIT_L(0); PG8_BAR; PG8_MMA(1, 0, At, B0); PG8_MMA(1, 1, At, B1); PG8_BAR; PG8_SCHED;
;             PG8_LDB(B0, 1, 0); PG8_LDB(B1, 1, 1); PG8_SCHED; PG8_LDA(At, 1, 0); PG8_STAGE(PG8_SA(0, 1), a2 + hstep, voffA);
;             PG8_WAIT_V(8); PG8_WAIT_L(0); PG8_BAR; PG8_MMA(0, 0, At, B0); PG8_MMA(0, 1, At, B1); PG8_BAR; PG8_SCHED;
	s_setprio 1
	s_waitcnt lgkmcnt(0)
	v_mfma_f32_16x16x32_bf16 v[62:65], v[146:149], v[188:191], v[62:65]
	v_mfma_f32_16x16x32_bf16 v[58:61], v[164:167], v[188:191], v[58:61]
	v_mfma_f32_16x16x32_bf16 v[46:49], v[146:149], v[196:199], v[46:49]
	v_mfma_f32_16x16x32_bf16 v[42:45], v[164:167], v[196:199], v[42:45]
	v_mfma_f32_16x16x32_bf16 v[30:33], v[146:149], v[204:207], v[30:33]
	v_mfma_f32_16x16x32_bf16 v[26:29], v[164:167], v[204:207], v[26:29]
	v_mfma_f32_16x16x32_bf16 v[14:17], v[146:149], v[216:219], v[14:17]
	v_mfma_f32_16x16x32_bf16 v[10:13], v[164:167], v[216:219], v[10:13]
	v_mfma_f32_16x16x32_bf16 v[62:65], v[160:163], v[192:195], v[62:65]
	v_mfma_f32_16x16x32_bf16 v[58:61], v[168:171], v[192:195], v[58:61]
	v_mfma_f32_16x16x32_bf16 v[46:49], v[160:163], v[200:203], v[46:49]
	v_mfma_f32_16x16x32_bf16 v[42:45], v[168:171], v[200:203], v[42:45]
	v_mfma_f32_16x16x32_bf16 v[30:33], v[160:163], v[212:215], v[30:33]
	v_mfma_f32_16x16x32_bf16 v[26:29], v[168:171], v[212:215], v[26:29]
	v_mfma_f32_16x16x32_bf16 v[14:17], v[160:163], v[220:223], v[14:17]
	v_mfma_f32_16x16x32_bf16 v[10:13], v[168:171], v[220:223], v[10:13]
	v_mfma_f32_16x16x32_bf16 v[54:57], v[172:175], v[188:191], v[54:57]
	v_mfma_f32_16x16x32_bf16 v[50:53], v[180:183], v[188:191], v[50:53]
	v_mfma_f32_16x16x32_bf16 v[38:41], v[172:175], v[196:199], v[38:41]
	v_mfma_f32_16x16x32_bf16 v[34:37], v[180:183], v[196:199], v[34:37]
	v_mfma_f32_16x16x32_bf16 v[22:25], v[172:175], v[204:207], v[22:25]
	v_mfma_f32_16x16x32_bf16 v[18:21], v[180:183], v[204:207], v[18:21]
	v_mfma_f32_16x16x32_bf16 v[6:9], v[172:175], v[216:219], v[6:9]
	v_mfma_f32_16x16x32_bf16 v[2:5], v[180:183], v[216:219], v[2:5]
	v_mfma_f32_16x16x32_bf16 v[54:57], v[176:179], v[192:195], v[54:57]
	v_mfma_f32_16x16x32_bf16 v[50:53], v[184:187], v[192:195], v[50:53]
	v_mfma_f32_16x16x32_bf16 v[38:41], v[176:179], v[200:203], v[38:41]
	v_mfma_f32_16x16x32_bf16 v[34:37], v[184:187], v[200:203], v[34:37]
	v_mfma_f32_16x16x32_bf16 v[22:25], v[176:179], v[212:215], v[22:25]
	v_mfma_f32_16x16x32_bf16 v[18:21], v[184:187], v[212:215], v[18:21]
	v_mfma_f32_16x16x32_bf16 v[6:9], v[176:179], v[220:223], v[6:9]
	v_mfma_f32_16x16x32_bf16 v[2:5], v[184:187], v[220:223], v[2:5]
	s_setprio 0
	s_barrier
	s_add_i32 s59, 0, 0x18000
	v_add_u32_e32 v159, s59, v152
	s_add_i32 s60, 0, 0x1c000
	ds_read_b128 v[146:149], v159
	ds_read_b128 v[160:163], v159 offset:1024
	ds_read_b128 v[164:167], v159 offset:2048
	ds_read_b128 v[168:171], v159 offset:3072
	v_add_u32_e32 v159, s60, v152
	ds_read_b128 v[172:175], v159
	ds_read_b128 v[176:179], v159 offset:1024
	ds_read_b128 v[180:183], v159 offset:2048
	ds_read_b128 v[184:187], v159 offset:3072
	s_add_u32 s0, s38, 0x100000
	s_addc_u32 s1, s39, 0
	s_mov_b32 m0, s46
	v_lshl_add_u64 v[228:229], s[0:1], 0, v[130:131]
	ds_read_b128 v[188:191], v156 offset:32768
	ds_read_b128 v[192:195], v156 offset:33792
	ds_read_b128 v[196:199], v156 offset:34816
	ds_read_b128 v[200:203], v156 offset:35840
	ds_read_b128 v[204:207], v156 offset:36864
	ds_read_b128 v[212:215], v156 offset:37888
	ds_read_b128 v[216:219], v156 offset:38912
	ds_read_b128 v[220:223], v156 offset:39936
	global_load_lds_dwordx4 v[228:229], off
	v_lshl_add_u64 v[228:229], s[0:1], 0, v[134:135]
	s_mov_b32 m0, s47
	s_nop 0
	global_load_lds_dwordx4 v[228:229], off
	s_waitcnt vmcnt(8)
	s_waitcnt lgkmcnt(0)
	s_barrier
	s_setprio 1
	s_waitcnt lgkmcnt(0)
	v_mfma_f32_16x16x32_bf16 v[126:129], v[146:149], v[188:191], v[126:129]
	v_mfma_f32_16x16x32_bf16 v[122:125], v[164:167], v[188:191], v[122:125]
	v_mfma_f32_16x16x32_bf16 v[110:113], v[146:149], v[196:199], v[110:113]
	v_mfma_f32_16x16x32_bf16 v[106:109], v[164:167], v[196:199], v[106:109]
	v_mfma_f32_16x16x32_bf16 v[94:97], v[146:149], v[204:207], v[94:97]
	v_mfma_f32_16x16x32_bf16 v[90:93], v[164:167], v[204:207], v[90:93]
	v_mfma_f32_16x16x32_bf16 v[78:81], v[146:149], v[216:219], v[78:81]
	v_mfma_f32_16x16x32_bf16 v[74:77], v[164:167], v[216:219], v[74:77]
	v_mfma_f32_16x16x32_bf16 v[126:129], v[160:163], v[192:195], v[126:129]
	v_mfma_f32_16x16x32_bf16 v[122:125], v[168:171], v[192:195], v[122:125]
	v_mfma_f32_16x16x32_bf16 v[110:113], v[160:163], v[200:203], v[110:113]
	v_mfma_f32_16x16x32_bf16 v[106:109], v[168:171], v[200:203], v[106:109]
	v_mfma_f32_16x16x32_bf16 v[94:97], v[160:163], v[212:215], v[94:97]
	v_mfma_f32_16x16x32_bf16 v[90:93], v[168:171], v[212:215], v[90:93]
	v_mfma_f32_16x16x32_bf16 v[78:81], v[160:163], v[220:223], v[78:81]
	v_mfma_f32_16x16x32_bf16 v[74:77], v[168:171], v[220:223], v[74:77]
	v_mfma_f32_16x16x32_bf16 v[118:121], v[172:175], v[188:191], v[118:121]
	v_mfma_f32_16x16x32_bf16 v[114:117], v[180:183], v[188:191], v[114:117]
	v_mfma_f32_16x16x32_bf16 v[102:105], v[172:175], v[196:199], v[102:105]
	v_mfma_f32_16x16x32_bf16 v[98:101], v[180:183], v[196:199], v[98:101]
	v_mfma_f32_16x16x32_bf16 v[86:89], v[172:175], v[204:207], v[86:89]
	v_mfma_f32_16x16x32_bf16 v[82:85], v[180:183], v[204:207], v[82:85]
	v_mfma_f32_16x16x32_bf16 v[70:73], v[172:175], v[216:219], v[70:73]
	v_mfma_f32_16x16x32_bf16 v[66:69], v[180:183], v[216:219], v[66:69]
	v_mfma_f32_16x16x32_bf16 v[118:121], v[176:179], v[192:195], v[118:121]
	v_mfma_f32_16x16x32_bf16 v[114:117], v[184:187], v[192:195], v[114:117]
	v_mfma_f32_16x16x32_bf16 v[102:105], v[176:179], v[200:203], v[102:105]
	v_mfma_f32_16x16x32_bf16 v[98:101], v[184:187], v[200:203], v[98:101]
	v_mfma_f32_16x16x32_bf16 v[86:89], v[176:179], v[212:215], v[86:89]
	v_mfma_f32_16x16x32_bf16 v[82:85], v[184:187], v[212:215], v[82:85]
	v_mfma_f32_16x16x32_bf16 v[70:73], v[176:179], v[220:223], v[70:73]
	v_mfma_f32_16x16x32_bf16 v[66:69], v[184:187], v[220:223], v[66:69]
	s_setprio 0
	s_barrier
; #define PG8_STAGE(bufoff, gbase, voff) do { _Pragma("unroll") for (int _i = 0; _i < 2; ++_i) \
;         __builtin_amdgcn_global_load_lds((const unsigned*)((const char*)(gbase) + (voff)[_i]), (PG8_LAS unsigned*)(lds + (bufoff) + ldsw + _i * 8192), 16, 0, 0); } while (0)
; #define PG8_LDA(dst, b, h) do { _Pragma("unroll") for (int m = 0; m < 4; ++m) _Pragma("unroll") for (int k = 0; k < 2; ++k) dst[m][k] = *(const PG8_LAS bf16x8*)(lds + PG8_SA(b, h) + aoff + m * 2048 + k * 1024); } while (0)
; #define PG8_MMA(ai, bj, At, Bt) do { __builtin_amdgcn_s_setprio(1); _Pragma("unroll") for (int m = 0; m < 4; ++m) _Pragma("unroll") for (int n = 0; n < 2; ++n) _Pragma("unroll") for (int k = 0; k < 2; ++k) \
;         acc[ai][bj][m][n] = __builtin_amdgcn_mfma_f32_16x16x32_bf16(Bt[n][k], At[m][k], acc[ai][bj][m][n], 0, 0, 0); __builtin_amdgcn_s_setprio(0); } while (0)
; #define PG8_WAIT_V(n) asm volatile("s_waitcnt vmcnt(" #n ")" ::: "memory")
; #define PG8_WAIT_L(n) asm volatile("s_waitcnt lgkmcnt(" #n ")" ::: "memory")
; #define PG8_BAR __builtin_amdgcn_s_barrier()
; #define PG8_SCHED __builtin_amdgcn_sched_barrier(0)
; template <class Epi, class Sched, bool ALIGN_EPI = false, bool SP2 = false>
; __device__ __forceinline__ void gemm_phase(PG8_LAS unsigned char* lds, const Gemm g, const Sched& S, const Epi& E) {
;     ...
;         for (int t = 0; t < nt; t += 2) {
;             const bool last = (t == nt - 2);
;             const char* a1 = cA + (size_t)(t + 1) * kstep;
;             const char* a2 = last ? nA : cA + (size_t)(t + 2) * kstep; const char* b2 = last ? nB : cB + (size_t)(t + 2) * kstep;
;             const char* a3 = a2 + kstep; const char* b3 = b2 + kstep;
;             if (last && has_next) S.a_ready(nxt);
;     ...
;             PG8_LDA(At, 1, 1); PG8_STAGE(PG8_SB(1, 0), b3, voffB); PG8_STAGE(PG8_SB(1, 1), b3 + hstep, voffB); PG8_STAGE(PG8_SA(1, 0), a3, voffA);
;             PG8_WAIT_V(8); PG8_WAIT_L(0); PG8_BAR; PG8_MMA(1, 0, At, B0); PG8_MMA(1, 1, At, B1); PG8_BAR; PG8_SCHED;
;     ...
;         if constexpr (ALIGN_EPI) { if (wr == 0) PG8_BAR; }
;         if constexpr (!Epi::AFTER_DRAIN) { E(acc, cur, wr, wc, fr, fq); S.done(cur); }
;         if (!has_next) break;
	s_add_i32 s0, s59, s44
	v_lshl_add_u64 v[150:151], v[150:151], 0, s[16:17]
	s_mov_b32 m0, s0
	ds_read_b128 v[188:191], v156 offset:49152
	ds_read_b128 v[192:195], v156 offset:50176
	ds_read_b128 v[196:199], v156 offset:51200
	ds_read_b128 v[200:203], v156 offset:52224
	ds_read_b128 v[204:207], v156 offset:53248
	ds_read_b128 v[212:215], v156 offset:54272
	ds_read_b128 v[216:219], v156 offset:55296
	ds_read_b128 v[220:223], v156 offset:56320
	global_load_lds_dwordx4 v[150:151], off
	s_add_i32 m0, s0, 0x2000
	s_add_u32 s0, s36, 0x100080
	v_lshl_add_u64 v[150:151], v[208:209], 0, s[16:17]
	s_addc_u32 s1, s37, 0
	s_add_i32 s36, s60, s44
	global_load_lds_dwordx4 v[150:151], off
	v_lshl_add_u64 v[150:151], s[0:1], 0, v[132:133]
	s_mov_b32 m0, s36
	s_nop 0
	global_load_lds_dwordx4 v[150:151], off
	v_lshl_add_u64 v[150:151], s[0:1], 0, v[136:137]
	s_add_i32 m0, s36, 0x2000
	s_nop 0
	global_load_lds_dwordx4 v[150:151], off
	v_lshl_add_u64 v[150:151], v[224:225], 0, s[16:17]
	s_mov_b32 m0, s49
	s_nop 0
	global_load_lds_dwordx4 v[150:151], off
	v_lshl_add_u64 v[150:151], v[226:227], 0, s[16:17]
	s_mov_b32 m0, s50
	s_nop 0
	global_load_lds_dwordx4 v[150:151], off
	s_waitcnt vmcnt(8)
	s_waitcnt lgkmcnt(0)
	s_barrier
	s_setprio 1
	s_waitcnt lgkmcnt(0)
	v_mfma_f32_16x16x32_bf16 v[62:65], v[146:149], v[188:191], v[62:65]
	v_mfma_f32_16x16x32_bf16 v[58:61], v[164:167], v[188:191], v[58:61]
	v_mfma_f32_16x16x32_bf16 v[46:49], v[146:149], v[196:199], v[46:49]
	v_mfma_f32_16x16x32_bf16 v[42:45], v[164:167], v[196:199], v[42:45]
	v_mfma_f32_16x16x32_bf16 v[30:33], v[146:149], v[204:207], v[30:33]
	v_mfma_f32_16x16x32_bf16 v[26:29], v[164:167], v[204:207], v[26:29]
	v_mfma_f32_16x16x32_bf16 v[14:17], v[146:149], v[216:219], v[14:17]
	v_mfma_f32_16x16x32_bf16 v[10:13], v[164:167], v[216:219], v[10:13]
	v_mfma_f32_16x16x32_bf16 v[62:65], v[160:163], v[192:195], v[62:65]
	v_mfma_f32_16x16x32_bf16 v[58:61], v[168:171], v[192:195], v[58:61]
	v_mfma_f32_16x16x32_bf16 v[46:49], v[160:163], v[200:203], v[46:49]
	v_mfma_f32_16x16x32_bf16 v[42:45], v[168:171], v[200:203], v[42:45]
	v_mfma_f32_16x16x32_bf16 v[30:33], v[160:163], v[212:215], v[30:33]
	v_mfma_f32_16x16x32_bf16 v[26:29], v[168:171], v[212:215], v[26:29]
	v_mfma_f32_16x16x32_bf16 v[14:17], v[160:163], v[220:223], v[14:17]
	v_mfma_f32_16x16x32_bf16 v[10:13], v[168:171], v[220:223], v[10:13]
	v_mfma_f32_16x16x32_bf16 v[54:57], v[172:175], v[188:191], v[54:57]
	v_mfma_f32_16x16x32_bf16 v[50:53], v[180:183], v[188:191], v[50:53]
	v_mfma_f32_16x16x32_bf16 v[38:41], v[172:175], v[196:199], v[38:41]
	v_mfma_f32_16x16x32_bf16 v[34:37], v[180:183], v[196:199], v[34:37]
	v_mfma_f32_16x16x32_bf16 v[22:25], v[172:175], v[204:207], v[22:25]
	v_mfma_f32_16x16x32_bf16 v[18:21], v[180:183], v[204:207], v[18:21]
	v_mfma_f32_16x16x32_bf16 v[6:9], v[172:175], v[216:219], v[6:9]
	v_mfma_f32_16x16x32_bf16 v[2:5], v[180:183], v[216:219], v[2:5]
	v_mfma_f32_16x16x32_bf16 v[54:57], v[176:179], v[192:195], v[54:57]
	v_mfma_f32_16x16x32_bf16 v[50:53], v[184:187], v[192:195], v[50:53]
	v_mfma_f32_16x16x32_bf16 v[38:41], v[176:179], v[200:203], v[38:41]
	v_mfma_f32_16x16x32_bf16 v[34:37], v[184:187], v[200:203], v[34:37]
	v_mfma_f32_16x16x32_bf16 v[22:25], v[176:179], v[212:215], v[22:25]
	v_mfma_f32_16x16x32_bf16 v[18:21], v[184:187], v[212:215], v[18:21]
	v_mfma_f32_16x16x32_bf16 v[6:9], v[176:179], v[220:223], v[6:9]
	v_mfma_f32_16x16x32_bf16 v[2:5], v[184:187], v[220:223], v[2:5]
	s_setprio 0
	s_barrier
	s_add_i32 s58, s58, 2
	s_add_u32 s34, s34, 0x100
	s_addc_u32 s35, s35, 0
	s_add_u32 s56, s56, 0x100
	s_addc_u32 s57, s57, 0
	s_cmp_gt_u32 s58, 61
	s_cbranch_scc0 .LBB0_1508
	s_and_b64 vcc, exec, s[18:19]
	s_cbranch_vccz .LBB0_1511
	s_barrier

; #define PG8_STAGE(bufoff, gbase, voff) do { _Pragma("unroll") for (int _i = 0; _i < 2; ++_i) \
;         __builtin_amdgcn_global_load_lds((const unsigned*)((const char*)(gbase) + (voff)[_i]), (PG8_LAS unsigned*)(lds + (bufoff) + ldsw + _i * 8192), 16, 0, 0); } while (0)
; #define PG8_LDA(dst, b, h) do { _Pragma("unroll") for (int m = 0; m < 4; ++m) _Pragma("unroll") for (int k = 0; k < 2; ++k) dst[m][k] = *(const PG8_LAS bf16x8*)(lds + PG8_SA(b, h) + aoff + m * 2048 + k * 1024); } while (0)
; #define PG8_LDB(dst, b, h) do { _Pragma("unroll") for (int n = 0; n < 2; ++n) _Pragma("unroll") for (int k = 0; k < 2; ++k) dst[n][k] = *(const PG8_LAS bf16x8*)(lds + PG8_SB(b, h) + boff + n * 2048 + k * 1024); } while (0)
; #define PG8_MMA(ai, bj, At, Bt) do { __builtin_amdgcn_s_setprio(1); _Pragma("unroll") for (int m = 0; m < 4; ++m) _Pragma("unroll") for (int n = 0; n < 2; ++n) _Pragma("unroll") for (int k = 0; k < 2; ++k) \
;         acc[ai][bj][m][n] = __builtin_amdgcn_mfma_f32_16x16x32_bf16(Bt[n][k], At[m][k], acc[ai][bj][m][n], 0, 0, 0); __builtin_amdgcn_s_setprio(0); } while (0)
; #define PG8_WAIT_V(n) asm volatile("s_waitcnt vmcnt(" #n ")" ::: "memory")
; #define PG8_WAIT_L(n) asm volatile("s_waitcnt lgkmcnt(" #n ")" ::: "memory")
; #define PG8_BAR __builtin_amdgcn_s_barrier()
; #define PG8_SCHED __builtin_amdgcn_sched_barrier(0)
; template <class Epi, class Sched, bool ALIGN_EPI = false, bool SP2 = false>
; __device__ __forceinline__ void gemm_phase(PG8_LAS unsigned char* lds, const Gemm g, const Sched& S, const Epi& E) {
;     ...
;             PG8_LDB(B0, 0, 0); PG8_LDB(B1, 0, 1); PG8_SCHED; PG8_LDA(At, 0, 0); PG8_STAGE(PG8_SA(1, 1), a1 + hstep, voffA);
;             PG8_WAIT_V(8); PG8_WAIT_L(0); PG8_BAR; PG8_MMA(0, 0, At, B0); PG8_MMA(0, 1, At, B1); PG8_BAR; PG8_SCHED;
;             PG8_LDA(At, 0, 1); PG8_STAGE(PG8_SB(0, 0), b2, voffB); PG8_STAGE(PG8_SB(0, 1), b2 + hstep, voffB); PG8_STAGE(PG8_SA(0, 0), a2, voffA);
;             PG8_WAIT_V(8); PG8_WAIT_L(0); PG8_BAR; PG8_MMA(1, 0, At, B0); PG8_MMA(1, 1, At, B1); PG8_BAR; PG8_SCHED;
.LBB0_1552:
	ds_read_b128 v[10:13], v183
	ds_read_b128 v[14:17], v183 offset:1024
	ds_read_b128 v[138:141], v183 offset:2048
	ds_read_b128 v[142:145], v183 offset:3072
	ds_read_b128 v[146:149], v184
	ds_read_b128 v[172:175], v184 offset:1024
	ds_read_b128 v[178:181], v184 offset:2048
	ds_read_b128 v[190:193], v184 offset:3072
	s_add_u32 s0, s8, 0xfffc0080
	s_addc_u32 s1, s9, -1
	s_cmp_eq_u32 s60, 12
	s_cselect_b32 s47, s7, s1
	s_cselect_b32 s46, s11, s0
	s_cselect_b32 s45, s35, s49
	s_cselect_b32 s44, s37, s48
	v_lshl_add_u64 v[228:229], s[8:9], 0, v[164:165]
	s_add_i32 m0, s52, 0xc000
	ds_read_b128 v[194:197], v185
	ds_read_b128 v[198:201], v185 offset:1024
	ds_read_b128 v[202:205], v185 offset:2048
	ds_read_b128 v[206:209], v185 offset:3072
	ds_read_b128 v[212:215], v185 offset:4096
	ds_read_b128 v[216:219], v185 offset:5120
	ds_read_b128 v[220:223], v185 offset:6144
	ds_read_b128 v[224:227], v185 offset:7168
	global_load_lds_dwordx4 v[228:229], off
	v_lshl_add_u64 v[228:229], s[8:9], 0, v[166:167]
	s_add_i32 m0, s52, 0xe000
	s_nop 0
	global_load_lds_dwordx4 v[228:229], off
	s_waitcnt vmcnt(8)
	s_waitcnt lgkmcnt(0)
	s_barrier
	s_setprio 1
	s_waitcnt lgkmcnt(0)
	v_mfma_f32_16x16x32_bf16 v[2:5], v[10:13], v[194:197], v[2:5]
	v_mfma_f32_16x16x32_bf16 v[6:9], v[138:141], v[194:197], v[6:9]
	v_mfma_f32_16x16x32_bf16 v[134:137], v[10:13], v[202:205], v[134:137]
	v_mfma_f32_16x16x32_bf16 v[130:133], v[138:141], v[202:205], v[130:133]
	v_mfma_f32_16x16x32_bf16 v[126:129], v[10:13], v[212:215], v[126:129]
	v_mfma_f32_16x16x32_bf16 v[122:125], v[138:141], v[212:215], v[122:125]
	v_mfma_f32_16x16x32_bf16 v[118:121], v[10:13], v[220:223], v[118:121]
	v_mfma_f32_16x16x32_bf16 v[114:117], v[138:141], v[220:223], v[114:117]
	v_mfma_f32_16x16x32_bf16 v[2:5], v[14:17], v[198:201], v[2:5]
	v_mfma_f32_16x16x32_bf16 v[6:9], v[142:145], v[198:201], v[6:9]
	v_mfma_f32_16x16x32_bf16 v[134:137], v[14:17], v[206:209], v[134:137]
	v_mfma_f32_16x16x32_bf16 v[130:133], v[142:145], v[206:209], v[130:133]
	v_mfma_f32_16x16x32_bf16 v[126:129], v[14:17], v[216:219], v[126:129]
	v_mfma_f32_16x16x32_bf16 v[122:125], v[142:145], v[216:219], v[122:125]
	v_mfma_f32_16x16x32_bf16 v[118:121], v[14:17], v[224:227], v[118:121]
	v_mfma_f32_16x16x32_bf16 v[114:117], v[142:145], v[224:227], v[114:117]
	v_mfma_f32_16x16x32_bf16 v[78:81], v[146:149], v[194:197], v[78:81]
	v_mfma_f32_16x16x32_bf16 v[74:77], v[178:181], v[194:197], v[74:77]
	v_mfma_f32_16x16x32_bf16 v[70:73], v[146:149], v[202:205], v[70:73]
	v_mfma_f32_16x16x32_bf16 v[66:69], v[178:181], v[202:205], v[66:69]
	v_mfma_f32_16x16x32_bf16 v[62:65], v[146:149], v[212:215], v[62:65]
	v_mfma_f32_16x16x32_bf16 v[58:61], v[178:181], v[212:215], v[58:61]
	v_mfma_f32_16x16x32_bf16 v[54:57], v[146:149], v[220:223], v[54:57]
	v_mfma_f32_16x16x32_bf16 v[50:53], v[178:181], v[220:223], v[50:53]
	v_mfma_f32_16x16x32_bf16 v[78:81], v[172:175], v[198:201], v[78:81]
	v_mfma_f32_16x16x32_bf16 v[74:77], v[190:193], v[198:201], v[74:77]
	v_mfma_f32_16x16x32_bf16 v[70:73], v[172:175], v[206:209], v[70:73]
	v_mfma_f32_16x16x32_bf16 v[66:69], v[190:193], v[206:209], v[66:69]
	v_mfma_f32_16x16x32_bf16 v[62:65], v[172:175], v[216:219], v[62:65]
	v_mfma_f32_16x16x32_bf16 v[58:61], v[190:193], v[216:219], v[58:61]
	v_mfma_f32_16x16x32_bf16 v[54:57], v[172:175], v[224:227], v[54:57]
	v_mfma_f32_16x16x32_bf16 v[50:53], v[190:193], v[224:227], v[50:53]
	s_setprio 0
	s_barrier
	s_add_i32 s0, s79, s51
	v_lshl_add_u64 v[228:229], s[44:45], 0, v[152:153]
	s_mov_b32 m0, s0
	ds_read_b128 v[194:197], v185 offset:16384
	ds_read_b128 v[198:201], v185 offset:17408
	ds_read_b128 v[202:205], v185 offset:18432
	ds_read_b128 v[206:209], v185 offset:19456
	ds_read_b128 v[212:215], v185 offset:20480
	ds_read_b128 v[216:219], v185 offset:21504
	ds_read_b128 v[220:223], v185 offset:22528
	ds_read_b128 v[224:227], v185 offset:23552
	global_load_lds_dwordx4 v[228:229], off
	s_add_i32 m0, s0, 0x2000
	s_add_u32 s0, s44, 0x40000
	v_lshl_add_u64 v[230:231], s[44:45], 0, v[156:157]
	s_addc_u32 s1, s45, 0
	s_add_i32 s61, s80, s51
	global_load_lds_dwordx4 v[230:231], off
	v_lshl_add_u64 v[232:233], s[0:1], 0, v[152:153]
	s_mov_b32 m0, s61
	v_lshl_add_u64 v[234:235], s[46:47], 0, v[154:155]
	global_load_lds_dwordx4 v[232:233], off
	v_lshl_add_u64 v[232:233], s[0:1], 0, v[156:157]
	s_add_i32 m0, s61, 0x2000
	s_nop 0
	global_load_lds_dwordx4 v[232:233], off
	v_lshl_add_u64 v[232:233], s[46:47], 0, v[150:151]
	s_mov_b32 m0, s52
	s_nop 0
	global_load_lds_dwordx4 v[232:233], off
	s_mov_b32 m0, s53
	s_nop 0
	global_load_lds_dwordx4 v[234:235], off
	s_waitcnt vmcnt(8)
	s_waitcnt lgkmcnt(0)
	s_barrier
; #define PG8_STAGE(bufoff, gbase, voff) do { _Pragma("unroll") for (int _i = 0; _i < 2; ++_i) \
;         __builtin_amdgcn_global_load_lds((const unsigned*)((const char*)(gbase) + (voff)[_i]), (PG8_LAS unsigned*)(lds + (bufoff) + ldsw + _i * 8192), 16, 0, 0); } while (0)
; #define PG8_LDA(dst, b, h) do { _Pragma("unroll") for (int m = 0; m < 4; ++m) _Pragma("unroll") for (int k = 0; k < 2; ++k) dst[m][k] = *(const PG8_LAS bf16x8*)(lds + PG8_SA(b, h) + aoff + m * 2048 + k * 1024); } while (0)
; #define PG8_LDB(dst, b, h) do { _Pragma("unroll") for (int n = 0; n < 2; ++n) _Pragma("unroll") for (int k = 0; k < 2; ++k) dst[n][k] = *(const PG8_LAS bf16x8*)(lds + PG8_SB(b, h) + boff + n * 2048 + k * 1024); } while (0)
; #define PG8_MMA(ai, bj, At, Bt) do { __builtin_amdgcn_s_setprio(1); _Pragma("unroll") for (int m = 0; m < 4; ++m) _Pragma("unroll") for (int n = 0; n < 2; ++n) _Pragma("unroll") for (int k = 0; k < 2; ++k) \
;         acc[ai][bj][m][n] = __builtin_amdgcn_mfma_f32_16x16x32_bf16(Bt[n][k], At[m][k], acc[ai][bj][m][n], 0, 0, 0); __builtin_amdgcn_s_setprio(0); } while (0)
; #define PG8_WAIT_V(n) asm volatile("s_waitcnt vmcnt(" #n ")" ::: "memory")
; #define PG8_WAIT_L(n) asm volatile("s_waitcnt lgkmcnt(" #n ")" ::: "memory")
; #define PG8_BAR __builtin_amdgcn_s_barrier()
; #define PG8_SCHED __builtin_amdgcn_sched_barrier(0)
; template <class Epi, class Sched, bool ALIGN_EPI = false, bool SP2 = false>
; __device__ __forceinline__ void gemm_phase(PG8_LAS unsigned char* lds, const Gemm g, const Sched& S, const Epi& E) {
;     ...
;             PG8_WAIT_V(8); PG8_WAIT_L(0); PG8_BAR; PG8_MMA(1, 0, At, B0); PG8_MMA(1, 1, At, B1); PG8_BAR; PG8_SCHED;
;             PG8_LDB(B0, 1, 0); PG8_LDB(B1, 1, 1); PG8_SCHED; PG8_LDA(At, 1, 0); PG8_STAGE(PG8_SA(0, 1), a2 + hstep, voffA);
;             PG8_WAIT_V(8); PG8_WAIT_L(0); PG8_BAR; PG8_MMA(0, 0, At, B0); PG8_MMA(0, 1, At, B1); PG8_BAR; PG8_SCHED;
	s_setprio 1
	s_waitcnt lgkmcnt(0)
	v_mfma_f32_16x16x32_bf16 v[110:113], v[10:13], v[194:197], v[110:113]
	v_mfma_f32_16x16x32_bf16 v[106:109], v[138:141], v[194:197], v[106:109]
	v_mfma_f32_16x16x32_bf16 v[102:105], v[10:13], v[202:205], v[102:105]
	v_mfma_f32_16x16x32_bf16 v[98:101], v[138:141], v[202:205], v[98:101]
	v_mfma_f32_16x16x32_bf16 v[94:97], v[10:13], v[212:215], v[94:97]
	v_mfma_f32_16x16x32_bf16 v[90:93], v[138:141], v[212:215], v[90:93]
	v_mfma_f32_16x16x32_bf16 v[10:13], v[10:13], v[220:223], v[86:89]
	v_mfma_f32_16x16x32_bf16 v[110:113], v[14:17], v[198:201], v[110:113]
	v_mfma_f32_16x16x32_bf16 v[106:109], v[142:145], v[198:201], v[106:109]
	v_mfma_f32_16x16x32_bf16 v[102:105], v[14:17], v[206:209], v[102:105]
	v_mfma_f32_16x16x32_bf16 v[98:101], v[142:145], v[206:209], v[98:101]
	v_mfma_f32_16x16x32_bf16 v[94:97], v[14:17], v[216:219], v[94:97]
	v_mfma_f32_16x16x32_bf16 v[90:93], v[142:145], v[216:219], v[90:93]
	v_mfma_f32_16x16x32_bf16 v[10:13], v[14:17], v[224:227], v[10:13]
	v_mfma_f32_16x16x32_bf16 v[14:17], v[138:141], v[220:223], v[82:85]
	v_mfma_f32_16x16x32_bf16 v[14:17], v[142:145], v[224:227], v[14:17]
	v_mfma_f32_16x16x32_bf16 v[46:49], v[146:149], v[194:197], v[46:49]
	v_mfma_f32_16x16x32_bf16 v[42:45], v[178:181], v[194:197], v[42:45]
	v_mfma_f32_16x16x32_bf16 v[38:41], v[146:149], v[202:205], v[38:41]
	v_mfma_f32_16x16x32_bf16 v[34:37], v[178:181], v[202:205], v[34:37]
	v_mfma_f32_16x16x32_bf16 v[30:33], v[146:149], v[212:215], v[30:33]
	v_mfma_f32_16x16x32_bf16 v[26:29], v[178:181], v[212:215], v[26:29]
	v_mfma_f32_16x16x32_bf16 v[22:25], v[146:149], v[220:223], v[22:25]
	v_mfma_f32_16x16x32_bf16 v[18:21], v[178:181], v[220:223], v[18:21]
	v_mfma_f32_16x16x32_bf16 v[46:49], v[172:175], v[198:201], v[46:49]
	v_mfma_f32_16x16x32_bf16 v[42:45], v[190:193], v[198:201], v[42:45]
	v_mfma_f32_16x16x32_bf16 v[38:41], v[172:175], v[206:209], v[38:41]
	v_mfma_f32_16x16x32_bf16 v[34:37], v[190:193], v[206:209], v[34:37]
	v_mfma_f32_16x16x32_bf16 v[30:33], v[172:175], v[216:219], v[30:33]
	v_mfma_f32_16x16x32_bf16 v[26:29], v[190:193], v[216:219], v[26:29]
	v_mfma_f32_16x16x32_bf16 v[22:25], v[172:175], v[224:227], v[22:25]
	v_mfma_f32_16x16x32_bf16 v[18:21], v[190:193], v[224:227], v[18:21]
	s_setprio 0
	s_barrier
	s_add_i32 s61, 0, 0x18000
	s_add_i32 s87, 0, 0x1c000
	v_add_u32_e32 v142, s61, v182
	v_add_u32_e32 v158, s87, v182
	ds_read_b128 v[82:85], v142
	ds_read_b128 v[86:89], v142 offset:1024
	ds_read_b128 v[138:141], v142 offset:2048
	ds_read_b128 v[142:145], v142 offset:3072
	ds_read_b128 v[146:149], v158
	ds_read_b128 v[172:175], v158 offset:1024
	ds_read_b128 v[178:181], v158 offset:2048
	ds_read_b128 v[190:193], v158 offset:3072
	s_add_u32 s0, s46, 0x40000
	s_addc_u32 s1, s47, 0
	s_mov_b32 m0, s54
	v_lshl_add_u64 v[236:237], s[0:1], 0, v[150:151]
	ds_read_b128 v[194:197], v185 offset:32768
	ds_read_b128 v[198:201], v185 offset:33792
	ds_read_b128 v[202:205], v185 offset:34816
	ds_read_b128 v[206:209], v185 offset:35840
	ds_read_b128 v[212:215], v185 offset:36864
	ds_read_b128 v[216:219], v185 offset:37888
	ds_read_b128 v[220:223], v185 offset:38912
	ds_read_b128 v[224:227], v185 offset:39936
	global_load_lds_dwordx4 v[236:237], off
	v_lshl_add_u64 v[236:237], s[0:1], 0, v[154:155]
	s_mov_b32 m0, s55
	s_nop 0
	global_load_lds_dwordx4 v[236:237], off
	s_waitcnt vmcnt(8)
	s_waitcnt lgkmcnt(0)
	s_barrier
	s_setprio 1
	s_waitcnt lgkmcnt(0)
	v_mfma_f32_16x16x32_bf16 v[2:5], v[82:85], v[194:197], v[2:5]
	v_mfma_f32_16x16x32_bf16 v[6:9], v[138:141], v[194:197], v[6:9]
	v_mfma_f32_16x16x32_bf16 v[134:137], v[82:85], v[202:205], v[134:137]
	v_mfma_f32_16x16x32_bf16 v[130:133], v[138:141], v[202:205], v[130:133]
	v_mfma_f32_16x16x32_bf16 v[126:129], v[82:85], v[212:215], v[126:129]
	v_mfma_f32_16x16x32_bf16 v[122:125], v[138:141], v[212:215], v[122:125]
	v_mfma_f32_16x16x32_bf16 v[118:121], v[82:85], v[220:223], v[118:121]
	v_mfma_f32_16x16x32_bf16 v[114:117], v[138:141], v[220:223], v[114:117]
	v_mfma_f32_16x16x32_bf16 v[2:5], v[86:89], v[198:201], v[2:5]
	v_mfma_f32_16x16x32_bf16 v[6:9], v[142:145], v[198:201], v[6:9]
	v_mfma_f32_16x16x32_bf16 v[134:137], v[86:89], v[206:209], v[134:137]
	v_mfma_f32_16x16x32_bf16 v[130:133], v[142:145], v[206:209], v[130:133]
	v_mfma_f32_16x16x32_bf16 v[126:129], v[86:89], v[216:219], v[126:129]
	v_mfma_f32_16x16x32_bf16 v[122:125], v[142:145], v[216:219], v[122:125]
	v_mfma_f32_16x16x32_bf16 v[118:121], v[86:89], v[224:227], v[118:121]
	v_mfma_f32_16x16x32_bf16 v[114:117], v[142:145], v[224:227], v[114:117]
	v_mfma_f32_16x16x32_bf16 v[78:81], v[146:149], v[194:197], v[78:81]
	v_mfma_f32_16x16x32_bf16 v[74:77], v[178:181], v[194:197], v[74:77]
	v_mfma_f32_16x16x32_bf16 v[70:73], v[146:149], v[202:205], v[70:73]
	v_mfma_f32_16x16x32_bf16 v[66:69], v[178:181], v[202:205], v[66:69]
	v_mfma_f32_16x16x32_bf16 v[62:65], v[146:149], v[212:215], v[62:65]
	v_mfma_f32_16x16x32_bf16 v[58:61], v[178:181], v[212:215], v[58:61]
	v_mfma_f32_16x16x32_bf16 v[54:57], v[146:149], v[220:223], v[54:57]
	v_mfma_f32_16x16x32_bf16 v[50:53], v[178:181], v[220:223], v[50:53]
	v_mfma_f32_16x16x32_bf16 v[78:81], v[172:175], v[198:201], v[78:81]
	v_mfma_f32_16x16x32_bf16 v[74:77], v[190:193], v[198:201], v[74:77]
	v_mfma_f32_16x16x32_bf16 v[70:73], v[172:175], v[206:209], v[70:73]
	v_mfma_f32_16x16x32_bf16 v[66:69], v[190:193], v[206:209], v[66:69]
	v_mfma_f32_16x16x32_bf16 v[62:65], v[172:175], v[216:219], v[62:65]
	v_mfma_f32_16x16x32_bf16 v[58:61], v[190:193], v[216:219], v[58:61]
	v_mfma_f32_16x16x32_bf16 v[54:57], v[172:175], v[224:227], v[54:57]
	v_mfma_f32_16x16x32_bf16 v[50:53], v[190:193], v[224:227], v[50:53]
	s_setprio 0
	s_barrier
; #define PG8_STAGE(bufoff, gbase, voff) do { _Pragma("unroll") for (int _i = 0; _i < 2; ++_i) \
;         __builtin_amdgcn_global_load_lds((const unsigned*)((const char*)(gbase) + (voff)[_i]), (PG8_LAS unsigned*)(lds + (bufoff) + ldsw + _i * 8192), 16, 0, 0); } while (0)
; #define PG8_LDA(dst, b, h) do { _Pragma("unroll") for (int m = 0; m < 4; ++m) _Pragma("unroll") for (int k = 0; k < 2; ++k) dst[m][k] = *(const PG8_LAS bf16x8*)(lds + PG8_SA(b, h) + aoff + m * 2048 + k * 1024); } while (0)
; #define PG8_MMA(ai, bj, At, Bt) do { __builtin_amdgcn_s_setprio(1); _Pragma("unroll") for (int m = 0; m < 4; ++m) _Pragma("unroll") for (int n = 0; n < 2; ++n) _Pragma("unroll") for (int k = 0; k < 2; ++k) \
;         acc[ai][bj][m][n] = __builtin_amdgcn_mfma_f32_16x16x32_bf16(Bt[n][k], At[m][k], acc[ai][bj][m][n], 0, 0, 0); __builtin_amdgcn_s_setprio(0); } while (0)
; #define PG8_WAIT_V(n) asm volatile("s_waitcnt vmcnt(" #n ")" ::: "memory")
; #define PG8_WAIT_L(n) asm volatile("s_waitcnt lgkmcnt(" #n ")" ::: "memory")
; #define PG8_BAR __builtin_amdgcn_s_barrier()
; #define PG8_SCHED __builtin_amdgcn_sched_barrier(0)
; template <class Epi, class Sched, bool ALIGN_EPI = false, bool SP2 = false>
; __device__ __forceinline__ void gemm_phase(PG8_LAS unsigned char* lds, const Gemm g, const Sched& S, const Epi& E) {
;     ...
;         for (int t = 0; t < nt; t += 2) {
;             const bool last = (t == nt - 2);
;             const char* a1 = cA + (size_t)(t + 1) * kstep;
;             const char* a2 = last ? nA : cA + (size_t)(t + 2) * kstep; const char* b2 = last ? nB : cB + (size_t)(t + 2) * kstep;
;             const char* a3 = a2 + kstep; const char* b3 = b2 + kstep;
;     ...
;             PG8_LDA(At, 1, 1); PG8_STAGE(PG8_SB(1, 0), b3, voffB); PG8_STAGE(PG8_SB(1, 1), b3 + hstep, voffB); PG8_STAGE(PG8_SA(1, 0), a3, voffA);
;             PG8_WAIT_V(8); PG8_WAIT_L(0); PG8_BAR; PG8_MMA(1, 0, At, B0); PG8_MMA(1, 1, At, B1); PG8_BAR; PG8_SCHED;
	s_add_i32 s0, s61, s51
	v_lshl_add_u64 v[228:229], v[228:229], 0, s[20:21]
	s_mov_b32 m0, s0
	ds_read_b128 v[194:197], v185 offset:49152
	ds_read_b128 v[198:201], v185 offset:50176
	ds_read_b128 v[202:205], v185 offset:51200
	ds_read_b128 v[206:209], v185 offset:52224
	ds_read_b128 v[212:215], v185 offset:53248
	ds_read_b128 v[216:219], v185 offset:54272
	ds_read_b128 v[220:223], v185 offset:55296
	ds_read_b128 v[224:227], v185 offset:56320
	global_load_lds_dwordx4 v[228:229], off
	s_add_i32 m0, s0, 0x2000
	s_add_u32 s0, s44, 0x40080
	v_lshl_add_u64 v[228:229], v[230:231], 0, s[20:21]
	s_addc_u32 s1, s45, 0
	s_add_i32 s44, s87, s51
	global_load_lds_dwordx4 v[228:229], off
	v_lshl_add_u64 v[228:229], s[0:1], 0, v[152:153]
	s_mov_b32 m0, s44
	s_nop 0
	global_load_lds_dwordx4 v[228:229], off
	v_lshl_add_u64 v[228:229], s[0:1], 0, v[156:157]
	s_add_i32 m0, s44, 0x2000
	s_nop 0
	global_load_lds_dwordx4 v[228:229], off
	v_lshl_add_u64 v[228:229], v[232:233], 0, s[20:21]
	s_mov_b32 m0, s72
	s_nop 0
	global_load_lds_dwordx4 v[228:229], off
	v_lshl_add_u64 v[228:229], v[234:235], 0, s[20:21]
	s_mov_b32 m0, s73
	s_nop 0
	global_load_lds_dwordx4 v[228:229], off
	s_waitcnt vmcnt(8)
	s_waitcnt lgkmcnt(0)
	s_barrier
	s_setprio 1
	s_waitcnt lgkmcnt(0)
	v_mfma_f32_16x16x32_bf16 v[110:113], v[82:85], v[194:197], v[110:113]
	v_mfma_f32_16x16x32_bf16 v[102:105], v[82:85], v[202:205], v[102:105]
	v_mfma_f32_16x16x32_bf16 v[94:97], v[82:85], v[212:215], v[94:97]
	v_mfma_f32_16x16x32_bf16 v[10:13], v[82:85], v[220:223], v[10:13]
	v_mfma_f32_16x16x32_bf16 v[110:113], v[86:89], v[198:201], v[110:113]
	v_mfma_f32_16x16x32_bf16 v[106:109], v[138:141], v[194:197], v[106:109]
	v_mfma_f32_16x16x32_bf16 v[102:105], v[86:89], v[206:209], v[102:105]
	v_mfma_f32_16x16x32_bf16 v[98:101], v[138:141], v[202:205], v[98:101]
	v_mfma_f32_16x16x32_bf16 v[94:97], v[86:89], v[216:219], v[94:97]
	v_mfma_f32_16x16x32_bf16 v[90:93], v[138:141], v[212:215], v[90:93]
	v_mfma_f32_16x16x32_bf16 v[86:89], v[86:89], v[224:227], v[10:13]
	v_mfma_f32_16x16x32_bf16 v[10:13], v[138:141], v[220:223], v[14:17]
	v_mfma_f32_16x16x32_bf16 v[106:109], v[142:145], v[198:201], v[106:109]
	v_mfma_f32_16x16x32_bf16 v[98:101], v[142:145], v[206:209], v[98:101]
	v_mfma_f32_16x16x32_bf16 v[90:93], v[142:145], v[216:219], v[90:93]
	v_mfma_f32_16x16x32_bf16 v[82:85], v[142:145], v[224:227], v[10:13]
	v_mfma_f32_16x16x32_bf16 v[10:13], v[146:149], v[194:197], v[46:49]
	v_mfma_f32_16x16x32_bf16 v[46:49], v[172:175], v[198:201], v[10:13]
	v_mfma_f32_16x16x32_bf16 v[10:13], v[178:181], v[194:197], v[42:45]
	v_mfma_f32_16x16x32_bf16 v[42:45], v[190:193], v[198:201], v[10:13]
	v_mfma_f32_16x16x32_bf16 v[10:13], v[146:149], v[202:205], v[38:41]
	v_mfma_f32_16x16x32_bf16 v[38:41], v[172:175], v[206:209], v[10:13]
	v_mfma_f32_16x16x32_bf16 v[10:13], v[178:181], v[202:205], v[34:37]
	v_mfma_f32_16x16x32_bf16 v[34:37], v[190:193], v[206:209], v[10:13]
	v_mfma_f32_16x16x32_bf16 v[10:13], v[146:149], v[212:215], v[30:33]
	v_mfma_f32_16x16x32_bf16 v[30:33], v[172:175], v[216:219], v[10:13]
	v_mfma_f32_16x16x32_bf16 v[10:13], v[178:181], v[212:215], v[26:29]
	v_mfma_f32_16x16x32_bf16 v[26:29], v[190:193], v[216:219], v[10:13]
	v_mfma_f32_16x16x32_bf16 v[10:13], v[146:149], v[220:223], v[22:25]
	v_mfma_f32_16x16x32_bf16 v[22:25], v[172:175], v[224:227], v[10:13]
	v_mfma_f32_16x16x32_bf16 v[10:13], v[178:181], v[220:223], v[18:21]
	v_mfma_f32_16x16x32_bf16 v[18:21], v[190:193], v[224:227], v[10:13]
	s_setprio 0
	s_barrier
	s_add_i32 s60, s60, 2
	s_add_u32 s8, s8, 0x100
	s_addc_u32 s9, s9, 0
	s_add_u32 s48, s48, 0x100
	s_addc_u32 s49, s49, 0
	s_cmp_gt_u32 s60, 13
	s_cbranch_scc0 .LBB0_1552
	s_and_b64 vcc, exec, s[22:23]
	s_cbranch_vccz .LBB0_1555
	s_barrier

; #define PG8_STAGE(bufoff, gbase, voff) do { _Pragma("unroll") for (int _i = 0; _i < 2; ++_i) \
;         __builtin_amdgcn_global_load_lds((const unsigned*)((const char*)(gbase) + (voff)[_i]), (PG8_LAS unsigned*)(lds + (bufoff) + ldsw + _i * 8192), 16, 0, 0); } while (0)
; #define PG8_LDA(dst, b, h) do { _Pragma("unroll") for (int m = 0; m < 4; ++m) _Pragma("unroll") for (int k = 0; k < 2; ++k) dst[m][k] = *(const PG8_LAS bf16x8*)(lds + PG8_SA(b, h) + aoff + m * 2048 + k * 1024); } while (0)
; #define PG8_LDB(dst, b, h) do { _Pragma("unroll") for (int n = 0; n < 2; ++n) _Pragma("unroll") for (int k = 0; k < 2; ++k) dst[n][k] = *(const PG8_LAS bf16x8*)(lds + PG8_SB(b, h) + boff + n * 2048 + k * 1024); } while (0)
; #define PG8_MMA(ai, bj, At, Bt) do { __builtin_amdgcn_s_setprio(1); _Pragma("unroll") for (int m = 0; m < 4; ++m) _Pragma("unroll") for (int n = 0; n < 2; ++n) _Pragma("unroll") for (int k = 0; k < 2; ++k) \
;         acc[ai][bj][m][n] = __builtin_amdgcn_mfma_f32_16x16x32_bf16(Bt[n][k], At[m][k], acc[ai][bj][m][n], 0, 0, 0); __builtin_amdgcn_s_setprio(0); } while (0)
; #define PG8_WAIT_V(n) asm volatile("s_waitcnt vmcnt(" #n ")" ::: "memory")
; #define PG8_WAIT_L(n) asm volatile("s_waitcnt lgkmcnt(" #n ")" ::: "memory")
; #define PG8_BAR __builtin_amdgcn_s_barrier()
; #define PG8_SCHED __builtin_amdgcn_sched_barrier(0)
; template <class Epi, class Sched, bool ALIGN_EPI = false, bool SP2 = false>
; __device__ __forceinline__ void gemm_phase(PG8_LAS unsigned char* lds, const Gemm g, const Sched& S, const Epi& E) {
;     ...
;             PG8_LDB(B0, 0, 0); PG8_LDB(B1, 0, 1); PG8_SCHED; PG8_LDA(At, 0, 0); PG8_STAGE(PG8_SA(1, 1), a1 + hstep, voffA);
;             PG8_WAIT_V(8); PG8_WAIT_L(0); PG8_BAR; PG8_MMA(0, 0, At, B0); PG8_MMA(0, 1, At, B1); PG8_BAR; PG8_SCHED;
;             PG8_LDA(At, 0, 1); PG8_STAGE(PG8_SB(0, 0), b2, voffB); PG8_STAGE(PG8_SB(0, 1), b2 + hstep, voffB); PG8_STAGE(PG8_SA(0, 0), a2, voffA);
;             PG8_WAIT_V(8); PG8_WAIT_L(0); PG8_BAR; PG8_MMA(1, 0, At, B0); PG8_MMA(1, 1, At, B1); PG8_BAR; PG8_SCHED;
.LBB0_3673:
	ds_read_b128 v[146:149], v152
	ds_read_b128 v[156:159], v152 offset:1024
	ds_read_b128 v[160:163], v152 offset:2048
	ds_read_b128 v[164:167], v152 offset:3072
	ds_read_b128 v[168:171], v153
	ds_read_b128 v[172:175], v153 offset:1024
	ds_read_b128 v[176:179], v153 offset:2048
	ds_read_b128 v[180:183], v153 offset:3072
	s_add_u32 s0, s30, 0xfffc0080
	s_addc_u32 s1, s31, -1
	s_cmp_eq_u32 s56, 12
	s_cselect_b32 s37, s21, s1
	s_cselect_b32 s36, s27, s0
	s_cselect_b32 s35, s19, s55
	s_cselect_b32 s34, s53, s54
	v_lshl_add_u64 v[208:209], s[30:31], 0, v[138:139]
	s_add_i32 m0, s29, 0xc000
	ds_read_b128 v[184:187], v154
	ds_read_b128 v[188:191], v154 offset:1024
	ds_read_b128 v[192:195], v154 offset:2048
	ds_read_b128 v[196:199], v154 offset:3072
	ds_read_b128 v[200:203], v154 offset:4096
	ds_read_b128 v[204:207], v154 offset:5120
	ds_read_b128 v[212:215], v154 offset:6144
	ds_read_b128 v[216:219], v154 offset:7168
	global_load_lds_dwordx4 v[208:209], off
	v_lshl_add_u64 v[208:209], s[30:31], 0, v[140:141]
	s_add_i32 m0, s29, 0xe000
	s_nop 0
	global_load_lds_dwordx4 v[208:209], off
	s_waitcnt vmcnt(8)
	s_waitcnt lgkmcnt(0)
	s_barrier
	s_setprio 1
	s_waitcnt lgkmcnt(0)
	v_mfma_f32_16x16x32_bf16 v[126:129], v[146:149], v[184:187], v[126:129]
	v_mfma_f32_16x16x32_bf16 v[122:125], v[160:163], v[184:187], v[122:125]
	v_mfma_f32_16x16x32_bf16 v[110:113], v[146:149], v[192:195], v[110:113]
	v_mfma_f32_16x16x32_bf16 v[106:109], v[160:163], v[192:195], v[106:109]
	v_mfma_f32_16x16x32_bf16 v[94:97], v[146:149], v[200:203], v[94:97]
	v_mfma_f32_16x16x32_bf16 v[90:93], v[160:163], v[200:203], v[90:93]
	v_mfma_f32_16x16x32_bf16 v[78:81], v[146:149], v[212:215], v[78:81]
	v_mfma_f32_16x16x32_bf16 v[74:77], v[160:163], v[212:215], v[74:77]
	v_mfma_f32_16x16x32_bf16 v[126:129], v[156:159], v[188:191], v[126:129]
	v_mfma_f32_16x16x32_bf16 v[122:125], v[164:167], v[188:191], v[122:125]
	v_mfma_f32_16x16x32_bf16 v[110:113], v[156:159], v[196:199], v[110:113]
	v_mfma_f32_16x16x32_bf16 v[106:109], v[164:167], v[196:199], v[106:109]
	v_mfma_f32_16x16x32_bf16 v[94:97], v[156:159], v[204:207], v[94:97]
	v_mfma_f32_16x16x32_bf16 v[90:93], v[164:167], v[204:207], v[90:93]
	v_mfma_f32_16x16x32_bf16 v[78:81], v[156:159], v[216:219], v[78:81]
	v_mfma_f32_16x16x32_bf16 v[74:77], v[164:167], v[216:219], v[74:77]
	v_mfma_f32_16x16x32_bf16 v[118:121], v[168:171], v[184:187], v[118:121]
	v_mfma_f32_16x16x32_bf16 v[114:117], v[176:179], v[184:187], v[114:117]
	v_mfma_f32_16x16x32_bf16 v[102:105], v[168:171], v[192:195], v[102:105]
	v_mfma_f32_16x16x32_bf16 v[98:101], v[176:179], v[192:195], v[98:101]
	v_mfma_f32_16x16x32_bf16 v[86:89], v[168:171], v[200:203], v[86:89]
	v_mfma_f32_16x16x32_bf16 v[82:85], v[176:179], v[200:203], v[82:85]
	v_mfma_f32_16x16x32_bf16 v[70:73], v[168:171], v[212:215], v[70:73]
	v_mfma_f32_16x16x32_bf16 v[66:69], v[176:179], v[212:215], v[66:69]
	v_mfma_f32_16x16x32_bf16 v[118:121], v[172:175], v[188:191], v[118:121]
	v_mfma_f32_16x16x32_bf16 v[114:117], v[180:183], v[188:191], v[114:117]
	v_mfma_f32_16x16x32_bf16 v[102:105], v[172:175], v[196:199], v[102:105]
	v_mfma_f32_16x16x32_bf16 v[98:101], v[180:183], v[196:199], v[98:101]
	v_mfma_f32_16x16x32_bf16 v[86:89], v[172:175], v[204:207], v[86:89]
	v_mfma_f32_16x16x32_bf16 v[82:85], v[180:183], v[204:207], v[82:85]
	v_mfma_f32_16x16x32_bf16 v[70:73], v[172:175], v[216:219], v[70:73]
	v_mfma_f32_16x16x32_bf16 v[66:69], v[180:183], v[216:219], v[66:69]
	s_setprio 0
	s_barrier
	s_add_i32 s0, s51, s40
	v_lshl_add_u64 v[208:209], s[34:35], 0, v[132:133]
	s_mov_b32 m0, s0
	ds_read_b128 v[184:187], v154 offset:16384
	ds_read_b128 v[188:191], v154 offset:17408
	ds_read_b128 v[192:195], v154 offset:18432
	ds_read_b128 v[196:199], v154 offset:19456
	ds_read_b128 v[200:203], v154 offset:20480
	ds_read_b128 v[204:207], v154 offset:21504
	ds_read_b128 v[212:215], v154 offset:22528
	ds_read_b128 v[216:219], v154 offset:23552
	global_load_lds_dwordx4 v[208:209], off
	s_add_i32 m0, s0, 0x2000
	s_add_u32 s0, s34, 0x40000
	v_lshl_add_u64 v[220:221], s[34:35], 0, v[136:137]
	s_addc_u32 s1, s35, 0
	s_add_i32 s57, s52, s40
	global_load_lds_dwordx4 v[220:221], off
	v_lshl_add_u64 v[222:223], s[0:1], 0, v[132:133]
	s_mov_b32 m0, s57
	v_lshl_add_u64 v[224:225], s[36:37], 0, v[134:135]
	global_load_lds_dwordx4 v[222:223], off
	v_lshl_add_u64 v[222:223], s[0:1], 0, v[136:137]
	s_add_i32 m0, s57, 0x2000
	s_nop 0
	global_load_lds_dwordx4 v[222:223], off
	v_lshl_add_u64 v[222:223], s[36:37], 0, v[130:131]
	s_mov_b32 m0, s29
	s_nop 0
	global_load_lds_dwordx4 v[222:223], off
	s_mov_b32 m0, s41
	s_nop 0
	global_load_lds_dwordx4 v[224:225], off
	s_waitcnt vmcnt(8)
	s_waitcnt lgkmcnt(0)
	s_barrier
; #define PG8_STAGE(bufoff, gbase, voff) do { _Pragma("unroll") for (int _i = 0; _i < 2; ++_i) \
;         __builtin_amdgcn_global_load_lds((const unsigned*)((const char*)(gbase) + (voff)[_i]), (PG8_LAS unsigned*)(lds + (bufoff) + ldsw + _i * 8192), 16, 0, 0); } while (0)
; #define PG8_LDA(dst, b, h) do { _Pragma("unroll") for (int m = 0; m < 4; ++m) _Pragma("unroll") for (int k = 0; k < 2; ++k) dst[m][k] = *(const PG8_LAS bf16x8*)(lds + PG8_SA(b, h) + aoff + m * 2048 + k * 1024); } while (0)
; #define PG8_LDB(dst, b, h) do { _Pragma("unroll") for (int n = 0; n < 2; ++n) _Pragma("unroll") for (int k = 0; k < 2; ++k) dst[n][k] = *(const PG8_LAS bf16x8*)(lds + PG8_SB(b, h) + boff + n * 2048 + k * 1024); } while (0)
; #define PG8_MMA(ai, bj, At, Bt) do { __builtin_amdgcn_s_setprio(1); _Pragma("unroll") for (int m = 0; m < 4; ++m) _Pragma("unroll") for (int n = 0; n < 2; ++n) _Pragma("unroll") for (int k = 0; k < 2; ++k) \
;         acc[ai][bj][m][n] = __builtin_amdgcn_mfma_f32_16x16x32_bf16(Bt[n][k], At[m][k], acc[ai][bj][m][n], 0, 0, 0); __builtin_amdgcn_s_setprio(0); } while (0)
; #define PG8_WAIT_V(n) asm volatile("s_waitcnt vmcnt(" #n ")" ::: "memory")
; #define PG8_WAIT_L(n) asm volatile("s_waitcnt lgkmcnt(" #n ")" ::: "memory")
; #define PG8_BAR __builtin_amdgcn_s_barrier()
; #define PG8_SCHED __builtin_amdgcn_sched_barrier(0)
; template <class Epi, class Sched, bool ALIGN_EPI = false, bool SP2 = false>
; __device__ __forceinline__ void gemm_phase(PG8_LAS unsigned char* lds, const Gemm g, const Sched& S, const Epi& E) {
;     ...
;             PG8_WAIT_V(8); PG8_WAIT_L(0); PG8_BAR; PG8_MMA(1, 0, At, B0); PG8_MMA(1, 1, At, B1); PG8_BAR; PG8_SCHED;
;             PG8_LDB(B0, 1, 0); PG8_LDB(B1, 1, 1); PG8_SCHED; PG8_LDA(At, 1, 0); PG8_STAGE(PG8_SA(0, 1), a2 + hstep, voffA);
;             PG8_WAIT_V(8); PG8_WAIT_L(0); PG8_BAR; PG8_MMA(0, 0, At, B0); PG8_MMA(0, 1, At, B1); PG8_BAR; PG8_SCHED;
	s_setprio 1
	s_waitcnt lgkmcnt(0)
	v_mfma_f32_16x16x32_bf16 v[62:65], v[146:149], v[184:187], v[62:65]
	v_mfma_f32_16x16x32_bf16 v[58:61], v[160:163], v[184:187], v[58:61]
	v_mfma_f32_16x16x32_bf16 v[46:49], v[146:149], v[192:195], v[46:49]
	v_mfma_f32_16x16x32_bf16 v[42:45], v[160:163], v[192:195], v[42:45]
	v_mfma_f32_16x16x32_bf16 v[30:33], v[146:149], v[200:203], v[30:33]
	v_mfma_f32_16x16x32_bf16 v[26:29], v[160:163], v[200:203], v[26:29]
	v_mfma_f32_16x16x32_bf16 v[14:17], v[146:149], v[212:215], v[14:17]
	v_mfma_f32_16x16x32_bf16 v[10:13], v[160:163], v[212:215], v[10:13]
	v_mfma_f32_16x16x32_bf16 v[62:65], v[156:159], v[188:191], v[62:65]
	v_mfma_f32_16x16x32_bf16 v[58:61], v[164:167], v[188:191], v[58:61]
	v_mfma_f32_16x16x32_bf16 v[46:49], v[156:159], v[196:199], v[46:49]
	v_mfma_f32_16x16x32_bf16 v[42:45], v[164:167], v[196:199], v[42:45]
	v_mfma_f32_16x16x32_bf16 v[30:33], v[156:159], v[204:207], v[30:33]
	v_mfma_f32_16x16x32_bf16 v[26:29], v[164:167], v[204:207], v[26:29]
	v_mfma_f32_16x16x32_bf16 v[14:17], v[156:159], v[216:219], v[14:17]
	v_mfma_f32_16x16x32_bf16 v[10:13], v[164:167], v[216:219], v[10:13]
	v_mfma_f32_16x16x32_bf16 v[54:57], v[168:171], v[184:187], v[54:57]
	v_mfma_f32_16x16x32_bf16 v[50:53], v[176:179], v[184:187], v[50:53]
	v_mfma_f32_16x16x32_bf16 v[38:41], v[168:171], v[192:195], v[38:41]
	v_mfma_f32_16x16x32_bf16 v[34:37], v[176:179], v[192:195], v[34:37]
	v_mfma_f32_16x16x32_bf16 v[22:25], v[168:171], v[200:203], v[22:25]
	v_mfma_f32_16x16x32_bf16 v[18:21], v[176:179], v[200:203], v[18:21]
	v_mfma_f32_16x16x32_bf16 v[6:9], v[168:171], v[212:215], v[6:9]
	v_mfma_f32_16x16x32_bf16 v[2:5], v[176:179], v[212:215], v[2:5]
	v_mfma_f32_16x16x32_bf16 v[54:57], v[172:175], v[188:191], v[54:57]
	v_mfma_f32_16x16x32_bf16 v[50:53], v[180:183], v[188:191], v[50:53]
	v_mfma_f32_16x16x32_bf16 v[38:41], v[172:175], v[196:199], v[38:41]
	v_mfma_f32_16x16x32_bf16 v[34:37], v[180:183], v[196:199], v[34:37]
	v_mfma_f32_16x16x32_bf16 v[22:25], v[172:175], v[204:207], v[22:25]
	v_mfma_f32_16x16x32_bf16 v[18:21], v[180:183], v[204:207], v[18:21]
	v_mfma_f32_16x16x32_bf16 v[6:9], v[172:175], v[216:219], v[6:9]
	v_mfma_f32_16x16x32_bf16 v[2:5], v[180:183], v[216:219], v[2:5]
	s_setprio 0
	s_barrier
	s_add_i32 s57, 0, 0x18000
	s_add_i32 s58, 0, 0x1c000
	v_add_u32_e32 v164, s57, v150
	v_add_u32_e32 v180, s58, v150
	ds_read_b128 v[146:149], v164
	ds_read_b128 v[156:159], v164 offset:1024
	ds_read_b128 v[160:163], v164 offset:2048
	ds_read_b128 v[164:167], v164 offset:3072
	ds_read_b128 v[168:171], v180
	ds_read_b128 v[172:175], v180 offset:1024
	ds_read_b128 v[176:179], v180 offset:2048
	ds_read_b128 v[180:183], v180 offset:3072
	s_add_u32 s0, s36, 0x40000
	s_addc_u32 s1, s37, 0
	s_mov_b32 m0, s44
	v_lshl_add_u64 v[226:227], s[0:1], 0, v[130:131]
	ds_read_b128 v[184:187], v154 offset:32768
	ds_read_b128 v[188:191], v154 offset:33792
	ds_read_b128 v[192:195], v154 offset:34816
	ds_read_b128 v[196:199], v154 offset:35840
	ds_read_b128 v[200:203], v154 offset:36864
	ds_read_b128 v[204:207], v154 offset:37888
	ds_read_b128 v[212:215], v154 offset:38912
	ds_read_b128 v[216:219], v154 offset:39936
	global_load_lds_dwordx4 v[226:227], off
	v_lshl_add_u64 v[226:227], s[0:1], 0, v[134:135]
	s_mov_b32 m0, s45
	s_nop 0
	global_load_lds_dwordx4 v[226:227], off
	s_waitcnt vmcnt(8)
	s_waitcnt lgkmcnt(0)
	s_barrier
	s_setprio 1
	s_waitcnt lgkmcnt(0)
	v_mfma_f32_16x16x32_bf16 v[126:129], v[146:149], v[184:187], v[126:129]
	v_mfma_f32_16x16x32_bf16 v[122:125], v[160:163], v[184:187], v[122:125]
	v_mfma_f32_16x16x32_bf16 v[110:113], v[146:149], v[192:195], v[110:113]
	v_mfma_f32_16x16x32_bf16 v[106:109], v[160:163], v[192:195], v[106:109]
	v_mfma_f32_16x16x32_bf16 v[94:97], v[146:149], v[200:203], v[94:97]
	v_mfma_f32_16x16x32_bf16 v[90:93], v[160:163], v[200:203], v[90:93]
	v_mfma_f32_16x16x32_bf16 v[78:81], v[146:149], v[212:215], v[78:81]
	v_mfma_f32_16x16x32_bf16 v[74:77], v[160:163], v[212:215], v[74:77]
	v_mfma_f32_16x16x32_bf16 v[126:129], v[156:159], v[188:191], v[126:129]
	v_mfma_f32_16x16x32_bf16 v[122:125], v[164:167], v[188:191], v[122:125]
	v_mfma_f32_16x16x32_bf16 v[110:113], v[156:159], v[196:199], v[110:113]
	v_mfma_f32_16x16x32_bf16 v[106:109], v[164:167], v[196:199], v[106:109]
	v_mfma_f32_16x16x32_bf16 v[94:97], v[156:159], v[204:207], v[94:97]
	v_mfma_f32_16x16x32_bf16 v[90:93], v[164:167], v[204:207], v[90:93]
	v_mfma_f32_16x16x32_bf16 v[78:81], v[156:159], v[216:219], v[78:81]
	v_mfma_f32_16x16x32_bf16 v[74:77], v[164:167], v[216:219], v[74:77]
	v_mfma_f32_16x16x32_bf16 v[118:121], v[168:171], v[184:187], v[118:121]
	v_mfma_f32_16x16x32_bf16 v[114:117], v[176:179], v[184:187], v[114:117]
	v_mfma_f32_16x16x32_bf16 v[102:105], v[168:171], v[192:195], v[102:105]
	v_mfma_f32_16x16x32_bf16 v[98:101], v[176:179], v[192:195], v[98:101]
	v_mfma_f32_16x16x32_bf16 v[86:89], v[168:171], v[200:203], v[86:89]
	v_mfma_f32_16x16x32_bf16 v[82:85], v[176:179], v[200:203], v[82:85]
	v_mfma_f32_16x16x32_bf16 v[70:73], v[168:171], v[212:215], v[70:73]
	v_mfma_f32_16x16x32_bf16 v[66:69], v[176:179], v[212:215], v[66:69]
	v_mfma_f32_16x16x32_bf16 v[118:121], v[172:175], v[188:191], v[118:121]
	v_mfma_f32_16x16x32_bf16 v[114:117], v[180:183], v[188:191], v[114:117]
	v_mfma_f32_16x16x32_bf16 v[102:105], v[172:175], v[196:199], v[102:105]
	v_mfma_f32_16x16x32_bf16 v[98:101], v[180:183], v[196:199], v[98:101]
	v_mfma_f32_16x16x32_bf16 v[86:89], v[172:175], v[204:207], v[86:89]
	v_mfma_f32_16x16x32_bf16 v[82:85], v[180:183], v[204:207], v[82:85]
	v_mfma_f32_16x16x32_bf16 v[70:73], v[172:175], v[216:219], v[70:73]
	v_mfma_f32_16x16x32_bf16 v[66:69], v[180:183], v[216:219], v[66:69]
	s_setprio 0
	s_barrier
; #define PG8_STAGE(bufoff, gbase, voff) do { _Pragma("unroll") for (int _i = 0; _i < 2; ++_i) \
;         __builtin_amdgcn_global_load_lds((const unsigned*)((const char*)(gbase) + (voff)[_i]), (PG8_LAS unsigned*)(lds + (bufoff) + ldsw + _i * 8192), 16, 0, 0); } while (0)
; #define PG8_LDA(dst, b, h) do { _Pragma("unroll") for (int m = 0; m < 4; ++m) _Pragma("unroll") for (int k = 0; k < 2; ++k) dst[m][k] = *(const PG8_LAS bf16x8*)(lds + PG8_SA(b, h) + aoff + m * 2048 + k * 1024); } while (0)
; #define PG8_MMA(ai, bj, At, Bt) do { __builtin_amdgcn_s_setprio(1); _Pragma("unroll") for (int m = 0; m < 4; ++m) _Pragma("unroll") for (int n = 0; n < 2; ++n) _Pragma("unroll") for (int k = 0; k < 2; ++k) \
;         acc[ai][bj][m][n] = __builtin_amdgcn_mfma_f32_16x16x32_bf16(Bt[n][k], At[m][k], acc[ai][bj][m][n], 0, 0, 0); __builtin_amdgcn_s_setprio(0); } while (0)
; #define PG8_WAIT_V(n) asm volatile("s_waitcnt vmcnt(" #n ")" ::: "memory")
; #define PG8_WAIT_L(n) asm volatile("s_waitcnt lgkmcnt(" #n ")" ::: "memory")
; #define PG8_BAR __builtin_amdgcn_s_barrier()
; #define PG8_SCHED __builtin_amdgcn_sched_barrier(0)
; template <class Epi, class Sched, bool ALIGN_EPI = false, bool SP2 = false>
; __device__ __forceinline__ void gemm_phase(PG8_LAS unsigned char* lds, const Gemm g, const Sched& S, const Epi& E) {
;     ...
;         for (int t = 0; t < nt; t += 2) {
;             const bool last = (t == nt - 2);
;             const char* a1 = cA + (size_t)(t + 1) * kstep;
;             const char* a2 = last ? nA : cA + (size_t)(t + 2) * kstep; const char* b2 = last ? nB : cB + (size_t)(t + 2) * kstep;
;             const char* a3 = a2 + kstep; const char* b3 = b2 + kstep;
;     ...
;             PG8_LDA(At, 1, 1); PG8_STAGE(PG8_SB(1, 0), b3, voffB); PG8_STAGE(PG8_SB(1, 1), b3 + hstep, voffB); PG8_STAGE(PG8_SA(1, 0), a3, voffA);
;             PG8_WAIT_V(8); PG8_WAIT_L(0); PG8_BAR; PG8_MMA(1, 0, At, B0); PG8_MMA(1, 1, At, B1); PG8_BAR; PG8_SCHED;
	s_add_i32 s0, s57, s40
	v_lshl_add_u64 v[208:209], v[208:209], 0, s[14:15]
	s_mov_b32 m0, s0
	ds_read_b128 v[184:187], v154 offset:49152
	ds_read_b128 v[188:191], v154 offset:50176
	ds_read_b128 v[192:195], v154 offset:51200
	ds_read_b128 v[196:199], v154 offset:52224
	ds_read_b128 v[200:203], v154 offset:53248
	ds_read_b128 v[204:207], v154 offset:54272
	ds_read_b128 v[212:215], v154 offset:55296
	ds_read_b128 v[216:219], v154 offset:56320
	global_load_lds_dwordx4 v[208:209], off
	s_add_i32 m0, s0, 0x2000
	s_add_u32 s0, s34, 0x40080
	v_lshl_add_u64 v[208:209], v[220:221], 0, s[14:15]
	s_addc_u32 s1, s35, 0
	s_add_i32 s34, s58, s40
	global_load_lds_dwordx4 v[208:209], off
	v_lshl_add_u64 v[208:209], s[0:1], 0, v[132:133]
	s_mov_b32 m0, s34
	s_nop 0
	global_load_lds_dwordx4 v[208:209], off
	v_lshl_add_u64 v[208:209], s[0:1], 0, v[136:137]
	s_add_i32 m0, s34, 0x2000
	s_nop 0
	global_load_lds_dwordx4 v[208:209], off
	v_lshl_add_u64 v[208:209], v[222:223], 0, s[14:15]
	s_mov_b32 m0, s47
	s_nop 0
	global_load_lds_dwordx4 v[208:209], off
	v_lshl_add_u64 v[208:209], v[224:225], 0, s[14:15]
	s_mov_b32 m0, s48
	s_nop 0
	global_load_lds_dwordx4 v[208:209], off
	s_waitcnt vmcnt(8)
	s_waitcnt lgkmcnt(0)
	s_barrier
	s_setprio 1
	s_waitcnt lgkmcnt(0)
	v_mfma_f32_16x16x32_bf16 v[62:65], v[146:149], v[184:187], v[62:65]
	v_mfma_f32_16x16x32_bf16 v[58:61], v[160:163], v[184:187], v[58:61]
	v_mfma_f32_16x16x32_bf16 v[46:49], v[146:149], v[192:195], v[46:49]
	v_mfma_f32_16x16x32_bf16 v[42:45], v[160:163], v[192:195], v[42:45]
	v_mfma_f32_16x16x32_bf16 v[30:33], v[146:149], v[200:203], v[30:33]
	v_mfma_f32_16x16x32_bf16 v[26:29], v[160:163], v[200:203], v[26:29]
	v_mfma_f32_16x16x32_bf16 v[14:17], v[146:149], v[212:215], v[14:17]
	v_mfma_f32_16x16x32_bf16 v[10:13], v[160:163], v[212:215], v[10:13]
	v_mfma_f32_16x16x32_bf16 v[62:65], v[156:159], v[188:191], v[62:65]
	v_mfma_f32_16x16x32_bf16 v[58:61], v[164:167], v[188:191], v[58:61]
	v_mfma_f32_16x16x32_bf16 v[46:49], v[156:159], v[196:199], v[46:49]
	v_mfma_f32_16x16x32_bf16 v[42:45], v[164:167], v[196:199], v[42:45]
	v_mfma_f32_16x16x32_bf16 v[30:33], v[156:159], v[204:207], v[30:33]
	v_mfma_f32_16x16x32_bf16 v[26:29], v[164:167], v[204:207], v[26:29]
	v_mfma_f32_16x16x32_bf16 v[14:17], v[156:159], v[216:219], v[14:17]
	v_mfma_f32_16x16x32_bf16 v[10:13], v[164:167], v[216:219], v[10:13]
	v_mfma_f32_16x16x32_bf16 v[54:57], v[168:171], v[184:187], v[54:57]
	v_mfma_f32_16x16x32_bf16 v[50:53], v[176:179], v[184:187], v[50:53]
	v_mfma_f32_16x16x32_bf16 v[38:41], v[168:171], v[192:195], v[38:41]
	v_mfma_f32_16x16x32_bf16 v[34:37], v[176:179], v[192:195], v[34:37]
	v_mfma_f32_16x16x32_bf16 v[22:25], v[168:171], v[200:203], v[22:25]
	v_mfma_f32_16x16x32_bf16 v[18:21], v[176:179], v[200:203], v[18:21]
	v_mfma_f32_16x16x32_bf16 v[6:9], v[168:171], v[212:215], v[6:9]
	v_mfma_f32_16x16x32_bf16 v[2:5], v[176:179], v[212:215], v[2:5]
	v_mfma_f32_16x16x32_bf16 v[54:57], v[172:175], v[188:191], v[54:57]
	v_mfma_f32_16x16x32_bf16 v[50:53], v[180:183], v[188:191], v[50:53]
	v_mfma_f32_16x16x32_bf16 v[38:41], v[172:175], v[196:199], v[38:41]
	v_mfma_f32_16x16x32_bf16 v[34:37], v[180:183], v[196:199], v[34:37]
	v_mfma_f32_16x16x32_bf16 v[22:25], v[172:175], v[204:207], v[22:25]
	v_mfma_f32_16x16x32_bf16 v[18:21], v[180:183], v[204:207], v[18:21]
	v_mfma_f32_16x16x32_bf16 v[6:9], v[172:175], v[216:219], v[6:9]
	v_mfma_f32_16x16x32_bf16 v[2:5], v[180:183], v[216:219], v[2:5]
	s_setprio 0
	s_barrier
	s_add_i32 s56, s56, 2
	s_add_u32 s30, s30, 0x100
	s_addc_u32 s31, s31, 0
	s_add_u32 s54, s54, 0x100
	s_addc_u32 s55, s55, 0
	s_cmp_gt_u32 s56, 13
	s_cbranch_scc0 .LBB0_3673
	s_and_b64 vcc, exec, s[16:17]
	s_cbranch_vccz .LBB0_3676
	s_barrier

; #define PG8_STAGE(bufoff, gbase, voff) do { _Pragma("unroll") for (int _i = 0; _i < 2; ++_i) \
;         __builtin_amdgcn_global_load_lds((const unsigned*)((const char*)(gbase) + (voff)[_i]), (PG8_LAS unsigned*)(lds + (bufoff) + ldsw + _i * 8192), 16, 0, 0); } while (0)
; #define PG8_LDA(dst, b, h) do { _Pragma("unroll") for (int m = 0; m < 4; ++m) _Pragma("unroll") for (int k = 0; k < 2; ++k) dst[m][k] = *(const PG8_LAS bf16x8*)(lds + PG8_SA(b, h) + aoff + m * 2048 + k * 1024); } while (0)
; #define PG8_LDB(dst, b, h) do { _Pragma("unroll") for (int n = 0; n < 2; ++n) _Pragma("unroll") for (int k = 0; k < 2; ++k) dst[n][k] = *(const PG8_LAS bf16x8*)(lds + PG8_SB(b, h) + boff + n * 2048 + k * 1024); } while (0)
; #define PG8_MMA(ai, bj, At, Bt) do { __builtin_amdgcn_s_setprio(1); _Pragma("unroll") for (int m = 0; m < 4; ++m) _Pragma("unroll") for (int n = 0; n < 2; ++n) _Pragma("unroll") for (int k = 0; k < 2; ++k) \
;         acc[ai][bj][m][n] = __builtin_amdgcn_mfma_f32_16x16x32_bf16(Bt[n][k], At[m][k], acc[ai][bj][m][n], 0, 0, 0); __builtin_amdgcn_s_setprio(0); } while (0)
; #define PG8_WAIT_V(n) asm volatile("s_waitcnt vmcnt(" #n ")" ::: "memory")
; #define PG8_WAIT_L(n) asm volatile("s_waitcnt lgkmcnt(" #n ")" ::: "memory")
; #define PG8_BAR __builtin_amdgcn_s_barrier()
; #define PG8_SCHED __builtin_amdgcn_sched_barrier(0)
; template <class Epi, class Sched, bool ALIGN_EPI = false, bool SP2 = false>
; __device__ __forceinline__ void gemm_phase(PG8_LAS unsigned char* lds, const Gemm g, const Sched& S, const Epi& E) {
;     ...
;             PG8_LDB(B0, 0, 0); PG8_LDB(B1, 0, 1); PG8_SCHED; PG8_LDA(At, 0, 0); PG8_STAGE(PG8_SA(1, 1), a1 + hstep, voffA);
;             PG8_WAIT_V(8); PG8_WAIT_L(0); PG8_BAR; PG8_MMA(0, 0, At, B0); PG8_MMA(0, 1, At, B1); PG8_BAR; PG8_SCHED;
;             PG8_LDA(At, 0, 1); PG8_STAGE(PG8_SB(0, 0), b2, voffB); PG8_STAGE(PG8_SB(0, 1), b2 + hstep, voffB); PG8_STAGE(PG8_SA(0, 0), a2, voffA);
;             PG8_WAIT_V(8); PG8_WAIT_L(0); PG8_BAR; PG8_MMA(1, 0, At, B0); PG8_MMA(1, 1, At, B1); PG8_BAR; PG8_SCHED;
.LBB0_3723:
	ds_read_b128 v[154:157], v150
	ds_read_b128 v[158:161], v150 offset:1024
	ds_read_b128 v[162:165], v150 offset:2048
	ds_read_b128 v[166:169], v150 offset:3072
	ds_read_b128 v[170:173], v151
	ds_read_b128 v[174:177], v151 offset:1024
	ds_read_b128 v[178:181], v151 offset:2048
	ds_read_b128 v[182:185], v151 offset:3072
	s_add_u32 s0, s30, 0xfffc0080
	s_addc_u32 s1, s31, -1
	s_cmp_eq_u32 s68, 12
	s_cselect_b32 s37, s23, s1
	s_cselect_b32 s36, s58, s0
	s_cselect_b32 s35, s21, s61
	s_cselect_b32 s34, s59, s60
	v_lshl_add_u64 v[146:147], s[30:31], 0, v[138:139]
	s_add_i32 m0, s29, 0xc000
	ds_read_b128 v[186:189], v152
	ds_read_b128 v[190:193], v152 offset:1024
	ds_read_b128 v[194:197], v152 offset:2048
	ds_read_b128 v[198:201], v152 offset:3072
	ds_read_b128 v[202:205], v152 offset:4096
	ds_read_b128 v[206:209], v152 offset:5120
	ds_read_b128 v[212:215], v152 offset:6144
	ds_read_b128 v[216:219], v152 offset:7168
	global_load_lds_dwordx4 v[146:147], off
	v_lshl_add_u64 v[146:147], s[30:31], 0, v[140:141]
	s_add_i32 m0, s29, 0xe000
	s_nop 0
	global_load_lds_dwordx4 v[146:147], off
	s_waitcnt vmcnt(8)
	s_waitcnt lgkmcnt(0)
	s_barrier
	s_setprio 1
	s_waitcnt lgkmcnt(0)
	v_mfma_f32_16x16x32_bf16 v[126:129], v[154:157], v[186:189], v[126:129]
	v_mfma_f32_16x16x32_bf16 v[122:125], v[162:165], v[186:189], v[122:125]
	v_mfma_f32_16x16x32_bf16 v[110:113], v[154:157], v[194:197], v[110:113]
	v_mfma_f32_16x16x32_bf16 v[106:109], v[162:165], v[194:197], v[106:109]
	v_mfma_f32_16x16x32_bf16 v[94:97], v[154:157], v[202:205], v[94:97]
	v_mfma_f32_16x16x32_bf16 v[90:93], v[162:165], v[202:205], v[90:93]
	v_mfma_f32_16x16x32_bf16 v[78:81], v[154:157], v[212:215], v[78:81]
	v_mfma_f32_16x16x32_bf16 v[74:77], v[162:165], v[212:215], v[74:77]
	v_mfma_f32_16x16x32_bf16 v[126:129], v[158:161], v[190:193], v[126:129]
	v_mfma_f32_16x16x32_bf16 v[122:125], v[166:169], v[190:193], v[122:125]
	v_mfma_f32_16x16x32_bf16 v[110:113], v[158:161], v[198:201], v[110:113]
	v_mfma_f32_16x16x32_bf16 v[106:109], v[166:169], v[198:201], v[106:109]
	v_mfma_f32_16x16x32_bf16 v[94:97], v[158:161], v[206:209], v[94:97]
	v_mfma_f32_16x16x32_bf16 v[90:93], v[166:169], v[206:209], v[90:93]
	v_mfma_f32_16x16x32_bf16 v[78:81], v[158:161], v[216:219], v[78:81]
	v_mfma_f32_16x16x32_bf16 v[74:77], v[166:169], v[216:219], v[74:77]
	v_mfma_f32_16x16x32_bf16 v[118:121], v[170:173], v[186:189], v[118:121]
	v_mfma_f32_16x16x32_bf16 v[114:117], v[178:181], v[186:189], v[114:117]
	v_mfma_f32_16x16x32_bf16 v[102:105], v[170:173], v[194:197], v[102:105]
	v_mfma_f32_16x16x32_bf16 v[98:101], v[178:181], v[194:197], v[98:101]
	v_mfma_f32_16x16x32_bf16 v[86:89], v[170:173], v[202:205], v[86:89]
	v_mfma_f32_16x16x32_bf16 v[82:85], v[178:181], v[202:205], v[82:85]
	v_mfma_f32_16x16x32_bf16 v[70:73], v[170:173], v[212:215], v[70:73]
	v_mfma_f32_16x16x32_bf16 v[66:69], v[178:181], v[212:215], v[66:69]
	v_mfma_f32_16x16x32_bf16 v[118:121], v[174:177], v[190:193], v[118:121]
	v_mfma_f32_16x16x32_bf16 v[114:117], v[182:185], v[190:193], v[114:117]
	v_mfma_f32_16x16x32_bf16 v[102:105], v[174:177], v[198:201], v[102:105]
	v_mfma_f32_16x16x32_bf16 v[98:101], v[182:185], v[198:201], v[98:101]
	v_mfma_f32_16x16x32_bf16 v[86:89], v[174:177], v[206:209], v[86:89]
	v_mfma_f32_16x16x32_bf16 v[82:85], v[182:185], v[206:209], v[82:85]
	v_mfma_f32_16x16x32_bf16 v[70:73], v[174:177], v[216:219], v[70:73]
	v_mfma_f32_16x16x32_bf16 v[66:69], v[182:185], v[216:219], v[66:69]
	s_setprio 0
	s_barrier
	s_add_i32 s0, s51, s41
	v_lshl_add_u64 v[146:147], s[34:35], 0, v[132:133]
	s_mov_b32 m0, s0
	ds_read_b128 v[186:189], v152 offset:16384
	ds_read_b128 v[190:193], v152 offset:17408
	ds_read_b128 v[194:197], v152 offset:18432
	ds_read_b128 v[198:201], v152 offset:19456
	ds_read_b128 v[202:205], v152 offset:20480
	ds_read_b128 v[206:209], v152 offset:21504
	ds_read_b128 v[212:215], v152 offset:22528
	ds_read_b128 v[216:219], v152 offset:23552
	global_load_lds_dwordx4 v[146:147], off
	s_add_i32 m0, s0, 0x2000
	s_add_u32 s0, s34, 0x40000
	v_lshl_add_u64 v[220:221], s[34:35], 0, v[136:137]
	s_addc_u32 s1, s35, 0
	s_add_i32 s69, s52, s41
	global_load_lds_dwordx4 v[220:221], off
	v_lshl_add_u64 v[222:223], s[0:1], 0, v[132:133]
	s_mov_b32 m0, s69
	v_lshl_add_u64 v[224:225], s[36:37], 0, v[134:135]
	global_load_lds_dwordx4 v[222:223], off
	v_lshl_add_u64 v[222:223], s[0:1], 0, v[136:137]
	s_add_i32 m0, s69, 0x2000
	s_nop 0
	global_load_lds_dwordx4 v[222:223], off
	v_lshl_add_u64 v[222:223], s[36:37], 0, v[130:131]
	s_mov_b32 m0, s29
	s_nop 0
	global_load_lds_dwordx4 v[222:223], off
	s_mov_b32 m0, s44
	s_nop 0
	global_load_lds_dwordx4 v[224:225], off
	s_waitcnt vmcnt(8)
	s_waitcnt lgkmcnt(0)
	s_barrier
; #define PG8_STAGE(bufoff, gbase, voff) do { _Pragma("unroll") for (int _i = 0; _i < 2; ++_i) \
;         __builtin_amdgcn_global_load_lds((const unsigned*)((const char*)(gbase) + (voff)[_i]), (PG8_LAS unsigned*)(lds + (bufoff) + ldsw + _i * 8192), 16, 0, 0); } while (0)
; #define PG8_LDA(dst, b, h) do { _Pragma("unroll") for (int m = 0; m < 4; ++m) _Pragma("unroll") for (int k = 0; k < 2; ++k) dst[m][k] = *(const PG8_LAS bf16x8*)(lds + PG8_SA(b, h) + aoff + m * 2048 + k * 1024); } while (0)
; #define PG8_LDB(dst, b, h) do { _Pragma("unroll") for (int n = 0; n < 2; ++n) _Pragma("unroll") for (int k = 0; k < 2; ++k) dst[n][k] = *(const PG8_LAS bf16x8*)(lds + PG8_SB(b, h) + boff + n * 2048 + k * 1024); } while (0)
; #define PG8_MMA(ai, bj, At, Bt) do { __builtin_amdgcn_s_setprio(1); _Pragma("unroll") for (int m = 0; m < 4; ++m) _Pragma("unroll") for (int n = 0; n < 2; ++n) _Pragma("unroll") for (int k = 0; k < 2; ++k) \
;         acc[ai][bj][m][n] = __builtin_amdgcn_mfma_f32_16x16x32_bf16(Bt[n][k], At[m][k], acc[ai][bj][m][n], 0, 0, 0); __builtin_amdgcn_s_setprio(0); } while (0)
; #define PG8_WAIT_V(n) asm volatile("s_waitcnt vmcnt(" #n ")" ::: "memory")
; #define PG8_WAIT_L(n) asm volatile("s_waitcnt lgkmcnt(" #n ")" ::: "memory")
; #define PG8_BAR __builtin_amdgcn_s_barrier()
; #define PG8_SCHED __builtin_amdgcn_sched_barrier(0)
; template <class Epi, class Sched, bool ALIGN_EPI = false, bool SP2 = false>
; __device__ __forceinline__ void gemm_phase(PG8_LAS unsigned char* lds, const Gemm g, const Sched& S, const Epi& E) {
;     ...
;             PG8_WAIT_V(8); PG8_WAIT_L(0); PG8_BAR; PG8_MMA(1, 0, At, B0); PG8_MMA(1, 1, At, B1); PG8_BAR; PG8_SCHED;
;             PG8_LDB(B0, 1, 0); PG8_LDB(B1, 1, 1); PG8_SCHED; PG8_LDA(At, 1, 0); PG8_STAGE(PG8_SA(0, 1), a2 + hstep, voffA);
;             PG8_WAIT_V(8); PG8_WAIT_L(0); PG8_BAR; PG8_MMA(0, 0, At, B0); PG8_MMA(0, 1, At, B1); PG8_BAR; PG8_SCHED;
	s_setprio 1
	s_waitcnt lgkmcnt(0)
	v_mfma_f32_16x16x32_bf16 v[62:65], v[154:157], v[186:189], v[62:65]
	v_mfma_f32_16x16x32_bf16 v[58:61], v[162:165], v[186:189], v[58:61]
	v_mfma_f32_16x16x32_bf16 v[50:53], v[154:157], v[194:197], v[50:53]
	v_mfma_f32_16x16x32_bf16 v[42:45], v[162:165], v[194:197], v[42:45]
	v_mfma_f32_16x16x32_bf16 v[34:37], v[154:157], v[202:205], v[34:37]
	v_mfma_f32_16x16x32_bf16 v[26:29], v[162:165], v[202:205], v[26:29]
	v_mfma_f32_16x16x32_bf16 v[18:21], v[154:157], v[212:215], v[18:21]
	v_mfma_f32_16x16x32_bf16 v[10:13], v[162:165], v[212:215], v[10:13]
	v_mfma_f32_16x16x32_bf16 v[62:65], v[158:161], v[190:193], v[62:65]
	v_mfma_f32_16x16x32_bf16 v[58:61], v[166:169], v[190:193], v[58:61]
	v_mfma_f32_16x16x32_bf16 v[50:53], v[158:161], v[198:201], v[50:53]
	v_mfma_f32_16x16x32_bf16 v[42:45], v[166:169], v[198:201], v[42:45]
	v_mfma_f32_16x16x32_bf16 v[34:37], v[158:161], v[206:209], v[34:37]
	v_mfma_f32_16x16x32_bf16 v[26:29], v[166:169], v[206:209], v[26:29]
	v_mfma_f32_16x16x32_bf16 v[18:21], v[158:161], v[216:219], v[18:21]
	v_mfma_f32_16x16x32_bf16 v[10:13], v[166:169], v[216:219], v[10:13]
	v_mfma_f32_16x16x32_bf16 v[54:57], v[170:173], v[186:189], v[54:57]
	v_mfma_f32_16x16x32_bf16 v[46:49], v[178:181], v[186:189], v[46:49]
	v_mfma_f32_16x16x32_bf16 v[38:41], v[170:173], v[194:197], v[38:41]
	v_mfma_f32_16x16x32_bf16 v[30:33], v[178:181], v[194:197], v[30:33]
	v_mfma_f32_16x16x32_bf16 v[22:25], v[170:173], v[202:205], v[22:25]
	v_mfma_f32_16x16x32_bf16 v[14:17], v[178:181], v[202:205], v[14:17]
	v_mfma_f32_16x16x32_bf16 v[6:9], v[170:173], v[212:215], v[6:9]
	v_mfma_f32_16x16x32_bf16 v[2:5], v[178:181], v[212:215], v[2:5]
	v_mfma_f32_16x16x32_bf16 v[54:57], v[174:177], v[190:193], v[54:57]
	v_mfma_f32_16x16x32_bf16 v[46:49], v[182:185], v[190:193], v[46:49]
	v_mfma_f32_16x16x32_bf16 v[38:41], v[174:177], v[198:201], v[38:41]
	v_mfma_f32_16x16x32_bf16 v[30:33], v[182:185], v[198:201], v[30:33]
	v_mfma_f32_16x16x32_bf16 v[22:25], v[174:177], v[206:209], v[22:25]
	v_mfma_f32_16x16x32_bf16 v[14:17], v[182:185], v[206:209], v[14:17]
	v_mfma_f32_16x16x32_bf16 v[6:9], v[174:177], v[216:219], v[6:9]
	v_mfma_f32_16x16x32_bf16 v[2:5], v[182:185], v[216:219], v[2:5]
	s_setprio 0
	s_barrier
	s_add_i32 s69, 0, 0x18000
	v_add_u32_e32 v153, s69, v148
	s_add_i32 s70, 0, 0x1c000
	ds_read_b128 v[154:157], v153
	ds_read_b128 v[158:161], v153 offset:1024
	ds_read_b128 v[162:165], v153 offset:2048
	ds_read_b128 v[166:169], v153 offset:3072
	v_add_u32_e32 v153, s70, v148
	ds_read_b128 v[170:173], v153
	ds_read_b128 v[174:177], v153 offset:1024
	ds_read_b128 v[178:181], v153 offset:2048
	ds_read_b128 v[182:185], v153 offset:3072
	s_add_u32 s0, s36, 0x40000
	s_addc_u32 s1, s37, 0
	s_mov_b32 m0, s45
	v_lshl_add_u64 v[226:227], s[0:1], 0, v[130:131]
	ds_read_b128 v[186:189], v152 offset:32768
	ds_read_b128 v[190:193], v152 offset:33792
	ds_read_b128 v[194:197], v152 offset:34816
	ds_read_b128 v[198:201], v152 offset:35840
	ds_read_b128 v[202:205], v152 offset:36864
	ds_read_b128 v[206:209], v152 offset:37888
	ds_read_b128 v[212:215], v152 offset:38912
	ds_read_b128 v[216:219], v152 offset:39936
	global_load_lds_dwordx4 v[226:227], off
	v_lshl_add_u64 v[226:227], s[0:1], 0, v[134:135]
	s_mov_b32 m0, s46
	s_nop 0
	global_load_lds_dwordx4 v[226:227], off
	s_waitcnt vmcnt(8)
	s_waitcnt lgkmcnt(0)
	s_barrier
	s_setprio 1
	s_waitcnt lgkmcnt(0)
	v_mfma_f32_16x16x32_bf16 v[126:129], v[154:157], v[186:189], v[126:129]
	v_mfma_f32_16x16x32_bf16 v[122:125], v[162:165], v[186:189], v[122:125]
	v_mfma_f32_16x16x32_bf16 v[110:113], v[154:157], v[194:197], v[110:113]
	v_mfma_f32_16x16x32_bf16 v[106:109], v[162:165], v[194:197], v[106:109]
	v_mfma_f32_16x16x32_bf16 v[94:97], v[154:157], v[202:205], v[94:97]
	v_mfma_f32_16x16x32_bf16 v[90:93], v[162:165], v[202:205], v[90:93]
	v_mfma_f32_16x16x32_bf16 v[78:81], v[154:157], v[212:215], v[78:81]
	v_mfma_f32_16x16x32_bf16 v[74:77], v[162:165], v[212:215], v[74:77]
	v_mfma_f32_16x16x32_bf16 v[126:129], v[158:161], v[190:193], v[126:129]
	v_mfma_f32_16x16x32_bf16 v[122:125], v[166:169], v[190:193], v[122:125]
	v_mfma_f32_16x16x32_bf16 v[110:113], v[158:161], v[198:201], v[110:113]
	v_mfma_f32_16x16x32_bf16 v[106:109], v[166:169], v[198:201], v[106:109]
	v_mfma_f32_16x16x32_bf16 v[94:97], v[158:161], v[206:209], v[94:97]
	v_mfma_f32_16x16x32_bf16 v[90:93], v[166:169], v[206:209], v[90:93]
	v_mfma_f32_16x16x32_bf16 v[78:81], v[158:161], v[216:219], v[78:81]
	v_mfma_f32_16x16x32_bf16 v[74:77], v[166:169], v[216:219], v[74:77]
	v_mfma_f32_16x16x32_bf16 v[118:121], v[170:173], v[186:189], v[118:121]
	v_mfma_f32_16x16x32_bf16 v[114:117], v[178:181], v[186:189], v[114:117]
	v_mfma_f32_16x16x32_bf16 v[102:105], v[170:173], v[194:197], v[102:105]
	v_mfma_f32_16x16x32_bf16 v[98:101], v[178:181], v[194:197], v[98:101]
	v_mfma_f32_16x16x32_bf16 v[86:89], v[170:173], v[202:205], v[86:89]
	v_mfma_f32_16x16x32_bf16 v[82:85], v[178:181], v[202:205], v[82:85]
	v_mfma_f32_16x16x32_bf16 v[70:73], v[170:173], v[212:215], v[70:73]
	v_mfma_f32_16x16x32_bf16 v[66:69], v[178:181], v[212:215], v[66:69]
	v_mfma_f32_16x16x32_bf16 v[118:121], v[174:177], v[190:193], v[118:121]
	v_mfma_f32_16x16x32_bf16 v[114:117], v[182:185], v[190:193], v[114:117]
	v_mfma_f32_16x16x32_bf16 v[102:105], v[174:177], v[198:201], v[102:105]
	v_mfma_f32_16x16x32_bf16 v[98:101], v[182:185], v[198:201], v[98:101]
	v_mfma_f32_16x16x32_bf16 v[86:89], v[174:177], v[206:209], v[86:89]
	v_mfma_f32_16x16x32_bf16 v[82:85], v[182:185], v[206:209], v[82:85]
	v_mfma_f32_16x16x32_bf16 v[70:73], v[174:177], v[216:219], v[70:73]
	v_mfma_f32_16x16x32_bf16 v[66:69], v[182:185], v[216:219], v[66:69]
	s_setprio 0
	s_barrier
; #define PG8_STAGE(bufoff, gbase, voff) do { _Pragma("unroll") for (int _i = 0; _i < 2; ++_i) \
;         __builtin_amdgcn_global_load_lds((const unsigned*)((const char*)(gbase) + (voff)[_i]), (PG8_LAS unsigned*)(lds + (bufoff) + ldsw + _i * 8192), 16, 0, 0); } while (0)
; #define PG8_LDA(dst, b, h) do { _Pragma("unroll") for (int m = 0; m < 4; ++m) _Pragma("unroll") for (int k = 0; k < 2; ++k) dst[m][k] = *(const PG8_LAS bf16x8*)(lds + PG8_SA(b, h) + aoff + m * 2048 + k * 1024); } while (0)
; #define PG8_MMA(ai, bj, At, Bt) do { __builtin_amdgcn_s_setprio(1); _Pragma("unroll") for (int m = 0; m < 4; ++m) _Pragma("unroll") for (int n = 0; n < 2; ++n) _Pragma("unroll") for (int k = 0; k < 2; ++k) \
;         acc[ai][bj][m][n] = __builtin_amdgcn_mfma_f32_16x16x32_bf16(Bt[n][k], At[m][k], acc[ai][bj][m][n], 0, 0, 0); __builtin_amdgcn_s_setprio(0); } while (0)
; #define PG8_WAIT_V(n) asm volatile("s_waitcnt vmcnt(" #n ")" ::: "memory")
; #define PG8_WAIT_L(n) asm volatile("s_waitcnt lgkmcnt(" #n ")" ::: "memory")
; #define PG8_BAR __builtin_amdgcn_s_barrier()
; #define PG8_SCHED __builtin_amdgcn_sched_barrier(0)
; template <class Epi, class Sched, bool ALIGN_EPI = false, bool SP2 = false>
; __device__ __forceinline__ void gemm_phase(PG8_LAS unsigned char* lds, const Gemm g, const Sched& S, const Epi& E) {
;     ...
;         for (int t = 0; t < nt; t += 2) {
;             const bool last = (t == nt - 2);
;             const char* a1 = cA + (size_t)(t + 1) * kstep;
;             const char* a2 = last ? nA : cA + (size_t)(t + 2) * kstep; const char* b2 = last ? nB : cB + (size_t)(t + 2) * kstep;
;             const char* a3 = a2 + kstep; const char* b3 = b2 + kstep;
;     ...
;             PG8_LDA(At, 1, 1); PG8_STAGE(PG8_SB(1, 0), b3, voffB); PG8_STAGE(PG8_SB(1, 1), b3 + hstep, voffB); PG8_STAGE(PG8_SA(1, 0), a3, voffA);
;             PG8_WAIT_V(8); PG8_WAIT_L(0); PG8_BAR; PG8_MMA(1, 0, At, B0); PG8_MMA(1, 1, At, B1); PG8_BAR; PG8_SCHED;
	s_add_i32 s0, s69, s41
	v_lshl_add_u64 v[146:147], v[146:147], 0, s[8:9]
	s_mov_b32 m0, s0
	ds_read_b128 v[186:189], v152 offset:49152
	ds_read_b128 v[190:193], v152 offset:50176
	ds_read_b128 v[194:197], v152 offset:51200
	ds_read_b128 v[198:201], v152 offset:52224
	ds_read_b128 v[202:205], v152 offset:53248
	ds_read_b128 v[206:209], v152 offset:54272
	ds_read_b128 v[212:215], v152 offset:55296
	ds_read_b128 v[216:219], v152 offset:56320
	global_load_lds_dwordx4 v[146:147], off
	s_add_i32 m0, s0, 0x2000
	s_add_u32 s0, s34, 0x40080
	v_lshl_add_u64 v[146:147], v[220:221], 0, s[8:9]
	s_addc_u32 s1, s35, 0
	s_add_i32 s34, s70, s41
	global_load_lds_dwordx4 v[146:147], off
	v_lshl_add_u64 v[146:147], s[0:1], 0, v[132:133]
	s_mov_b32 m0, s34
	s_nop 0
	global_load_lds_dwordx4 v[146:147], off
	v_lshl_add_u64 v[146:147], s[0:1], 0, v[136:137]
	s_add_i32 m0, s34, 0x2000
	s_nop 0
	global_load_lds_dwordx4 v[146:147], off
	v_lshl_add_u64 v[146:147], v[222:223], 0, s[8:9]
	s_mov_b32 m0, s48
	s_nop 0
	global_load_lds_dwordx4 v[146:147], off
	v_lshl_add_u64 v[146:147], v[224:225], 0, s[8:9]
	s_mov_b32 m0, s49
	s_nop 0
	global_load_lds_dwordx4 v[146:147], off
	s_waitcnt vmcnt(8)
	s_waitcnt lgkmcnt(0)
	s_barrier
	s_setprio 1
	s_waitcnt lgkmcnt(0)
	v_mfma_f32_16x16x32_bf16 v[62:65], v[154:157], v[186:189], v[62:65]
	v_mfma_f32_16x16x32_bf16 v[58:61], v[162:165], v[186:189], v[58:61]
	v_mfma_f32_16x16x32_bf16 v[50:53], v[154:157], v[194:197], v[50:53]
	v_mfma_f32_16x16x32_bf16 v[42:45], v[162:165], v[194:197], v[42:45]
	v_mfma_f32_16x16x32_bf16 v[34:37], v[154:157], v[202:205], v[34:37]
	v_mfma_f32_16x16x32_bf16 v[26:29], v[162:165], v[202:205], v[26:29]
	v_mfma_f32_16x16x32_bf16 v[18:21], v[154:157], v[212:215], v[18:21]
	v_mfma_f32_16x16x32_bf16 v[10:13], v[162:165], v[212:215], v[10:13]
	v_mfma_f32_16x16x32_bf16 v[62:65], v[158:161], v[190:193], v[62:65]
	v_mfma_f32_16x16x32_bf16 v[58:61], v[166:169], v[190:193], v[58:61]
	v_mfma_f32_16x16x32_bf16 v[50:53], v[158:161], v[198:201], v[50:53]
	v_mfma_f32_16x16x32_bf16 v[42:45], v[166:169], v[198:201], v[42:45]
	v_mfma_f32_16x16x32_bf16 v[34:37], v[158:161], v[206:209], v[34:37]
	v_mfma_f32_16x16x32_bf16 v[26:29], v[166:169], v[206:209], v[26:29]
	v_mfma_f32_16x16x32_bf16 v[18:21], v[158:161], v[216:219], v[18:21]
	v_mfma_f32_16x16x32_bf16 v[10:13], v[166:169], v[216:219], v[10:13]
	v_mfma_f32_16x16x32_bf16 v[54:57], v[170:173], v[186:189], v[54:57]
	v_mfma_f32_16x16x32_bf16 v[46:49], v[178:181], v[186:189], v[46:49]
	v_mfma_f32_16x16x32_bf16 v[38:41], v[170:173], v[194:197], v[38:41]
	v_mfma_f32_16x16x32_bf16 v[30:33], v[178:181], v[194:197], v[30:33]
	v_mfma_f32_16x16x32_bf16 v[22:25], v[170:173], v[202:205], v[22:25]
	v_mfma_f32_16x16x32_bf16 v[14:17], v[178:181], v[202:205], v[14:17]
	v_mfma_f32_16x16x32_bf16 v[6:9], v[170:173], v[212:215], v[6:9]
	v_mfma_f32_16x16x32_bf16 v[2:5], v[178:181], v[212:215], v[2:5]
	v_mfma_f32_16x16x32_bf16 v[54:57], v[174:177], v[190:193], v[54:57]
	v_mfma_f32_16x16x32_bf16 v[46:49], v[182:185], v[190:193], v[46:49]
	v_mfma_f32_16x16x32_bf16 v[38:41], v[174:177], v[198:201], v[38:41]
	v_mfma_f32_16x16x32_bf16 v[30:33], v[182:185], v[198:201], v[30:33]
	v_mfma_f32_16x16x32_bf16 v[22:25], v[174:177], v[206:209], v[22:25]
	v_mfma_f32_16x16x32_bf16 v[14:17], v[182:185], v[206:209], v[14:17]
	v_mfma_f32_16x16x32_bf16 v[6:9], v[174:177], v[216:219], v[6:9]
	v_mfma_f32_16x16x32_bf16 v[2:5], v[182:185], v[216:219], v[2:5]
	s_setprio 0
	s_barrier
	s_add_i32 s68, s68, 2
	s_add_u32 s30, s30, 0x100
	s_addc_u32 s31, s31, 0
	s_add_u32 s60, s60, 0x100
	s_addc_u32 s61, s61, 0
	s_cmp_gt_u32 s68, 13
	s_cbranch_scc0 .LBB0_3723
	s_and_b64 vcc, exec, s[10:11]
	s_cbranch_vccz .LBB0_3726
	s_barrier
